# mixer output stores (retention out, dilated attention, neighbourhood attention): lane re-map via ds_bpermute of data and address so each lane quad writes 32 contiguous bytes of one row
# speedup vs baseline: 1.0017x; 1.0017x over previous
; __device__ __forceinline__ float log_sigmoid_(float x) { return -log1pf(__expf(-x)); }
; __global__ void __launch_bounds__(NTHR, 2) fwd_megakernel(Params p) {
;     ...
; #pragma unroll 1
;                         for (int it = bx; it < 128 * 4; it += G) { const int gn = it >> 2, hb = it & 3; int t2 = tid; asm volatile("" : "+v"(t2));
;                             mixB3_mfma_unit(Zb, ST, Y + (size_t)MC * 512, lds, gn, hb, log_sigmoid_(p.in[8][L * 4 + hb]), log_sigmoid_(p.in[9][L * 4 + hb]), t2); }
.LBB0_154:
	s_and_b32 s2, s14, 3
	s_or_b32 s70, s2, s64
	v_readlane_b32 s48, v253, 60
	s_ashr_i32 s20, s14, 2
	s_lshl_b64 s[16:17], s[70:71], 2
	v_readlane_b32 s60, v254, 8
	v_readlane_b32 s61, v254, 9
	s_add_u32 s24, s60, s16
	v_mov_b32_e32 v28, v91
	s_addc_u32 s25, s61, s17
	global_load_dword v1, v0, s[24:25]
	v_readlane_b32 s62, v254, 10
	v_readlane_b32 s63, v254, 11
	s_add_u32 s16, s62, s16
	s_addc_u32 s17, s63, s17
	s_ashr_i32 s21, s20, 31
	s_mul_i32 s4, s20, 0x1e0000
	s_mul_hi_i32 s3, s20, 0x1e0000
	v_ashrrev_i32_e32 v30, 3, v28
	v_lshlrev_b32_e32 v31, 4, v28
	v_add_u32_e32 v32, 0x200, v28
	v_and_b32_e32 v26, 0x70, v31
	v_mov_b32_e32 v27, v0
	v_ashrrev_i32_e32 v33, 3, v32
	v_readlane_b32 s49, v253, 61
	v_lshlrev_b32_e32 v29, 3, v28
	v_ashrrev_i32_e32 v69, 4, v28
	s_mov_b32 s49, s71
	v_mov_b32_e32 v25, v0
	v_ashrrev_i32_e32 v70, 4, v32
	v_add_u32_e32 v72, 0x600, v28
	v_ashrrev_i32_e32 v73, 4, v72
	v_mov_b32_e32 v35, v0
	v_lshlrev_b32_e32 v36, 5, v28
	v_cmp_gt_u32_e64 s[40:41], s39, v32
	v_and_b32_e32 v50, 0x7e00, v36
	v_mov_b32_e32 v51, v0
	v_mov_b32_e32 v43, v0
	v_mov_b32_e32 v59, v0
	v_mov_b32_e32 v45, v0
	v_mov_b32_e32 v53, v0
	v_cmp_gt_u32_e64 s[44:45], s39, v72
	v_mov_b32_e32 v63, v0
	v_bfe_u32 v68, v28, 4, 2
	v_lshlrev_b32_e32 v102, 2, v68
	v_lshlrev_b32_e32 v92, 3, v68
	v_mov_b32_e32 v93, v0
	v_and_b32_e32 v100, 24, v29
	v_lshlrev_b32_e32 v68, 4, v68
	v_readlane_b32 s50, v253, 62
	v_readlane_b32 s51, v253, 63
	v_readlane_b32 s52, v254, 0
	v_readlane_b32 s53, v254, 1
	v_readlane_b32 s54, v254, 2
	v_readlane_b32 s55, v254, 3
	v_readlane_b32 s56, v254, 4
	v_readlane_b32 s57, v254, 5
	v_readlane_b32 s58, v254, 6
	v_readlane_b32 s59, v254, 7
	s_waitcnt vmcnt(0)
	v_mul_f32_e32 v1, 0xbfb8aa3b, v1
	v_exp_f32_e32 v1, v1
	s_nop 0
	v_add_f32_e32 v4, 1.0, v1
	v_add_f32_e32 v2, -1.0, v4
	v_sub_f32_e32 v3, v2, v4
	v_add_f32_e32 v3, 1.0, v3
	v_sub_f32_e32 v2, v1, v2
	v_add_f32_e32 v5, v2, v3
	v_frexp_mant_f32_e32 v2, v4
	v_cmp_gt_f32_e32 vcc, s31, v2
	v_cvt_f64_f32_e32 v[2:3], v4
	v_frexp_exp_i32_f64_e32 v2, v[2:3]
	v_subbrev_co_u32_e32 v10, vcc, 0, v2, vcc
	v_sub_u32_e32 v2, 0, v10
	v_ldexp_f32 v3, v4, v2
	v_add_f32_e32 v4, -1.0, v3
	v_add_f32_e32 v6, 1.0, v3
	v_ldexp_f32 v2, v5, v2
	v_add_f32_e32 v5, 1.0, v4
	v_add_f32_e32 v7, -1.0, v6
	v_sub_f32_e32 v5, v3, v5
	v_sub_f32_e32 v3, v3, v7
	v_add_f32_e32 v5, v2, v5
	v_add_f32_e32 v2, v2, v3
	v_add_f32_e32 v11, v6, v2
	v_rcp_f32_e32 v13, v11
	v_sub_f32_e32 v3, v11, v6
	v_sub_f32_e32 v12, v2, v3
	v_add_f32_e32 v3, v4, v5
	v_mul_f32_e32 v15, v3, v13
	v_sub_f32_e32 v2, v3, v4
	v_mul_f32_e32 v4, v11, v15
	v_fma_f32 v6, v15, v11, -v4
	v_fmac_f32_e32 v6, v15, v12
	v_sub_f32_e32 v14, v5, v2
	v_add_f32_e32 v2, v4, v6
	v_sub_f32_e32 v5, v3, v2
	v_pk_add_f32 v[8:9], v[2:3], v[4:5] neg_lo:[0,1] neg_hi:[0,1]
	v_mov_b32_e32 v7, v2
	v_pk_add_f32 v[2:3], v[8:9], v[6:7] neg_lo:[0,1] neg_hi:[0,1]
	v_cmp_neq_f32_e32 vcc, s22, v1
	v_add_f32_e32 v3, v14, v3
	v_add_f32_e32 v2, v2, v3
	v_add_f32_e32 v3, v5, v2
	v_mul_f32_e32 v14, v13, v3
	v_mul_f32_e32 v4, v11, v14
	v_fma_f32 v6, v14, v11, -v4
	v_fmac_f32_e32 v6, v14, v12
	v_sub_f32_e32 v5, v5, v3
	v_add_f32_e32 v11, v2, v5
	v_add_f32_e32 v2, v4, v6
	v_sub_f32_e32 v5, v3, v2
	v_pk_add_f32 v[8:9], v[2:3], v[4:5] neg_lo:[0,1] neg_hi:[0,1]
	v_mov_b32_e32 v7, v2
	v_pk_add_f32 v[2:3], v[8:9], v[6:7] neg_lo:[0,1] neg_hi:[0,1]
	s_nop 0
	v_add_f32_e32 v3, v11, v3
	v_add_f32_e32 v2, v2, v3
	v_add_f32_e32 v3, v15, v14
	v_add_f32_e32 v2, v5, v2
	v_sub_f32_e32 v4, v3, v15
	v_mul_f32_e32 v2, v13, v2
	v_sub_f32_e32 v4, v14, v4
	v_add_f32_e32 v4, v4, v2
	v_add_f32_e32 v6, v3, v4
	v_mul_f32_e32 v7, v6, v6
	v_fmamk_f32 v2, v7, 0x3e9b6dac, v229
	v_fmaak_f32 v199, v7, v2, 0x3f2aaada
	v_cvt_f32_i32_e32 v2, v10
	v_sub_f32_e32 v3, v6, v3
	v_sub_f32_e32 v3, v4, v3
	v_ldexp_f32 v8, v3, 1
	v_mul_f32_e32 v3, v6, v7
	v_ldexp_f32 v5, v6, 1
	v_pk_mul_f32 v[6:7], v[2:3], v[198:199]
	s_nop 0
	v_fma_f32 v4, v2, s33, -v6
	v_fmac_f32_e32 v4, 0xb102e308, v2
	v_pk_add_f32 v[2:3], v[6:7], v[4:5]
	s_nop 0
	v_sub_f32_e32 v5, v3, v5
	v_sub_f32_e32 v5, v7, v5
	v_add_f32_e32 v9, v8, v5
	v_mov_b32_e32 v8, v6
	v_pk_add_f32 v[6:7], v[2:3], v[6:7] neg_lo:[0,1] neg_hi:[0,1]
	v_pk_add_f32 v[10:11], v[2:3], v[8:9]
	v_mov_b32_e32 v5, v2
	v_mov_b32_e32 v7, v11
	v_pk_add_f32 v[12:13], v[4:5], v[6:7] neg_lo:[0,1] neg_hi:[0,1]
	v_pk_add_f32 v[4:5], v[4:5], v[6:7]
	v_mov_b32_e32 v16, v3
	v_pk_add_f32 v[6:7], v[4:5], v[2:3] op_sel:[1,0] op_sel_hi:[0,1] neg_lo:[0,1] neg_hi:[0,1]
	v_pk_add_f32 v[14:15], v[10:11], v[6:7] op_sel_hi:[1,0] neg_lo:[0,1] neg_hi:[0,1]
	v_mov_b32_e32 v10, v11
	v_mov_b32_e32 v11, v5
	v_mov_b32_e32 v17, v6
	v_pk_add_f32 v[6:7], v[10:11], v[16:17] neg_lo:[0,1] neg_hi:[0,1]
	v_mov_b32_e32 v8, v9
	v_mov_b32_e32 v9, v2
	v_pk_add_f32 v[2:3], v[8:9], v[6:7] neg_lo:[0,1] neg_hi:[0,1]
	v_mov_b32_e32 v14, v12
	v_pk_add_f32 v[6:7], v[14:15], v[2:3]
	v_mov_b32_e32 v13, v5
	v_pk_add_f32 v[8:9], v[6:7], v[6:7] op_sel:[0,1] op_sel_hi:[1,0]
	s_nop 0
	v_pk_add_f32 v[4:5], v[4:5], v[8:9] op_sel:[1,0] op_sel_hi:[0,1]
	v_mov_b32_e32 v7, v4
	v_pk_add_f32 v[10:11], v[6:7], v[12:13] neg_lo:[0,1] neg_hi:[0,1]
	v_mov_b32_e32 v3, v8
	v_sub_f32_e32 v5, v6, v10
	v_pk_add_f32 v[2:3], v[2:3], v[10:11] neg_lo:[0,1] neg_hi:[0,1]
	v_sub_f32_e32 v5, v12, v5
	v_add_f32_e32 v2, v2, v5
	v_add_f32_e32 v2, v2, v3
	v_add_f32_e32 v2, v4, v2
	v_cndmask_b32_e32 v2, v230, v2, vcc
	v_cmp_ngt_f32_e32 vcc, -1.0, v1
	s_nop 1
	v_cndmask_b32_e32 v2, v240, v2, vcc
	v_cmp_neq_f32_e32 vcc, -1.0, v1
	s_nop 1
	v_cndmask_b32_e32 v2, v234, v2, vcc
	v_cmp_lt_f32_e64 vcc, |v1|, s38
	s_nop 1
	v_cndmask_b32_e32 v1, v2, v1, vcc
	global_load_dword v2, v0, s[16:17]
	s_add_u32 s16, s12, s4
	s_addc_u32 s17, s13, s3
	v_mov_b64_e32 v[22:23], s[16:17]
	s_lshl_b32 s70, s2, 7
	s_lshl_b32 s48, s2, 8
	v_mov_b32_e32 v61, s70
	s_barrier
; __device__ __forceinline__ void mixB3_mfma_unit(const bf16* Z, const float* ST, bf16* Yb, LAS unsigned char* lds, int gn, int hb, float lgf, float lgb, int tid) {
;     ...
;     {
;         pg8::u32x4 kbuf[2], vbuf[4]; f32x4 sbuf[4][2];
; #pragma unroll
;         for (int i = 0; i < 2; ++i) { const int c = tid + i * NTHR, row = c >> 3, ch = c & 7; kbuf[i] = *(const pg8::u32x4*)(zb + (size_t)row * NZ + 4864 + hb * 64 + ch * 8); }
; #pragma unroll
;         for (int i = 0; i < 4; ++i) { const int c = tid + i * NTHR, row = c >> 4, ch = c & 15; vbuf[i] = *(const pg8::u32x4*)(zb + (size_t)row * NZ + 5120 + hb * 128 + ch * 8); }
; #pragma unroll
;         for (int i = 0; i < 4; ++i) { const int c = tid + i * NTHR, dir = c >> 10, cc = c & 1023, row = cc >> 4, ch = cc & 15;
;             const float* sp = (dir ? Sb : Sf) + row * 128 + ch * 8; sbuf[i][0] = *(const f32x4*)sp; sbuf[i][1] = *(const f32x4*)(sp + 4); }
; __device__ __forceinline__ float log_sigmoid_(float x) { return -log1pf(__expf(-x)); }
	s_add_i32 s14, s14, s98
	s_waitcnt vmcnt(0)
	v_mul_f32_e32 v2, 0xbfb8aa3b, v2
	v_exp_f32_e32 v18, v2
	s_nop 0
	v_add_f32_e32 v4, 1.0, v18
	v_add_f32_e32 v2, -1.0, v4
	v_sub_f32_e32 v3, v2, v4
	v_add_f32_e32 v3, 1.0, v3
	v_sub_f32_e32 v2, v18, v2
	v_add_f32_e32 v5, v2, v3
	v_frexp_mant_f32_e32 v2, v4
	v_cmp_gt_f32_e32 vcc, s31, v2
	v_cvt_f64_f32_e32 v[2:3], v4
	v_frexp_exp_i32_f64_e32 v2, v[2:3]
	v_subbrev_co_u32_e32 v10, vcc, 0, v2, vcc
	v_sub_u32_e32 v2, 0, v10
	v_ldexp_f32 v3, v4, v2
	v_add_f32_e32 v4, -1.0, v3
	v_add_f32_e32 v6, 1.0, v3
	v_ldexp_f32 v2, v5, v2
	v_add_f32_e32 v5, 1.0, v4
	v_add_f32_e32 v7, -1.0, v6
	v_sub_f32_e32 v5, v3, v5
	v_sub_f32_e32 v3, v3, v7
	v_add_f32_e32 v5, v2, v5
	v_add_f32_e32 v2, v2, v3
	v_add_f32_e32 v11, v6, v2
	v_rcp_f32_e32 v13, v11
	v_sub_f32_e32 v3, v11, v6
	v_sub_f32_e32 v12, v2, v3
	v_add_f32_e32 v3, v4, v5
	v_mul_f32_e32 v15, v3, v13
	v_sub_f32_e32 v2, v3, v4
	v_mul_f32_e32 v4, v11, v15
	v_fma_f32 v6, v15, v11, -v4
	v_fmac_f32_e32 v6, v15, v12
	v_sub_f32_e32 v14, v5, v2
	v_add_f32_e32 v2, v4, v6
	v_sub_f32_e32 v5, v3, v2
	v_pk_add_f32 v[8:9], v[2:3], v[4:5] neg_lo:[0,1] neg_hi:[0,1]
	v_mov_b32_e32 v7, v2
	v_pk_add_f32 v[2:3], v[8:9], v[6:7] neg_lo:[0,1] neg_hi:[0,1]
	v_cmp_neq_f32_e32 vcc, s22, v18
	v_add_f32_e32 v3, v14, v3
	v_add_f32_e32 v2, v2, v3
	v_add_f32_e32 v3, v5, v2
	v_mul_f32_e32 v14, v13, v3
	v_mul_f32_e32 v4, v11, v14
	v_fma_f32 v6, v14, v11, -v4
	v_fmac_f32_e32 v6, v14, v12
	v_sub_f32_e32 v5, v5, v3
	v_add_f32_e32 v11, v2, v5
	v_add_f32_e32 v2, v4, v6
	v_sub_f32_e32 v5, v3, v2
	v_pk_add_f32 v[8:9], v[2:3], v[4:5] neg_lo:[0,1] neg_hi:[0,1]
	v_mov_b32_e32 v7, v2
	v_pk_add_f32 v[2:3], v[8:9], v[6:7] neg_lo:[0,1] neg_hi:[0,1]
	s_nop 0
	v_add_f32_e32 v3, v11, v3
	v_add_f32_e32 v2, v2, v3
	v_add_f32_e32 v3, v15, v14
	v_add_f32_e32 v2, v5, v2
	v_sub_f32_e32 v4, v3, v15
	v_mul_f32_e32 v2, v13, v2
	v_sub_f32_e32 v4, v14, v4
	v_add_f32_e32 v4, v4, v2
	v_add_f32_e32 v6, v3, v4
	v_mul_f32_e32 v7, v6, v6
	v_fmamk_f32 v2, v7, 0x3e9b6dac, v229
	v_fmaak_f32 v199, v7, v2, 0x3f2aaada
	v_cvt_f32_i32_e32 v2, v10
	v_sub_f32_e32 v3, v6, v3
	v_sub_f32_e32 v3, v4, v3
	v_ldexp_f32 v8, v3, 1
	v_mul_f32_e32 v3, v6, v7
	v_ldexp_f32 v5, v6, 1
	v_pk_mul_f32 v[6:7], v[2:3], v[198:199]
	s_nop 0
	v_fma_f32 v4, v2, s33, -v6
	v_fmac_f32_e32 v4, 0xb102e308, v2
	v_pk_add_f32 v[2:3], v[6:7], v[4:5]
	s_nop 0
	v_sub_f32_e32 v5, v3, v5
	v_sub_f32_e32 v5, v7, v5
	v_add_f32_e32 v9, v8, v5
	v_mov_b32_e32 v8, v6
	v_pk_add_f32 v[6:7], v[2:3], v[6:7] neg_lo:[0,1] neg_hi:[0,1]
	v_pk_add_f32 v[10:11], v[2:3], v[8:9]
	v_mov_b32_e32 v5, v2
	v_mov_b32_e32 v7, v11
	v_pk_add_f32 v[12:13], v[4:5], v[6:7] neg_lo:[0,1] neg_hi:[0,1]
	v_pk_add_f32 v[4:5], v[4:5], v[6:7]
	v_mov_b32_e32 v16, v3
	v_pk_add_f32 v[6:7], v[4:5], v[2:3] op_sel:[1,0] op_sel_hi:[0,1] neg_lo:[0,1] neg_hi:[0,1]
	v_pk_add_f32 v[14:15], v[10:11], v[6:7] op_sel_hi:[1,0] neg_lo:[0,1] neg_hi:[0,1]
	v_mov_b32_e32 v10, v11
	v_mov_b32_e32 v11, v5
	v_mov_b32_e32 v17, v6
	v_pk_add_f32 v[6:7], v[10:11], v[16:17] neg_lo:[0,1] neg_hi:[0,1]
	v_mov_b32_e32 v8, v9
	v_mov_b32_e32 v9, v2
	v_pk_add_f32 v[2:3], v[8:9], v[6:7] neg_lo:[0,1] neg_hi:[0,1]
	v_mov_b32_e32 v14, v12
	v_pk_add_f32 v[6:7], v[14:15], v[2:3]
	v_mov_b32_e32 v13, v5
	v_pk_add_f32 v[8:9], v[6:7], v[6:7] op_sel:[0,1] op_sel_hi:[1,0]
	v_mad_i64_i32 v[14:15], s[2:3], v70, s66, v[22:23]
	v_pk_add_f32 v[4:5], v[4:5], v[8:9] op_sel:[1,0] op_sel_hi:[0,1]
	v_mov_b32_e32 v7, v4
	v_pk_add_f32 v[10:11], v[6:7], v[12:13] neg_lo:[0,1] neg_hi:[0,1]
	v_mov_b32_e32 v3, v8
	v_sub_f32_e32 v5, v6, v10
	v_pk_add_f32 v[2:3], v[2:3], v[10:11] neg_lo:[0,1] neg_hi:[0,1]
	v_sub_f32_e32 v5, v12, v5
	v_add_f32_e32 v2, v2, v5
	v_add_f32_e32 v2, v2, v3
	v_add_f32_e32 v2, v4, v2
	v_cndmask_b32_e32 v2, v230, v2, vcc
	v_cmp_ngt_f32_e32 vcc, -1.0, v18
	v_mad_i64_i32 v[6:7], s[16:17], v33, s66, v[22:23]
	s_nop 0
	v_cndmask_b32_e32 v2, v240, v2, vcc
	v_cmp_neq_f32_e32 vcc, -1.0, v18
	v_lshl_add_u64 v[6:7], v[6:7], 0, s[70:71]
	v_lshl_add_u64 v[6:7], v[6:7], 0, v[26:27]
	v_cndmask_b32_e32 v2, v234, v2, vcc
	v_cmp_lt_f32_e64 vcc, |v18|, s38
	v_mad_i64_i32 v[10:11], s[16:17], v69, s66, v[22:23]
	s_nop 0
	v_cndmask_b32_e32 v98, v2, v18, vcc
	v_mad_i64_i32 v[2:3], s[16:17], v30, s66, v[22:23]
	v_lshl_add_u64 v[2:3], v[2:3], 0, s[70:71]
	v_lshl_add_u64 v[2:3], v[2:3], 0, v[26:27]
	v_add_co_u32_e32 v2, vcc, s15, v2
	v_and_b32_e32 v27, 0x78, v29
	s_nop 0
	v_addc_co_u32_e32 v3, vcc, 0, v3, vcc
	v_add_co_u32_e32 v6, vcc, s15, v6
	v_lshl_add_u64 v[10:11], v[10:11], 0, s[48:49]
	v_lshlrev_b32_e32 v24, 1, v27
	v_addc_co_u32_e32 v7, vcc, 0, v7, vcc
	v_lshl_add_u64 v[10:11], v[10:11], 0, v[24:25]
	v_add_u32_e32 v18, 0x400, v28
	v_add_co_u32_e32 v10, vcc, s15, v10
	v_lshl_add_u64 v[14:15], v[14:15], 0, s[48:49]
	v_ashrrev_i32_e32 v71, 4, v18
	v_addc_co_u32_e32 v11, vcc, 0, v11, vcc
	v_lshl_add_u64 v[14:15], v[14:15], 0, v[24:25]
	v_mad_i64_i32 v[18:19], s[2:3], v71, s66, v[22:23]
	v_add_co_u32_e32 v14, vcc, s15, v14
	v_lshl_add_u64 v[18:19], v[18:19], 0, s[48:49]
	s_nop 0
	v_addc_co_u32_e32 v15, vcc, 0, v15, vcc
	v_lshl_add_u64 v[18:19], v[18:19], 0, v[24:25]
	v_mad_i64_i32 v[22:23], s[2:3], v73, s66, v[22:23]
	v_add_co_u32_e32 v18, vcc, s15, v18
	v_lshl_add_u64 v[22:23], v[22:23], 0, s[48:49]
	s_nop 0
	v_addc_co_u32_e32 v19, vcc, 0, v19, vcc
	v_lshl_add_u64 v[22:23], v[22:23], 0, v[24:25]
	v_add_co_u32_e32 v22, vcc, s15, v22
	s_or_b32 s2, s70, 0x200
	s_nop 0
	v_addc_co_u32_e32 v23, vcc, 0, v23, vcc
	v_cmp_gt_u32_e32 vcc, s39, v28
	v_mov_b32_e32 v60, s2
	global_load_dwordx4 v[2:5], v[2:3], off offset:1536
	v_cndmask_b32_e32 v34, v60, v61, vcc
; __device__ __forceinline__ unsigned cvt_pk_bf16(float lo, float hi) { unsigned r; asm volatile("v_cvt_pk_bf16_f32 %0, %1, %2" : "=v"(r) : "v"(lo), "v"(hi)); return r; }
; #define LAS __attribute__((address_space(3)))
; __device__ __forceinline__ void mixB3_mfma_unit(const bf16* Z, const float* ST, bf16* Yb, LAS unsigned char* lds, int gn, int hb, float lgf, float lgb, int tid) {
;     ...
;         for (int i = 0; i < 4; ++i) { const int c = tid + i * NTHR, row = c >> 4, ch = c & 15; vbuf[i] = *(const pg8::u32x4*)(zb + (size_t)row * NZ + 5120 + hb * 128 + ch * 8); }
; #pragma unroll
;         for (int i = 0; i < 4; ++i) { const int c = tid + i * NTHR, dir = c >> 10, cc = c & 1023, row = cc >> 4, ch = cc & 15;
;             const float* sp = (dir ? Sb : Sf) + row * 128 + ch * 8; sbuf[i][0] = *(const f32x4*)sp; sbuf[i][1] = *(const f32x4*)(sp + 4); }
; #pragma unroll
;         for (int i = 0; i < 2; ++i) { const int c = tid + i * NTHR, row = c >> 3, ch = c & 7; *(LAS pg8::u32x4*)(lds + B3_K + row * KPITCH + ch * 16) = kbuf[i]; }
; #pragma unroll
;         for (int i = 0; i < 4; ++i) { const int c = tid + i * NTHR, row = c >> 4, ch = c & 15; *(LAS pg8::u32x4*)(lds + B3_V + row * VPITCH + ch * 16) = vbuf[i]; }
; #pragma unroll
;         for (int i = 0; i < 4; ++i) { const int c = tid + i * NTHR, dir = c >> 10, cc = c & 1023, row = cc >> 4, ch = cc & 15;
;             const f32x4 x0 = sbuf[i][0], x1 = sbuf[i][1];
;             pg8::u32x4 a; a.x = pg8::cvt_pk_bf16(x0[0], x0[1]); a.y = pg8::cvt_pk_bf16(x0[2], x0[3]); a.z = pg8::cvt_pk_bf16(x1[0], x1[1]); a.w = pg8::cvt_pk_bf16(x1[2], x1[3]);
;             *(LAS pg8::u32x4*)(lds + (dir ? B3_SB : B3_SF) + row * VPITCH + ch * 16) = a; }
;     }
;     __syncthreads();
;     const int i = 16 * w + n, tokc = gn * 128 + i;
;     const bf16* qp = Z + (size_t)tokc * NZ + 4608 + hb * 64;
;     const int rsel = 4 * q + ((lane >> 2) & 3), csel = 8 * (lane & 3);
	global_load_dwordx4 v[6:9], v[6:7], off offset:1536
	v_lshl_add_u64 v[34:35], v[34:35], 0, s[20:21]
	v_lshlrev_b64 v[34:35], 15, v[34:35]
	v_lshl_add_u64 v[34:35], s[46:47], 0, v[34:35]
	v_cndmask_b32_e64 v42, v60, v61, s[40:41]
	global_load_dwordx4 v[10:13], v[10:11], off offset:2048
	v_lshl_add_u64 v[34:35], v[34:35], 0, v[50:51]
	v_lshlrev_b32_e32 v58, 2, v27
	v_lshl_add_u64 v[42:43], v[42:43], 0, s[20:21]
	s_movk_i32 s2, 0xfbff
	global_load_dwordx4 v[14:17], v[14:15], off offset:2048
	v_lshl_add_u64 v[38:39], v[34:35], 0, v[58:59]
	v_lshlrev_b64 v[42:43], 15, v[42:43]
	v_lshlrev_b32_e32 v27, 5, v32
	v_cmp_lt_u32_e64 s[42:43], s2, v28
	global_load_dwordx4 v[18:21], v[18:19], off offset:2048
	v_lshl_add_u64 v[42:43], s[46:47], 0, v[42:43]
	global_load_dwordx4 v[22:25], v[22:23], off offset:2048
	s_nop 0
	global_load_dwordx4 v[34:37], v[38:39], off offset:16
	s_nop 0
	global_load_dwordx4 v[38:41], v[38:39], off
	v_and_b32_e32 v44, 0x7e00, v27
	v_cndmask_b32_e64 v52, v60, v61, s[42:43]
	v_lshl_add_u64 v[42:43], v[42:43], 0, v[44:45]
	v_lshl_add_u64 v[52:53], v[52:53], 0, s[20:21]
	v_lshl_add_u64 v[46:47], v[42:43], 0, v[58:59]
	v_lshlrev_b64 v[52:53], 15, v[52:53]
	v_cndmask_b32_e64 v60, v60, v61, s[44:45]
	v_mov_b32_e32 v61, v0
	global_load_dwordx4 v[42:45], v[46:47], off offset:16
	s_nop 0
	global_load_dwordx4 v[46:49], v[46:47], off
	v_lshl_add_u64 v[52:53], s[46:47], 0, v[52:53]
	v_lshl_add_u64 v[60:61], v[60:61], 0, s[20:21]
	v_lshl_add_u64 v[50:51], v[52:53], 0, v[50:51]
	v_lshlrev_b64 v[60:61], 15, v[60:61]
	v_lshlrev_b32_e32 v27, 5, v72
	v_lshl_add_u64 v[54:55], v[50:51], 0, v[58:59]
	v_lshl_add_u64 v[60:61], s[46:47], 0, v[60:61]
	v_and_b32_e32 v62, 0x7e00, v27
	global_load_dwordx4 v[50:53], v[54:55], off offset:16
	s_nop 0
	global_load_dwordx4 v[54:57], v[54:55], off
	v_lshl_add_u64 v[60:61], v[60:61], 0, v[62:63]
	v_lshl_add_u64 v[62:63], v[60:61], 0, v[58:59]
	global_load_dwordx4 v[58:61], v[62:63], off offset:16
	s_nop 0
	global_load_dwordx4 v[62:65], v[62:63], off
	v_add_u32_e32 v26, 0, v26
	v_mad_u64_u32 v[66:67], s[2:3], v30, s67, v[26:27]
	s_waitcnt vmcnt(13)
	ds_write_b128 v66, v[2:5]
	v_mad_u64_u32 v[2:3], s[2:3], v33, s67, v[26:27]
	s_waitcnt vmcnt(12)
	ds_write_b128 v2, v[6:9]
	v_and_b32_e32 v6, 0xf0, v31
	v_add_u32_e32 v2, 0, v6
	v_mad_u64_u32 v[4:5], s[2:3], v69, s68, v[2:3]
	v_bfe_u32 v7, v28, 4, 6
	v_cndmask_b32_e32 v8, v235, v236, vcc
	s_waitcnt vmcnt(11)
	ds_write_b128 v4, v[10:13] offset:18432
	v_mad_u64_u32 v[4:5], s[2:3], v70, s68, v[2:3]
	v_add_u32_e32 v8, 0, v8
	v_mul_u32_u24_e32 v7, 0x120, v7
	s_waitcnt vmcnt(10)
	ds_write_b128 v4, v[14:17] offset:18432
	v_mad_u64_u32 v[4:5], s[2:3], v71, s68, v[2:3]
	v_mad_u64_u32 v[2:3], s[2:3], v73, s68, v[2:3]
	v_add3_u32 v8, v8, v7, v6
	s_waitcnt vmcnt(9)
	ds_write_b128 v4, v[18:21] offset:18432
	s_waitcnt vmcnt(8)
	ds_write_b128 v2, v[22:25] offset:18432
	s_waitcnt vmcnt(6)
	v_cvt_pk_bf16_f32 v2, v38, v39
	v_cvt_pk_bf16_f32 v3, v40, v41
	v_cvt_pk_bf16_f32 v4, v34, v35
	v_cvt_pk_bf16_f32 v5, v36, v37
	ds_write_b128 v8, v[2:5]
	v_bfe_u32 v8, v32, 4, 6
	v_cndmask_b32_e64 v9, v235, v236, s[40:41]
	v_add_u32_e32 v9, 0, v9
	v_mul_u32_u24_e32 v8, 0x120, v8
	v_add3_u32 v8, v9, v8, v6
	s_waitcnt vmcnt(4)
	v_cvt_pk_bf16_f32 v2, v46, v47
	v_cvt_pk_bf16_f32 v3, v48, v49
	v_cvt_pk_bf16_f32 v4, v42, v43
	v_cvt_pk_bf16_f32 v5, v44, v45
	ds_write_b128 v8, v[2:5]
	v_cndmask_b32_e64 v8, v235, v236, s[42:43]
	v_add_u32_e32 v8, 0, v8
	v_add3_u32 v7, v8, v7, v6
	s_waitcnt vmcnt(2)
	v_cvt_pk_bf16_f32 v2, v54, v55
	v_cvt_pk_bf16_f32 v3, v56, v57
	v_cvt_pk_bf16_f32 v4, v50, v51
	v_cvt_pk_bf16_f32 v5, v52, v53
	ds_write_b128 v7, v[2:5]
	v_bfe_u32 v7, v72, 4, 6
	v_cndmask_b32_e64 v8, v235, v236, s[44:45]
	v_add_u32_e32 v8, 0, v8
	v_mul_u32_u24_e32 v7, 0x120, v7
	s_waitcnt vmcnt(0)
	v_cvt_pk_bf16_f32 v2, v62, v63
	v_add3_u32 v6, v8, v7, v6
	v_cvt_pk_bf16_f32 v3, v64, v65
	v_cvt_pk_bf16_f32 v4, v58, v59
	v_cvt_pk_bf16_f32 v5, v60, v61
	ds_write_b128 v6, v[2:5]
	v_ashrrev_i32_e32 v2, 2, v28
	v_bfi_b32 v99, -16, v2, v28
	v_lshl_add_u32 v94, s20, 7, v99
	v_mov_b64_e32 v[2:3], s[12:13]
	v_mad_i64_i32 v[96:97], s[2:3], v94, s66, v[2:3]
	v_lshl_add_u64 v[2:3], v[96:97], 0, s[70:71]
	s_mov_b64 s[2:3], 0x2400
	v_lshl_add_u64 v[66:67], v[2:3], 0, s[2:3]
	v_lshrrev_b32_e32 v2, 2, v28
	v_and_or_b32 v4, v2, 3, v102
	v_lshl_add_u64 v[2:3], v[66:67], 0, v[92:93]
	s_waitcnt lgkmcnt(0)
	s_barrier
; #define LAS __attribute__((address_space(3)))
; __device__ __forceinline__ s16x4_t trread(LAS unsigned char* p) { return __builtin_amdgcn_ds_read_tr16_b64_v4i16((LAS s16x4_t*)p); }
; __device__ __forceinline__ bf16x8_t cat4(s16x4_t a, s16x4_t b) { return (bf16x8_t){a[0], a[1], a[2], a[3], b[0], b[1], b[2], b[3]}; }
; __device__ __forceinline__ void mixB3_mfma_unit(const bf16* Z, const float* ST, bf16* Yb, LAS unsigned char* lds, int gn, int hb, float lgf, float lgb, int tid) {
;     ...
;         const uint2 a0 = *(const uint2*)(qp + 4 * q), a1 = *(const uint2*)(qp + 16 + 4 * q), a2 = *(const uint2*)(qp + 32 + 4 * q), a3 = *(const uint2*)(qp + 48 + 4 * q);
;         const bf16x8_t qc0 = __builtin_bit_cast(bf16x8_t, (uint4){a0.x, a0.y, a1.x, a1.y}), qc1 = __builtin_bit_cast(bf16x8_t, (uint4){a2.x, a2.y, a3.x, a3.y});
;         const float cf = __expf(lgf * (float)(i + 1)), cb = __expf(lgb * (float)(128 - i));
; #pragma unroll
;         for (int et = 0; et < 8; ++et) {
;             LAS unsigned char* sf = lds + B3_SF + rsel * VPITCH + et * 32 + csel;
;             LAS unsigned char* sb = lds + B3_SB + rsel * VPITCH + et * 32 + csel;
;             f32x4 f = {0.f, 0.f, 0.f, 0.f}, b = {0.f, 0.f, 0.f, 0.f};
;             f = __builtin_amdgcn_mfma_f32_16x16x32_bf16(cat4(trread(sf), trread(sf + 16 * VPITCH)), qc0, f, 0, 0, 0);
;             f = __builtin_amdgcn_mfma_f32_16x16x32_bf16(cat4(trread(sf + 32 * VPITCH), trread(sf + 48 * VPITCH)), qc1, f, 0, 0, 0);
;             b = __builtin_amdgcn_mfma_f32_16x16x32_bf16(cat4(trread(sb), trread(sb + 16 * VPITCH)), qc0, b, 0, 0, 0);
;             b = __builtin_amdgcn_mfma_f32_16x16x32_bf16(cat4(trread(sb + 32 * VPITCH), trread(sb + 48 * VPITCH)), qc1, b, 0, 0, 0);
;             o[et] = f * cf + b * cb;
	global_load_dwordx2 v[62:63], v[2:3], off
	global_load_dwordx2 v[64:65], v[2:3], off offset:32
	global_load_dwordx2 v[72:73], v[2:3], off offset:64
	global_load_dwordx2 v[74:75], v[2:3], off offset:96
	v_mul_u32_u24_e32 v101, 0x120, v4
	v_add3_u32 v69, 0, v101, v100
	ds_read_b64_tr_b16 v[4:5], v69 offset:59904
	ds_read_b64_tr_b16 v[2:3], v69 offset:55296
	ds_read_b64_tr_b16 v[10:11], v69 offset:55328
	v_add_u32_e32 v71, 0xd800, v69
	s_waitcnt vmcnt(2) lgkmcnt(1)
	v_mfma_f32_16x16x32_bf16 v[2:5], v[2:5], v[62:65], 0
	ds_read_b64_tr_b16 v[6:7], v69 offset:64512
	ds_read_b64_tr_b16 v[8:9], v71 offset:13824
	ds_read_b64_tr_b16 v[14:15], v71 offset:13856
	s_add_i32 s2, 0, 0x12000
	v_add3_u32 v80, s2, v101, v100
	s_waitcnt vmcnt(0) lgkmcnt(1)
	v_mfma_f32_16x16x32_bf16 v[2:5], v[6:9], v[72:75], v[2:5]
	ds_read_b64_tr_b16 v[8:9], v80 offset:4608
	ds_read_b64_tr_b16 v[6:7], v80
	ds_read_b64_tr_b16 v[16:17], v80 offset:32
	ds_read_b64_tr_b16 v[18:19], v80 offset:9216
	ds_read_b64_tr_b16 v[20:21], v80 offset:13824
	ds_read_b64_tr_b16 v[12:13], v69 offset:59936
	s_waitcnt lgkmcnt(4)
	v_mfma_f32_16x16x32_bf16 v[6:9], v[6:9], v[62:65], 0
	v_and_b32_e32 v70, 15, v28
	v_cmp_gt_i32_e32 vcc, v102, v99
	s_mov_b64 s[2:3], 0x2c00
	s_waitcnt lgkmcnt(1)
	v_mfma_f32_16x16x32_bf16 v[6:9], v[18:21], v[72:75], v[6:9]
	v_ashrrev_i32_e32 v95, 31, v94
	s_cmpk_gt_i32 s14, 0x1ff
	s_waitcnt lgkmcnt(0)
	v_mfma_f32_16x16x32_bf16 v[18:21], v[10:13], v[62:65], 0
	ds_read_b64_tr_b16 v[12:13], v69 offset:64544
	s_waitcnt lgkmcnt(0)
	v_mfma_f32_16x16x32_bf16 v[10:13], v[12:15], v[72:75], v[18:21]
	s_nop 4
	ds_read_b64_tr_b16 v[18:19], v80 offset:4640
	s_waitcnt lgkmcnt(0)
	v_mfma_f32_16x16x32_bf16 v[14:17], v[16:19], v[62:65], 0
	ds_read_b64_tr_b16 v[18:19], v80 offset:9248
	ds_read_b64_tr_b16 v[20:21], v80 offset:13856
	s_waitcnt lgkmcnt(0)
	v_mfma_f32_16x16x32_bf16 v[14:17], v[18:21], v[72:75], v[14:17]
	ds_read_b64_tr_b16 v[18:19], v69 offset:55360
	ds_read_b64_tr_b16 v[20:21], v69 offset:59968
	ds_read_b64_tr_b16 v[22:23], v69 offset:64576
	ds_read_b64_tr_b16 v[24:25], v71 offset:13888
	s_waitcnt lgkmcnt(2)
	v_mfma_f32_16x16x32_bf16 v[18:21], v[18:21], v[62:65], 0
	s_waitcnt lgkmcnt(0)
	v_mfma_f32_16x16x32_bf16 v[18:21], v[22:25], v[72:75], v[18:21]
	ds_read_b64_tr_b16 v[22:23], v80 offset:64
	ds_read_b64_tr_b16 v[24:25], v80 offset:4672
	ds_read_b64_tr_b16 v[26:27], v80 offset:9280
	ds_read_b64_tr_b16 v[28:29], v80 offset:13888
	s_waitcnt lgkmcnt(2)
	v_mfma_f32_16x16x32_bf16 v[22:25], v[22:25], v[62:65], 0
	s_waitcnt lgkmcnt(0)
	v_mfma_f32_16x16x32_bf16 v[22:25], v[26:29], v[72:75], v[22:25]
	ds_read_b64_tr_b16 v[26:27], v69 offset:55392
	ds_read_b64_tr_b16 v[28:29], v69 offset:60000
	ds_read_b64_tr_b16 v[30:31], v69 offset:64608
	ds_read_b64_tr_b16 v[32:33], v71 offset:13920
	s_waitcnt lgkmcnt(2)
	v_mfma_f32_16x16x32_bf16 v[26:29], v[26:29], v[62:65], 0
	s_waitcnt lgkmcnt(0)
	v_mfma_f32_16x16x32_bf16 v[26:29], v[30:33], v[72:75], v[26:29]
	ds_read_b64_tr_b16 v[30:31], v80 offset:96
	ds_read_b64_tr_b16 v[32:33], v80 offset:4704
	ds_read_b64_tr_b16 v[34:35], v80 offset:9312
	ds_read_b64_tr_b16 v[36:37], v80 offset:13920
	s_waitcnt lgkmcnt(2)
	v_mfma_f32_16x16x32_bf16 v[30:33], v[30:33], v[62:65], 0
	s_waitcnt lgkmcnt(0)
	v_mfma_f32_16x16x32_bf16 v[30:33], v[34:37], v[72:75], v[30:33]
	ds_read_b64_tr_b16 v[34:35], v69 offset:55424
	ds_read_b64_tr_b16 v[36:37], v69 offset:60032
	ds_read_b64_tr_b16 v[38:39], v69 offset:64640
	ds_read_b64_tr_b16 v[40:41], v71 offset:13952
	s_waitcnt lgkmcnt(2)
	v_mfma_f32_16x16x32_bf16 v[34:37], v[34:37], v[62:65], 0
	s_waitcnt lgkmcnt(0)
	v_mfma_f32_16x16x32_bf16 v[34:37], v[38:41], v[72:75], v[34:37]
	ds_read_b64_tr_b16 v[38:39], v80 offset:128
	ds_read_b64_tr_b16 v[40:41], v80 offset:4736
	ds_read_b64_tr_b16 v[42:43], v80 offset:9344
	ds_read_b64_tr_b16 v[44:45], v80 offset:13952
	s_waitcnt lgkmcnt(2)
	v_mfma_f32_16x16x32_bf16 v[38:41], v[38:41], v[62:65], 0
	s_waitcnt lgkmcnt(0)
	v_mfma_f32_16x16x32_bf16 v[38:41], v[42:45], v[72:75], v[38:41]
	ds_read_b64_tr_b16 v[42:43], v69 offset:55456
	ds_read_b64_tr_b16 v[44:45], v69 offset:60064
	ds_read_b64_tr_b16 v[46:47], v69 offset:64672
	ds_read_b64_tr_b16 v[48:49], v71 offset:13984
	s_waitcnt lgkmcnt(2)
	v_mfma_f32_16x16x32_bf16 v[42:45], v[42:45], v[62:65], 0
	s_waitcnt lgkmcnt(0)
	v_mfma_f32_16x16x32_bf16 v[42:45], v[46:49], v[72:75], v[42:45]
	ds_read_b64_tr_b16 v[46:47], v80 offset:160
	ds_read_b64_tr_b16 v[48:49], v80 offset:4768
	ds_read_b64_tr_b16 v[50:51], v80 offset:9376
	ds_read_b64_tr_b16 v[52:53], v80 offset:13984
	s_waitcnt lgkmcnt(2)
	v_mfma_f32_16x16x32_bf16 v[46:49], v[46:49], v[62:65], 0
	s_waitcnt lgkmcnt(0)
	v_mfma_f32_16x16x32_bf16 v[46:49], v[50:53], v[72:75], v[46:49]
	ds_read_b64_tr_b16 v[50:51], v69 offset:55488
	ds_read_b64_tr_b16 v[52:53], v69 offset:60096
	ds_read_b64_tr_b16 v[54:55], v69 offset:64704
	ds_read_b64_tr_b16 v[56:57], v71 offset:14016
	s_waitcnt lgkmcnt(2)
	v_mfma_f32_16x16x32_bf16 v[50:53], v[50:53], v[62:65], 0
	s_waitcnt lgkmcnt(0)
	v_mfma_f32_16x16x32_bf16 v[50:53], v[54:57], v[72:75], v[50:53]
	ds_read_b64_tr_b16 v[54:55], v80 offset:192
	ds_read_b64_tr_b16 v[56:57], v80 offset:4800
	ds_read_b64_tr_b16 v[58:59], v80 offset:9408
	ds_read_b64_tr_b16 v[60:61], v80 offset:14016
	s_waitcnt lgkmcnt(2)
	v_mfma_f32_16x16x32_bf16 v[54:57], v[54:57], v[62:65], 0
	s_waitcnt lgkmcnt(0)
	v_mfma_f32_16x16x32_bf16 v[54:57], v[58:61], v[72:75], v[54:57]
	ds_read_b64_tr_b16 v[58:59], v69 offset:55520
	ds_read_b64_tr_b16 v[60:61], v69 offset:60128
	ds_read_b64_tr_b16 v[76:77], v69 offset:64736
	ds_read_b64_tr_b16 v[78:79], v71 offset:14048
	v_mov_b32_e32 v69, v0
	s_waitcnt lgkmcnt(2)
; #define LAS __attribute__((address_space(3)))
; __device__ __forceinline__ void mixB3_mfma_unit(const bf16* Z, const float* ST, bf16* Yb, LAS unsigned char* lds, int gn, int hb, float lgf, float lgb, int tid) {
;     ...
;     {
;         const bf16x8_t qf0 = *(const bf16x8_t*)(qp + 8 * q), qf1 = *(const bf16x8_t*)(qp + 32 + 8 * q);
;         f32x4 s[8];
; #pragma unroll
;         for (int t = 0; t < 8; ++t) {
;             LAS unsigned char* kp = lds + B3_K + (16 * t + n) * KPITCH + q * 16;
;             f32x4 a = {0.f, 0.f, 0.f, 0.f};
;             a = __builtin_amdgcn_mfma_f32_16x16x32_bf16(*(LAS bf16x8_t*)kp, qf0, a, 0, 0, 0);
;             a = __builtin_amdgcn_mfma_f32_16x16x32_bf16(*(LAS bf16x8_t*)(kp + 64), qf1, a, 0, 0, 0);
; #pragma unroll
;             for (int j = 0; j < 4; ++j) { const int jj = 16 * t + 4 * q + j; const float dcy = (jj <= i) ? __expf(lgf * (float)(i - jj)) : __expf(lgb * (float)(jj - i)); a[j] = a[j] * 0.125f * dcy; }
;             s[t] = a;
;         }
	v_mfma_f32_16x16x32_bf16 v[58:61], v[58:61], v[62:65], 0
	v_lshl_add_u64 v[66:67], v[66:67], 0, v[68:69]
	s_waitcnt lgkmcnt(0)
	v_mfma_f32_16x16x32_bf16 v[58:61], v[76:79], v[72:75], v[58:61]
	ds_read_b64_tr_b16 v[76:77], v80 offset:224
	ds_read_b64_tr_b16 v[78:79], v80 offset:4832
	s_waitcnt lgkmcnt(0)
	v_mfma_f32_16x16x32_bf16 v[62:65], v[76:79], v[62:65], 0
	ds_read_b64_tr_b16 v[76:77], v80 offset:9440
	ds_read_b64_tr_b16 v[78:79], v80 offset:14048
	s_waitcnt lgkmcnt(0)
	v_mfma_f32_16x16x32_bf16 v[62:65], v[76:79], v[72:75], v[62:65]
	global_load_dwordx4 v[78:81], v[66:67], off
	global_load_dwordx4 v[74:77], v[66:67], off offset:64
	v_mul_u32_u24_e32 v66, 0x90, v70
	v_add3_u32 v103, 0, v68, v66
	ds_read_b128 v[66:69], v103
	ds_read_b128 v[70:73], v103 offset:64
	s_waitcnt vmcnt(1) lgkmcnt(1)
	v_mfma_f32_16x16x32_bf16 v[66:69], v[66:69], v[78:81], 0
	ds_read_b128 v[82:85], v103 offset:2368
	ds_read_b128 v[86:89], v103 offset:4672
	ds_read_b128 v[104:107], v103 offset:6976
	s_waitcnt vmcnt(0) lgkmcnt(3)
	v_mfma_f32_16x16x32_bf16 v[66:69], v[70:73], v[74:77], v[66:69]
	v_sub_u32_e32 v70, v102, v99
	v_sub_u32_e32 v71, 0, v70
	v_max_i32_e32 v70, v70, v71
	v_cvt_f32_u32_e32 v70, v70
	v_cndmask_b32_e32 v71, v1, v98, vcc
	v_cmp_lt_i32_e32 vcc, v102, v99
	ds_read_b128 v[108:111], v103 offset:9280
	v_mul_f32_e32 v70, v71, v70
	v_mul_f32_e32 v70, 0xbfb8aa3b, v70
	v_exp_f32_e32 v120, v70
	v_or_b32_e32 v70, 1, v102
	v_sub_u32_e32 v71, v70, v99
	v_sub_u32_e32 v70, v99, v70
	v_cndmask_b32_e32 v70, v71, v70, vcc
	v_cvt_f32_i32_e32 v70, v70
	v_cndmask_b32_e32 v71, v98, v1, vcc
	v_mul_f32_e32 v66, 0x3e000000, v66
	v_mul_f32_e32 v69, 0x3e000000, v69
	v_mul_f32_e32 v70, v71, v70
	v_mul_f32_e32 v70, 0xbfb8aa3b, v70
	v_exp_f32_e32 v121, v70
	v_or_b32_e32 v70, 2, v102
	v_cmp_gt_i32_e32 vcc, v70, v99
	v_sub_u32_e32 v70, v70, v99
	v_sub_u32_e32 v71, 0, v70
	v_max_i32_e32 v70, v70, v71
	v_cvt_f32_u32_e32 v70, v70
	v_cndmask_b32_e32 v71, v1, v98, vcc
	ds_read_b128 v[112:115], v103 offset:11584
	ds_read_b128 v[116:119], v103 offset:13888
	v_mul_f32_e32 v70, v71, v70
	v_mul_f32_e32 v70, 0xbfb8aa3b, v70
	v_exp_f32_e32 v122, v70
	v_or_b32_e32 v70, 3, v102
	v_cmp_gt_i32_e32 vcc, v70, v99
	v_sub_u32_e32 v70, v70, v99
	v_sub_u32_e32 v71, 0, v70
	v_max_i32_e32 v70, v70, v71
	v_cvt_f32_u32_e32 v70, v70
	v_cndmask_b32_e32 v71, v1, v98, vcc
	v_mul_f32_e32 v70, v71, v70
	v_mul_f32_e32 v70, 0xbfb8aa3b, v70
	v_exp_f32_e32 v123, v70
	ds_read_b128 v[70:73], v103 offset:2304
	s_waitcnt lgkmcnt(0)
	v_mfma_f32_16x16x32_bf16 v[70:73], v[70:73], v[78:81], 0
	v_mul_f32_e32 v69, v123, v69
	v_mfma_f32_16x16x32_bf16 v[70:73], v[82:85], v[74:77], v[70:73]
	v_or_b32_e32 v82, 16, v102
	v_cmp_gt_i32_e32 vcc, v82, v99
	v_sub_u32_e32 v82, v82, v99
	v_sub_u32_e32 v83, 0, v82
	v_max_i32_e32 v82, v82, v83
	v_cvt_f32_u32_e32 v82, v82
	v_cndmask_b32_e32 v83, v1, v98, vcc
	s_nop 0
	v_mul_f32_e32 v73, 0x3e000000, v73
	v_mul_f32_e32 v70, 0x3e000000, v70
	v_mul_f32_e32 v82, v83, v82
	v_mul_f32_e32 v82, 0xbfb8aa3b, v82
	v_exp_f32_e32 v124, v82
	v_or_b32_e32 v82, 17, v102
	v_cmp_gt_i32_e32 vcc, v82, v99
	v_sub_u32_e32 v82, v82, v99
	v_sub_u32_e32 v83, 0, v82
	v_max_i32_e32 v82, v82, v83
	v_cvt_f32_u32_e32 v82, v82
	v_cndmask_b32_e32 v83, v1, v98, vcc
	v_mul_f32_e32 v71, 0x3e000000, v71
	v_mul_f32_e32 v72, 0x3e000000, v72
	v_mul_f32_e32 v82, v83, v82
	v_mul_f32_e32 v82, 0xbfb8aa3b, v82
	v_exp_f32_e32 v125, v82
	v_or_b32_e32 v82, 18, v102
	v_cmp_gt_i32_e32 vcc, v82, v99
	v_sub_u32_e32 v82, v82, v99
	v_sub_u32_e32 v83, 0, v82
	v_max_i32_e32 v82, v82, v83
	v_cvt_f32_u32_e32 v82, v82
	v_cndmask_b32_e32 v83, v1, v98, vcc
	v_mul_f32_e32 v70, v124, v70
	v_mul_f32_e32 v71, v125, v71
	v_mul_f32_e32 v82, v83, v82
	v_mul_f32_e32 v82, 0xbfb8aa3b, v82
	v_exp_f32_e32 v126, v82
	v_or_b32_e32 v82, 19, v102
	v_cmp_gt_i32_e32 vcc, v82, v99
	v_sub_u32_e32 v82, v82, v99
	v_sub_u32_e32 v83, 0, v82
	v_max_i32_e32 v82, v82, v83
	v_cvt_f32_u32_e32 v82, v82
	v_cndmask_b32_e32 v83, v1, v98, vcc
	v_mul_f32_e32 v72, v126, v72
	v_mul_f32_e32 v82, v83, v82
	v_mul_f32_e32 v82, 0xbfb8aa3b, v82
	v_exp_f32_e32 v127, v82
	ds_read_b128 v[82:85], v103 offset:4608
	s_waitcnt lgkmcnt(0)
	v_mfma_f32_16x16x32_bf16 v[82:85], v[82:85], v[78:81], 0
	v_mul_f32_e32 v73, v127, v73
	v_mfma_f32_16x16x32_bf16 v[82:85], v[86:89], v[74:77], v[82:85]
	v_or_b32_e32 v86, 32, v102
	v_cmp_gt_i32_e32 vcc, v86, v99
	v_sub_u32_e32 v86, v86, v99
	v_sub_u32_e32 v87, 0, v86
	v_max_i32_e32 v86, v86, v87
	v_cvt_f32_u32_e32 v86, v86
	v_cndmask_b32_e32 v87, v1, v98, vcc
	s_nop 0
	v_mul_f32_e32 v85, 0x3e000000, v85
	v_mul_f32_e32 v82, 0x3e000000, v82
	v_mul_f32_e32 v86, v87, v86
	v_mul_f32_e32 v86, 0xbfb8aa3b, v86
	v_exp_f32_e32 v128, v86
	v_or_b32_e32 v86, 33, v102
	v_cmp_gt_i32_e32 vcc, v86, v99
	v_sub_u32_e32 v86, v86, v99
	v_sub_u32_e32 v87, 0, v86
	v_max_i32_e32 v86, v86, v87
	v_cvt_f32_u32_e32 v86, v86
	v_cndmask_b32_e32 v87, v1, v98, vcc
	v_mul_f32_e32 v83, 0x3e000000, v83
	v_mul_f32_e32 v84, 0x3e000000, v84
	v_mul_f32_e32 v86, v87, v86
	v_mul_f32_e32 v86, 0xbfb8aa3b, v86
	v_exp_f32_e32 v129, v86
	v_or_b32_e32 v86, 34, v102
	v_cmp_gt_i32_e32 vcc, v86, v99
	v_sub_u32_e32 v86, v86, v99
	v_sub_u32_e32 v87, 0, v86
	v_max_i32_e32 v86, v86, v87
	v_cvt_f32_u32_e32 v86, v86
	v_cndmask_b32_e32 v87, v1, v98, vcc
	v_mul_f32_e32 v82, v128, v82
	v_mul_f32_e32 v83, v129, v83
	v_mul_f32_e32 v86, v87, v86
	v_mul_f32_e32 v86, 0xbfb8aa3b, v86
	v_exp_f32_e32 v130, v86
	v_or_b32_e32 v86, 35, v102
	v_cmp_gt_i32_e32 vcc, v86, v99
	v_sub_u32_e32 v86, v86, v99
	v_sub_u32_e32 v87, 0, v86
	v_max_i32_e32 v86, v86, v87
	v_cvt_f32_u32_e32 v86, v86
	v_cndmask_b32_e32 v87, v1, v98, vcc
	v_mul_f32_e32 v84, v130, v84
	v_mul_f32_e32 v86, v87, v86
	v_mul_f32_e32 v86, 0xbfb8aa3b, v86
	v_exp_f32_e32 v131, v86
	ds_read_b128 v[86:89], v103 offset:6912
	s_waitcnt lgkmcnt(0)
; #define LAS __attribute__((address_space(3)))
; __device__ __forceinline__ void mixB3_mfma_unit(const bf16* Z, const float* ST, bf16* Yb, LAS unsigned char* lds, int gn, int hb, float lgf, float lgb, int tid) {
;     ...
;     {
;         const bf16x8_t qf0 = *(const bf16x8_t*)(qp + 8 * q), qf1 = *(const bf16x8_t*)(qp + 32 + 8 * q);
;         f32x4 s[8];
; #pragma unroll
;         for (int t = 0; t < 8; ++t) {
;             LAS unsigned char* kp = lds + B3_K + (16 * t + n) * KPITCH + q * 16;
;             f32x4 a = {0.f, 0.f, 0.f, 0.f};
;             a = __builtin_amdgcn_mfma_f32_16x16x32_bf16(*(LAS bf16x8_t*)kp, qf0, a, 0, 0, 0);
;             a = __builtin_amdgcn_mfma_f32_16x16x32_bf16(*(LAS bf16x8_t*)(kp + 64), qf1, a, 0, 0, 0);
; #pragma unroll
;             for (int j = 0; j < 4; ++j) { const int jj = 16 * t + 4 * q + j; const float dcy = (jj <= i) ? __expf(lgf * (float)(i - jj)) : __expf(lgb * (float)(jj - i)); a[j] = a[j] * 0.125f * dcy; }
;             s[t] = a;
;         }
	v_mfma_f32_16x16x32_bf16 v[86:89], v[86:89], v[78:81], 0
	v_mul_f32_e32 v85, v131, v85
	v_mfma_f32_16x16x32_bf16 v[86:89], v[104:107], v[74:77], v[86:89]
	v_or_b32_e32 v104, 48, v102
	v_cmp_gt_i32_e32 vcc, v104, v99
	v_sub_u32_e32 v104, v104, v99
	v_sub_u32_e32 v105, 0, v104
	v_max_i32_e32 v104, v104, v105
	v_cvt_f32_u32_e32 v104, v104
	v_cndmask_b32_e32 v105, v1, v98, vcc
	s_nop 0
	v_mul_f32_e32 v89, 0x3e000000, v89
	v_mul_f32_e32 v86, 0x3e000000, v86
	v_mul_f32_e32 v104, v105, v104
	v_mul_f32_e32 v104, 0xbfb8aa3b, v104
	v_exp_f32_e32 v132, v104
	v_or_b32_e32 v104, 49, v102
	v_cmp_gt_i32_e32 vcc, v104, v99
	v_sub_u32_e32 v104, v104, v99
	v_sub_u32_e32 v105, 0, v104
	v_max_i32_e32 v104, v104, v105
	v_cvt_f32_u32_e32 v104, v104
	v_cndmask_b32_e32 v105, v1, v98, vcc
	v_mul_f32_e32 v87, 0x3e000000, v87
	v_mul_f32_e32 v88, 0x3e000000, v88
	v_mul_f32_e32 v104, v105, v104
	v_mul_f32_e32 v104, 0xbfb8aa3b, v104
	v_exp_f32_e32 v133, v104
	v_or_b32_e32 v104, 50, v102
	v_cmp_gt_i32_e32 vcc, v104, v99
	v_sub_u32_e32 v104, v104, v99
	v_sub_u32_e32 v105, 0, v104
	v_max_i32_e32 v104, v104, v105
	v_cvt_f32_u32_e32 v104, v104
	v_cndmask_b32_e32 v105, v1, v98, vcc
	v_mul_f32_e32 v86, v132, v86
	v_mul_f32_e32 v87, v133, v87
	v_mul_f32_e32 v104, v105, v104
	v_mul_f32_e32 v104, 0xbfb8aa3b, v104
	v_exp_f32_e32 v134, v104
	v_or_b32_e32 v104, 51, v102
	v_cmp_gt_i32_e32 vcc, v104, v99
	v_sub_u32_e32 v104, v104, v99
	v_sub_u32_e32 v105, 0, v104
	v_max_i32_e32 v104, v104, v105
	v_cvt_f32_u32_e32 v104, v104
	v_cndmask_b32_e32 v105, v1, v98, vcc
	v_mul_f32_e32 v88, v134, v88
	v_mul_f32_e32 v104, v105, v104
	v_mul_f32_e32 v104, 0xbfb8aa3b, v104
	v_exp_f32_e32 v135, v104
	ds_read_b128 v[104:107], v103 offset:9216
	s_waitcnt lgkmcnt(0)
	v_mfma_f32_16x16x32_bf16 v[104:107], v[104:107], v[78:81], 0
	v_mul_f32_e32 v89, v135, v89
	v_mfma_f32_16x16x32_bf16 v[104:107], v[108:111], v[74:77], v[104:107]
	v_or_b32_e32 v108, 64, v102
	v_cmp_gt_i32_e32 vcc, v108, v99
	v_sub_u32_e32 v108, v108, v99
	v_sub_u32_e32 v109, 0, v108
	v_max_i32_e32 v108, v108, v109
	v_cvt_f32_u32_e32 v108, v108
	v_cndmask_b32_e32 v109, v1, v98, vcc
	s_nop 0
	v_mul_f32_e32 v107, 0x3e000000, v107
	v_mul_f32_e32 v104, 0x3e000000, v104
	v_mul_f32_e32 v108, v109, v108
	v_mul_f32_e32 v108, 0xbfb8aa3b, v108
	v_exp_f32_e32 v136, v108
	v_or_b32_e32 v108, 0x41, v102
	v_cmp_gt_i32_e32 vcc, v108, v99
	v_sub_u32_e32 v108, v108, v99
	v_sub_u32_e32 v109, 0, v108
	v_max_i32_e32 v108, v108, v109
	v_cvt_f32_u32_e32 v108, v108
	v_cndmask_b32_e32 v109, v1, v98, vcc
	v_mul_f32_e32 v105, 0x3e000000, v105
	v_mul_f32_e32 v106, 0x3e000000, v106
	v_mul_f32_e32 v108, v109, v108
	v_mul_f32_e32 v108, 0xbfb8aa3b, v108
	v_exp_f32_e32 v137, v108
	v_or_b32_e32 v108, 0x42, v102
	v_cmp_gt_i32_e32 vcc, v108, v99
	v_sub_u32_e32 v108, v108, v99
	v_sub_u32_e32 v109, 0, v108
	v_max_i32_e32 v108, v108, v109
	v_cvt_f32_u32_e32 v108, v108
	v_cndmask_b32_e32 v109, v1, v98, vcc
	v_mul_f32_e32 v104, v136, v104
	v_mul_f32_e32 v105, v137, v105
	v_mul_f32_e32 v108, v109, v108
	v_mul_f32_e32 v108, 0xbfb8aa3b, v108
	v_exp_f32_e32 v138, v108
	v_or_b32_e32 v108, 0x43, v102
	v_cmp_gt_i32_e32 vcc, v108, v99
	v_sub_u32_e32 v108, v108, v99
	v_sub_u32_e32 v109, 0, v108
	v_max_i32_e32 v108, v108, v109
	v_cvt_f32_u32_e32 v108, v108
	v_cndmask_b32_e32 v109, v1, v98, vcc
	v_mul_f32_e32 v106, v138, v106
	v_mul_f32_e32 v108, v109, v108
	v_mul_f32_e32 v108, 0xbfb8aa3b, v108
	v_exp_f32_e32 v139, v108
	ds_read_b128 v[108:111], v103 offset:11520
	s_waitcnt lgkmcnt(0)
	v_mfma_f32_16x16x32_bf16 v[108:111], v[108:111], v[78:81], 0
	v_mul_f32_e32 v107, v139, v107
	v_mfma_f32_16x16x32_bf16 v[108:111], v[112:115], v[74:77], v[108:111]
	v_or_b32_e32 v112, 0x50, v102
	v_cmp_gt_i32_e32 vcc, v112, v99
	v_sub_u32_e32 v112, v112, v99
	v_sub_u32_e32 v113, 0, v112
	v_max_i32_e32 v112, v112, v113
	v_cvt_f32_u32_e32 v112, v112
	v_cndmask_b32_e32 v113, v1, v98, vcc
	s_nop 0
	v_mul_f32_e32 v108, 0x3e000000, v108
	v_mul_f32_e32 v109, 0x3e000000, v109
	v_mul_f32_e32 v112, v113, v112
	v_mul_f32_e32 v112, 0xbfb8aa3b, v112
	v_exp_f32_e32 v140, v112
	v_or_b32_e32 v112, 0x51, v102
	v_cmp_gt_i32_e32 vcc, v112, v99
	v_sub_u32_e32 v112, v112, v99
	v_sub_u32_e32 v113, 0, v112
	v_max_i32_e32 v112, v112, v113
	v_cvt_f32_u32_e32 v112, v112
	v_cndmask_b32_e32 v113, v1, v98, vcc
	v_mul_f32_e32 v110, 0x3e000000, v110
	v_mul_f32_e32 v108, v140, v108
	v_mul_f32_e32 v112, v113, v112
	v_mul_f32_e32 v112, 0xbfb8aa3b, v112
	v_exp_f32_e32 v141, v112
	v_or_b32_e32 v112, 0x52, v102
	v_cmp_gt_i32_e32 vcc, v112, v99
	v_sub_u32_e32 v112, v112, v99
	v_sub_u32_e32 v113, 0, v112
	v_max_i32_e32 v112, v112, v113
	v_cvt_f32_u32_e32 v112, v112
	v_cndmask_b32_e32 v113, v1, v98, vcc
	v_mul_f32_e32 v109, v141, v109
	v_mul_f32_e32 v112, v113, v112
	v_mul_f32_e32 v112, 0xbfb8aa3b, v112
	v_exp_f32_e32 v142, v112
	v_or_b32_e32 v112, 0x53, v102
	v_cmp_gt_i32_e32 vcc, v112, v99
	v_sub_u32_e32 v112, v112, v99
	v_sub_u32_e32 v113, 0, v112
	v_max_i32_e32 v112, v112, v113
	v_cvt_f32_u32_e32 v112, v112
	v_cndmask_b32_e32 v113, v1, v98, vcc
	v_mul_f32_e32 v110, v142, v110
	v_mul_f32_e32 v112, v113, v112
	v_mul_f32_e32 v112, 0xbfb8aa3b, v112
	v_exp_f32_e32 v143, v112
	ds_read_b128 v[112:115], v103 offset:13824
	s_waitcnt lgkmcnt(0)
; #define LAS __attribute__((address_space(3)))
; __device__ __forceinline__ void mixB3_mfma_unit(const bf16* Z, const float* ST, bf16* Yb, LAS unsigned char* lds, int gn, int hb, float lgf, float lgb, int tid) {
;     ...
;         const float cf = __expf(lgf * (float)(i + 1)), cb = __expf(lgb * (float)(128 - i));
; #pragma unroll
;         for (int et = 0; et < 8; ++et) {
;             LAS unsigned char* sf = lds + B3_SF + rsel * VPITCH + et * 32 + csel;
;             LAS unsigned char* sb = lds + B3_SB + rsel * VPITCH + et * 32 + csel;
;             f32x4 f = {0.f, 0.f, 0.f, 0.f}, b = {0.f, 0.f, 0.f, 0.f};
;             f = __builtin_amdgcn_mfma_f32_16x16x32_bf16(cat4(trread(sf), trread(sf + 16 * VPITCH)), qc0, f, 0, 0, 0);
;             f = __builtin_amdgcn_mfma_f32_16x16x32_bf16(cat4(trread(sf + 32 * VPITCH), trread(sf + 48 * VPITCH)), qc1, f, 0, 0, 0);
;             b = __builtin_amdgcn_mfma_f32_16x16x32_bf16(cat4(trread(sb), trread(sb + 16 * VPITCH)), qc0, b, 0, 0, 0);
;             b = __builtin_amdgcn_mfma_f32_16x16x32_bf16(cat4(trread(sb + 32 * VPITCH), trread(sb + 48 * VPITCH)), qc1, b, 0, 0, 0);
;             o[et] = f * cf + b * cb;
;         }
;     }
;     {
;         const bf16x8_t qf0 = *(const bf16x8_t*)(qp + 8 * q), qf1 = *(const bf16x8_t*)(qp + 32 + 8 * q);
;         f32x4 s[8];
; #pragma unroll
;         for (int t = 0; t < 8; ++t) {
;             LAS unsigned char* kp = lds + B3_K + (16 * t + n) * KPITCH + q * 16;
;             f32x4 a = {0.f, 0.f, 0.f, 0.f};
;             a = __builtin_amdgcn_mfma_f32_16x16x32_bf16(*(LAS bf16x8_t*)kp, qf0, a, 0, 0, 0);
;             a = __builtin_amdgcn_mfma_f32_16x16x32_bf16(*(LAS bf16x8_t*)(kp + 64), qf1, a, 0, 0, 0);
; #pragma unroll
;             for (int j = 0; j < 4; ++j) { const int jj = 16 * t + 4 * q + j; const float dcy = (jj <= i) ? __expf(lgf * (float)(i - jj)) : __expf(lgb * (float)(jj - i)); a[j] = a[j] * 0.125f * dcy; }
;             s[t] = a;
;         }
; #pragma unroll
;         for (int G = 0; G < 4; ++G) {
;             const bf16x8_t pb = packp(s[2 * G], s[2 * G + 1]);
; #pragma unroll
;             for (int et = 0; et < 8; ++et) {
;                 LAS unsigned char* vp = lds + B3_V + (32 * G + rsel) * VPITCH + et * 32 + csel;
;                 o[et] = __builtin_amdgcn_mfma_f32_16x16x32_bf16(cat4(trread(vp), trread(vp + 16 * VPITCH)), pb, o[et], 0, 0, 0);
;             }
;         }
	v_mfma_f32_16x16x32_bf16 v[112:115], v[112:115], v[78:81], 0
	v_mfma_f32_16x16x32_bf16 v[112:115], v[116:119], v[74:77], v[112:115]
	v_or_b32_e32 v116, 0x60, v102
	v_cmp_gt_i32_e32 vcc, v116, v99
	v_sub_u32_e32 v116, v116, v99
	v_sub_u32_e32 v117, 0, v116
	v_max_i32_e32 v116, v116, v117
	v_cvt_f32_u32_e32 v116, v116
	v_cndmask_b32_e32 v117, v1, v98, vcc
	v_mul_f32_e32 v116, v117, v116
	v_mul_f32_e32 v116, 0xbfb8aa3b, v116
	v_exp_f32_e32 v144, v116
	v_or_b32_e32 v116, 0x61, v102
	v_cmp_gt_i32_e32 vcc, v116, v99
	v_sub_u32_e32 v116, v116, v99
	v_sub_u32_e32 v117, 0, v116
	v_max_i32_e32 v116, v116, v117
	v_cvt_f32_u32_e32 v116, v116
	v_cndmask_b32_e32 v117, v1, v98, vcc
	v_mul_f32_e32 v116, v117, v116
	v_mul_f32_e32 v116, 0xbfb8aa3b, v116
	v_exp_f32_e32 v145, v116
	v_or_b32_e32 v116, 0x62, v102
	v_cmp_gt_i32_e32 vcc, v116, v99
	v_sub_u32_e32 v116, v116, v99
	v_sub_u32_e32 v117, 0, v116
	v_max_i32_e32 v116, v116, v117
	v_cvt_f32_u32_e32 v116, v116
	v_cndmask_b32_e32 v117, v1, v98, vcc
	v_mul_f32_e32 v116, v117, v116
	v_mul_f32_e32 v116, 0xbfb8aa3b, v116
	v_exp_f32_e32 v146, v116
	v_or_b32_e32 v116, 0x63, v102
	v_cmp_gt_i32_e32 vcc, v116, v99
	v_sub_u32_e32 v116, v116, v99
	v_sub_u32_e32 v117, 0, v116
	v_max_i32_e32 v116, v116, v117
	v_cvt_f32_u32_e32 v116, v116
	v_cndmask_b32_e32 v117, v1, v98, vcc
	v_mul_f32_e32 v116, v117, v116
	v_mul_f32_e32 v116, 0xbfb8aa3b, v116
	v_exp_f32_e32 v147, v116
	ds_read_b128 v[116:119], v103 offset:16128
	s_waitcnt lgkmcnt(0)
	v_mfma_f32_16x16x32_bf16 v[78:81], v[116:119], v[78:81], 0
	ds_read_b128 v[116:119], v103 offset:16192
	v_mul_f32_e32 v103, 0x3e000000, v111
	v_mul_f32_e32 v111, v120, v66
	s_waitcnt lgkmcnt(0)
	v_mfma_f32_16x16x32_bf16 v[74:77], v[116:119], v[74:77], v[78:81]
	s_nop 2
	v_or_b32_e32 v78, 0x70, v102
	v_cmp_gt_i32_e32 vcc, v78, v99
	v_sub_u32_e32 v78, v78, v99
	v_sub_u32_e32 v79, 0, v78
	v_max_i32_e32 v78, v78, v79
	v_cvt_f32_u32_e32 v78, v78
	v_cndmask_b32_e32 v79, v1, v98, vcc
	v_mul_f32_e32 v66, 0x3e000000, v67
	v_mul_f32_e32 v75, 0x3e000000, v75
	v_mul_f32_e32 v78, v79, v78
	v_or_b32_e32 v79, 0x71, v102
	v_cmp_gt_i32_e32 vcc, v79, v99
	v_sub_u32_e32 v79, v79, v99
	v_sub_u32_e32 v80, 0, v79
	v_max_i32_e32 v79, v79, v80
	v_cvt_f32_u32_e32 v79, v79
	v_cndmask_b32_e32 v80, v1, v98, vcc
	v_mul_f32_e32 v67, v121, v66
	v_mul_f32_e32 v66, 0x3e000000, v68
	v_mul_f32_e32 v79, v80, v79
	v_or_b32_e32 v80, 0x72, v102
	v_mul_f32_e32 v79, 0xbfb8aa3b, v79
	v_cmp_gt_i32_e32 vcc, v80, v99
	v_sub_u32_e32 v80, v80, v99
	v_exp_f32_e32 v79, v79
	v_sub_u32_e32 v81, 0, v80
	v_max_i32_e32 v80, v80, v81
	v_cvt_f32_u32_e32 v80, v80
	v_mul_f32_e32 v75, v79, v75
	v_mul_f32_e32 v79, 0x3e000000, v112
	v_mul_f32_e32 v112, v122, v66
	v_add_u32_e32 v66, 1, v99
	v_cndmask_b32_e32 v81, v1, v98, vcc
	v_cvt_f32_i32_e32 v66, v66
	v_mul_f32_e32 v80, v81, v80
	v_or_b32_e32 v81, 0x73, v102
	v_cmp_gt_i32_e32 vcc, v81, v99
	v_sub_u32_e32 v81, v81, v99
	v_sub_u32_e32 v102, 0, v81
	v_max_i32_e32 v81, v81, v102
	v_cndmask_b32_e32 v102, v1, v98, vcc
	v_mul_f32_e32 v1, v66, v1
	v_mul_f32_e32 v1, 0xbfb8aa3b, v1
	v_exp_f32_e32 v66, v1
	v_sub_u32_e32 v1, 0x80, v99
	v_cvt_f32_i32_e32 v1, v1
	v_mul_f32_e32 v103, v143, v103
	v_cvt_f32_u32_e32 v81, v81
	v_mul_f32_e32 v78, 0xbfb8aa3b, v78
	v_mul_f32_e32 v1, v1, v98
	v_mul_f32_e32 v1, 0xbfb8aa3b, v1
	v_exp_f32_e32 v68, v1
	v_mul_f32_e32 v80, 0xbfb8aa3b, v80
	v_mul_f32_e32 v81, v102, v81
	v_exp_f32_e32 v78, v78
	v_pk_mul_f32 v[54:55], v[68:69], v[54:55] op_sel_hi:[0,1]
	v_pk_fma_f32 v[50:51], v[66:67], v[50:51], v[54:55] op_sel_hi:[0,1,1]
	v_pk_mul_f32 v[22:23], v[68:69], v[22:23] op_sel_hi:[0,1]
	v_pk_mul_f32 v[24:25], v[68:69], v[24:25] op_sel_hi:[0,1]
	v_pk_mul_f32 v[14:15], v[68:69], v[14:15] op_sel_hi:[0,1]
	v_pk_mul_f32 v[16:17], v[68:69], v[16:17] op_sel_hi:[0,1]
	v_pk_mul_f32 v[6:7], v[6:7], v[68:69] op_sel_hi:[1,0]
	v_pk_mul_f32 v[8:9], v[8:9], v[68:69] op_sel_hi:[1,0]
	v_add3_u32 v54, 0, v100, v101
	v_pk_fma_f32 v[20:21], v[66:67], v[20:21], v[24:25] op_sel_hi:[0,1,1]
	v_pk_fma_f32 v[18:19], v[66:67], v[18:19], v[22:23] op_sel_hi:[0,1,1]
	v_pk_fma_f32 v[12:13], v[66:67], v[12:13], v[16:17] op_sel_hi:[0,1,1]
	v_pk_fma_f32 v[10:11], v[66:67], v[10:11], v[14:15] op_sel_hi:[0,1,1]
	v_pk_fma_f32 v[4:5], v[4:5], v[66:67], v[8:9] op_sel_hi:[1,0,1]
	v_pk_fma_f32 v[2:3], v[2:3], v[66:67], v[6:7] op_sel_hi:[1,0,1]
	v_cvt_pk_bf16_f32 v6, v111, v67
	v_cvt_pk_bf16_f32 v7, v112, v69
	v_cvt_pk_bf16_f32 v8, v70, v71
	v_cvt_pk_bf16_f32 v9, v72, v73
	ds_read_b64_tr_b16 v[16:17], v54 offset:23040
	ds_read_b64_tr_b16 v[14:15], v54 offset:18432
	ds_read_b64_tr_b16 v[22:23], v54 offset:18464
	ds_read_b64_tr_b16 v[24:25], v54 offset:23072
	s_waitcnt lgkmcnt(2)
	v_mfma_f32_16x16x32_bf16 v[2:5], v[14:17], v[6:9], v[2:5]
	ds_read_b64_tr_b16 v[14:15], v54 offset:18496
	ds_read_b64_tr_b16 v[16:17], v54 offset:23104
	v_pk_mul_f32 v[38:39], v[68:69], v[38:39] op_sel_hi:[0,1]
	v_pk_mul_f32 v[40:41], v[68:69], v[40:41] op_sel_hi:[0,1]
	s_waitcnt lgkmcnt(2)
	v_mfma_f32_16x16x32_bf16 v[10:13], v[22:25], v[6:9], v[10:13]
	v_mul_f32_e64 v30, v68, v30
	v_mul_f32_e64 v31, v68, v31
	v_pk_mul_f32 v[32:33], v[68:69], v[32:33] op_sel_hi:[0,1]
	v_pk_fma_f32 v[36:37], v[66:67], v[36:37], v[40:41] op_sel_hi:[0,1,1]
	s_waitcnt lgkmcnt(0)
	v_mfma_f32_16x16x32_bf16 v[14:17], v[14:17], v[6:9], v[18:21]
	s_nop 2
	ds_read_b64_tr_b16 v[18:19], v54 offset:18528
	ds_read_b64_tr_b16 v[20:21], v54 offset:23136
	ds_read_b64_tr_b16 v[22:23], v54 offset:18560
	ds_read_b64_tr_b16 v[24:25], v54 offset:23168
	v_pk_fma_f32 v[34:35], v[66:67], v[34:35], v[38:39] op_sel_hi:[0,1,1]
	v_pk_fma_f32 v[28:29], v[66:67], v[28:29], v[32:33] op_sel_hi:[0,1,1]
	v_pk_fma_f32 v[26:27], v[66:67], v[26:27], v[30:31] op_sel_hi:[0,1,1]
	s_waitcnt lgkmcnt(0)
; #define LAS __attribute__((address_space(3)))
; __device__ __forceinline__ s16x4_t trread(LAS unsigned char* p) { return __builtin_amdgcn_ds_read_tr16_b64_v4i16((LAS s16x4_t*)p); }
; __device__ __forceinline__ bf16x8_t cat4(s16x4_t a, s16x4_t b) { return (bf16x8_t){a[0], a[1], a[2], a[3], b[0], b[1], b[2], b[3]}; }
; __device__ __forceinline__ void mixB3_mfma_unit(const bf16* Z, const float* ST, bf16* Yb, LAS unsigned char* lds, int gn, int hb, float lgf, float lgb, int tid) {
;     ...
; #pragma unroll
;         for (int G = 0; G < 4; ++G) {
;             const bf16x8_t pb = packp(s[2 * G], s[2 * G + 1]);
; #pragma unroll
;             for (int et = 0; et < 8; ++et) {
;                 LAS unsigned char* vp = lds + B3_V + (32 * G + rsel) * VPITCH + et * 32 + csel;
;                 o[et] = __builtin_amdgcn_mfma_f32_16x16x32_bf16(cat4(trread(vp), trread(vp + 16 * VPITCH)), pb, o[et], 0, 0, 0);
;             }
;         }
	v_mfma_f32_16x16x32_bf16 v[22:25], v[22:25], v[6:9], v[34:37]
	v_mul_f32_e64 v62, v68, v62
	v_mul_f32_e64 v63, v68, v63
	v_pk_mul_f32 v[64:65], v[68:69], v[64:65] op_sel_hi:[0,1]
	v_pk_mul_f32 v[56:57], v[68:69], v[56:57] op_sel_hi:[0,1]
	v_mfma_f32_16x16x32_bf16 v[18:21], v[18:21], v[6:9], v[26:29]
	s_nop 2
	ds_read_b64_tr_b16 v[26:27], v54 offset:18592
	ds_read_b64_tr_b16 v[28:29], v54 offset:23200
	ds_read_b64_tr_b16 v[30:31], v54 offset:18624
	ds_read_b64_tr_b16 v[32:33], v54 offset:23232
	ds_read_b64_tr_b16 v[34:35], v54 offset:18656
	ds_read_b64_tr_b16 v[36:37], v54 offset:23264
	v_pk_mul_f32 v[46:47], v[68:69], v[46:47] op_sel_hi:[0,1]
	v_pk_mul_f32 v[48:49], v[68:69], v[48:49] op_sel_hi:[0,1]
	v_pk_fma_f32 v[60:61], v[66:67], v[60:61], v[64:65] op_sel_hi:[0,1,1]
	v_pk_fma_f32 v[58:59], v[66:67], v[58:59], v[62:63] op_sel_hi:[0,1,1]
	v_pk_fma_f32 v[52:53], v[66:67], v[52:53], v[56:57] op_sel_hi:[0,1,1]
	v_pk_fma_f32 v[44:45], v[66:67], v[44:45], v[48:49] op_sel_hi:[0,1,1]
	v_pk_fma_f32 v[42:43], v[66:67], v[42:43], v[46:47] op_sel_hi:[0,1,1]
	s_waitcnt lgkmcnt(2)
	v_mfma_f32_16x16x32_bf16 v[30:33], v[30:33], v[6:9], v[50:53]
	v_exp_f32_e32 v80, v80
	v_mul_f32_e32 v81, 0xbfb8aa3b, v81
	v_exp_f32_e32 v81, v81
	v_mfma_f32_16x16x32_bf16 v[26:29], v[26:29], v[6:9], v[42:45]
	v_mul_f32_e32 v74, 0x3e000000, v74
	v_mul_f32_e32 v76, 0x3e000000, v76
	v_mul_f32_e32 v74, v78, v74
	s_waitcnt lgkmcnt(0)
	v_mfma_f32_16x16x32_bf16 v[6:9], v[34:37], v[6:9], v[58:61]
	v_cvt_pk_bf16_f32 v34, v82, v83
	v_cvt_pk_bf16_f32 v35, v84, v85
	v_cvt_pk_bf16_f32 v36, v86, v87
	v_cvt_pk_bf16_f32 v37, v88, v89
	ds_read_b64_tr_b16 v[40:41], v54 offset:32256
	ds_read_b64_tr_b16 v[38:39], v54 offset:27648
	ds_read_b64_tr_b16 v[42:43], v54 offset:27680
	s_waitcnt lgkmcnt(1)
	v_mfma_f32_16x16x32_bf16 v[2:5], v[38:41], v[34:37], v[2:5]
	ds_read_b64_tr_b16 v[44:45], v54 offset:32288
	ds_read_b64_tr_b16 v[38:39], v54 offset:27712
	ds_read_b64_tr_b16 v[40:41], v54 offset:32320
	v_mul_f32_e32 v76, v80, v76
	s_waitcnt lgkmcnt(0)
	v_mfma_f32_16x16x32_bf16 v[14:17], v[38:41], v[34:37], v[14:17]
	ds_read_b64_tr_b16 v[38:39], v54 offset:27744
	ds_read_b64_tr_b16 v[40:41], v54 offset:32352
	v_mul_f32_e32 v78, 0x3e000000, v115
	v_mul_f32_e32 v80, 0x3e000000, v113
	s_waitcnt lgkmcnt(0)
	v_mfma_f32_16x16x32_bf16 v[18:21], v[38:41], v[34:37], v[18:21]
	ds_read_b64_tr_b16 v[38:39], v54 offset:27776
	ds_read_b64_tr_b16 v[40:41], v54 offset:32384
	v_mul_f32_e32 v102, 0x3e000000, v114
	v_mul_f32_e32 v1, 0x3e000000, v77
	s_waitcnt lgkmcnt(0)
	v_mfma_f32_16x16x32_bf16 v[22:25], v[38:41], v[34:37], v[22:25]
	ds_read_b64_tr_b16 v[38:39], v54 offset:27808
	ds_read_b64_tr_b16 v[40:41], v54 offset:32416
	v_mul_f32_e32 v78, v147, v78
	v_mul_f32_e32 v79, v144, v79
	s_waitcnt lgkmcnt(0)
	v_mfma_f32_16x16x32_bf16 v[26:29], v[38:41], v[34:37], v[26:29]
	ds_read_b64_tr_b16 v[38:39], v54 offset:27840
	ds_read_b64_tr_b16 v[40:41], v54 offset:32448
	v_mul_f32_e32 v80, v145, v80
	v_mul_f32_e32 v102, v146, v102
	s_waitcnt lgkmcnt(0)
	v_mfma_f32_16x16x32_bf16 v[30:33], v[38:41], v[34:37], v[30:33]
	ds_read_b64_tr_b16 v[38:39], v54 offset:27872
	ds_read_b64_tr_b16 v[40:41], v54 offset:32480
	v_mul_f32_e32 v1, v81, v1
	v_mfma_f32_16x16x32_bf16 v[10:13], v[42:45], v[34:37], v[10:13]
	s_waitcnt lgkmcnt(0)
	v_mfma_f32_16x16x32_bf16 v[6:9], v[38:41], v[34:37], v[6:9]
	v_cvt_pk_bf16_f32 v34, v104, v105
	v_cvt_pk_bf16_f32 v35, v106, v107
	v_cvt_pk_bf16_f32 v36, v108, v109
	v_cvt_pk_bf16_f32 v37, v110, v103
	ds_read_b64_tr_b16 v[40:41], v54 offset:41472
	ds_read_b64_tr_b16 v[38:39], v54 offset:36864
	ds_read_b64_tr_b16 v[42:43], v54 offset:36896
	s_waitcnt lgkmcnt(1)
	v_mfma_f32_16x16x32_bf16 v[2:5], v[38:41], v[34:37], v[2:5]
	ds_read_b64_tr_b16 v[44:45], v54 offset:41504
	ds_read_b64_tr_b16 v[38:39], v54 offset:36928
	ds_read_b64_tr_b16 v[40:41], v54 offset:41536
	s_waitcnt lgkmcnt(0)
	v_mfma_f32_16x16x32_bf16 v[14:17], v[38:41], v[34:37], v[14:17]
	ds_read_b64_tr_b16 v[38:39], v54 offset:36960
	ds_read_b64_tr_b16 v[40:41], v54 offset:41568
	s_waitcnt lgkmcnt(0)
	v_mfma_f32_16x16x32_bf16 v[18:21], v[38:41], v[34:37], v[18:21]
	ds_read_b64_tr_b16 v[38:39], v54 offset:36992
	ds_read_b64_tr_b16 v[40:41], v54 offset:41600
	s_waitcnt lgkmcnt(0)
	v_mfma_f32_16x16x32_bf16 v[38:41], v[38:41], v[34:37], v[22:25]
	s_nop 2
	ds_read_b64_tr_b16 v[22:23], v54 offset:37024
	ds_read_b64_tr_b16 v[24:25], v54 offset:41632
	v_mfma_f32_16x16x32_bf16 v[10:13], v[42:45], v[34:37], v[10:13]
	s_waitcnt lgkmcnt(0)
	v_mfma_f32_16x16x32_bf16 v[42:45], v[22:25], v[34:37], v[26:29]
	ds_read_b64_tr_b16 v[22:23], v54 offset:37056
	ds_read_b64_tr_b16 v[24:25], v54 offset:41664
	s_waitcnt lgkmcnt(0)
	v_mfma_f32_16x16x32_bf16 v[46:49], v[22:25], v[34:37], v[30:33]
	ds_read_b64_tr_b16 v[22:23], v54 offset:37088
	ds_read_b64_tr_b16 v[24:25], v54 offset:41696
	v_cvt_pk_bf16_f32 v50, v79, v80
	v_cvt_pk_bf16_f32 v51, v102, v78
	s_waitcnt lgkmcnt(0)
	v_mfma_f32_16x16x32_bf16 v[34:37], v[22:25], v[34:37], v[6:9]
	v_cvt_pk_bf16_f32 v52, v74, v75
	v_cvt_pk_bf16_f32 v53, v76, v1
	s_nop 2
	ds_read_b64_tr_b16 v[8:9], v54 offset:50688
	ds_read_b64_tr_b16 v[6:7], v54 offset:46080
	ds_read_b64_tr_b16 v[22:23], v54 offset:46112
	ds_read_b64_tr_b16 v[24:25], v54 offset:50720
	s_waitcnt lgkmcnt(2)
	v_mfma_f32_16x16x32_bf16 v[30:33], v[6:9], v[50:53], v[2:5]
	s_nop 2
	ds_read_b64_tr_b16 v[2:3], v54 offset:46144
	ds_read_b64_tr_b16 v[4:5], v54 offset:50752
	s_waitcnt lgkmcnt(2)
	v_mfma_f32_16x16x32_bf16 v[26:29], v[22:25], v[50:53], v[10:13]
	s_waitcnt lgkmcnt(0)
	v_mfma_f32_16x16x32_bf16 v[22:25], v[2:5], v[50:53], v[14:17]
	ds_read_b64_tr_b16 v[2:3], v54 offset:46176
	ds_read_b64_tr_b16 v[4:5], v54 offset:50784
	s_waitcnt lgkmcnt(0)
; #define LAS __attribute__((address_space(3)))
; __device__ __forceinline__ s16x4_t trread(LAS unsigned char* p) { return __builtin_amdgcn_ds_read_tr16_b64_v4i16((LAS s16x4_t*)p); }
; __device__ __forceinline__ bf16x8_t cat4(s16x4_t a, s16x4_t b) { return (bf16x8_t){a[0], a[1], a[2], a[3], b[0], b[1], b[2], b[3]}; }
; __device__ __forceinline__ void mixB3_mfma_unit(const bf16* Z, const float* ST, bf16* Yb, LAS unsigned char* lds, int gn, int hb, float lgf, float lgb, int tid) {
;     ...
; #pragma unroll
;         for (int G = 0; G < 4; ++G) {
;             const bf16x8_t pb = packp(s[2 * G], s[2 * G + 1]);
; #pragma unroll
;             for (int et = 0; et < 8; ++et) {
;                 LAS unsigned char* vp = lds + B3_V + (32 * G + rsel) * VPITCH + et * 32 + csel;
;                 o[et] = __builtin_amdgcn_mfma_f32_16x16x32_bf16(cat4(trread(vp), trread(vp + 16 * VPITCH)), pb, o[et], 0, 0, 0);
;             }
;         }
;     }
;     float s1 = 0.f;
; #pragma unroll
;     for (int et = 0; et < 8; ++et) s1 += (o[et][0] + o[et][1]) + (o[et][2] + o[et][3]);
;     s1 += __shfl_xor(s1, 16); s1 += __shfl_xor(s1, 32);
;     const float mu = s1 * (1.f / 128.f);
;     float s2 = 0.f;
; #pragma unroll
;     for (int et = 0; et < 8; ++et) { o[et] = o[et] - mu; s2 += (o[et][0] * o[et][0] + o[et][1] * o[et][1]) + (o[et][2] * o[et][2] + o[et][3] * o[et][3]); }
;     s2 += __shfl_xor(s2, 16); s2 += __shfl_xor(s2, 32);
	v_mfma_f32_16x16x32_bf16 v[18:21], v[2:5], v[50:53], v[18:21]
	ds_read_b64_tr_b16 v[2:3], v54 offset:46208
	ds_read_b64_tr_b16 v[4:5], v54 offset:50816
	s_waitcnt lgkmcnt(0)
	v_mfma_f32_16x16x32_bf16 v[14:17], v[2:5], v[50:53], v[38:41]
	ds_read_b64_tr_b16 v[2:3], v54 offset:46240
	ds_read_b64_tr_b16 v[4:5], v54 offset:50848
	s_nop 0
	v_mov_b32_e32 v38, v33
	v_mov_b32_e32 v39, v29
	s_waitcnt lgkmcnt(0)
	v_mfma_f32_16x16x32_bf16 v[10:13], v[2:5], v[50:53], v[42:45]
	ds_read_b64_tr_b16 v[2:3], v54 offset:46272
	ds_read_b64_tr_b16 v[4:5], v54 offset:50880
	v_add_f32_e32 v40, v20, v21
	v_mov_b32_e32 v41, v17
	s_waitcnt lgkmcnt(0)
	v_mfma_f32_16x16x32_bf16 v[6:9], v[2:5], v[50:53], v[46:49]
	ds_read_b64_tr_b16 v[2:3], v54 offset:46304
	ds_read_b64_tr_b16 v[4:5], v54 offset:50912
	s_waitcnt lgkmcnt(0)
	v_mfma_f32_16x16x32_bf16 v[2:5], v[2:5], v[50:53], v[34:37]
	s_nop 2
	v_mov_b32_e32 v34, v30
	v_mov_b32_e32 v35, v26
	v_mov_b32_e32 v36, v31
	v_mov_b32_e32 v37, v27
	v_pk_add_f32 v[34:35], v[34:35], v[36:37]
	v_mov_b32_e32 v36, v32
	v_mov_b32_e32 v37, v28
	v_pk_add_f32 v[36:37], v[36:37], v[38:39]
	v_mov_b32_e32 v38, v22
	v_pk_add_f32 v[34:35], v[34:35], v[36:37]
	v_mov_b32_e32 v36, v23
	v_mov_b32_e32 v37, v24
	v_mov_b32_e32 v39, v25
	v_pk_add_f32 v[36:37], v[36:37], v[38:39]
	v_add_f32_e32 v1, 0, v34
	v_pk_add_f32 v[36:37], v[36:37], v[36:37] op_sel:[0,1] op_sel_hi:[1,0]
	v_add_f32_e32 v34, v1, v35
	v_add_f32_e32 v38, v18, v19
	v_mov_b32_e32 v35, v14
	v_mov_b32_e32 v37, v15
	v_mov_b32_e32 v39, v16
	v_pk_add_f32 v[34:35], v[34:35], v[36:37]
	v_pk_add_f32 v[36:37], v[38:39], v[40:41]
	v_mov_b32_e32 v38, v10
	v_pk_add_f32 v[34:35], v[34:35], v[36:37]
	v_mov_b32_e32 v36, v11
	v_mov_b32_e32 v37, v12
	v_mov_b32_e32 v39, v13
	v_pk_add_f32 v[36:37], v[36:37], v[38:39]
	v_pk_add_f32 v[34:35], v[34:35], v[34:35] op_sel:[0,1] op_sel_hi:[1,0]
	v_pk_add_f32 v[36:37], v[36:37], v[36:37] op_sel:[0,1] op_sel_hi:[1,0]
	v_add_f32_e32 v38, v6, v7
	v_add_f32_e32 v40, v8, v9
	v_mov_b32_e32 v35, v2
	v_mov_b32_e32 v37, v3
	v_mov_b32_e32 v39, v4
	v_mov_b32_e32 v41, v5
	v_pk_add_f32 v[34:35], v[34:35], v[36:37]
	v_pk_add_f32 v[36:37], v[38:39], v[40:41]
	s_nop 0
	v_pk_add_f32 v[34:35], v[34:35], v[36:37]
	s_nop 0
	v_add_f32_e32 v1, v34, v35
	v_and_b32_e32 v35, 64, v231
	v_xor_b32_e32 v34, 16, v231
	v_add_u32_e32 v35, 64, v35
	v_cmp_lt_i32_e32 vcc, v34, v35
	s_nop 1
	v_cndmask_b32_e32 v34, v231, v34, vcc
	v_lshlrev_b32_e32 v40, 2, v34
	ds_bpermute_b32 v34, v40, v1
	s_waitcnt lgkmcnt(0)
	v_add_f32_e32 v1, v1, v34
	v_xor_b32_e32 v34, 32, v231
	v_cmp_lt_i32_e32 vcc, v34, v35
	s_nop 1
	v_cndmask_b32_e32 v34, v231, v34, vcc
	v_lshlrev_b32_e32 v41, 2, v34
	ds_bpermute_b32 v34, v41, v1
	s_waitcnt lgkmcnt(0)
	v_add_f32_e32 v42, v1, v34
	v_fmamk_f32 v37, v42, 0xbc000000, v33
	v_fmac_f32_e32 v31, 0xbc000000, v42
	v_fmamk_f32 v38, v42, 0xbc000000, v32
	v_fmamk_f32 v39, v42, 0xbc000000, v30
	v_mul_f32_e32 v1, v31, v31
	v_mul_f32_e32 v30, v37, v37
	v_fmac_f32_e32 v1, v39, v39
	v_fmac_f32_e32 v30, v38, v38
	v_fmamk_f32 v34, v42, 0xbc000000, v29
	v_fmac_f32_e32 v27, 0xbc000000, v42
	v_add_f32_e32 v1, v1, v30
	v_fmamk_f32 v35, v42, 0xbc000000, v28
	v_fmamk_f32 v36, v42, 0xbc000000, v26
	v_mul_f32_e32 v26, v27, v27
	v_mul_f32_e32 v28, v34, v34
	v_fmamk_f32 v30, v42, 0xbc000000, v25
	v_fmac_f32_e32 v23, 0xbc000000, v42
	v_fmac_f32_e32 v26, v36, v36
	v_fmac_f32_e32 v28, v35, v35
	v_fmamk_f32 v32, v42, 0xbc000000, v24
	v_fmamk_f32 v33, v42, 0xbc000000, v22
	v_mul_f32_e32 v22, v23, v23
	v_mul_f32_e32 v24, v30, v30
	v_add_f32_e32 v26, v26, v28
	v_fmac_f32_e32 v22, v33, v33
	v_fmac_f32_e32 v24, v32, v32
	v_add_f32_e32 v1, v1, v26
	v_add_f32_e32 v22, v22, v24
	v_fmamk_f32 v26, v42, 0xbc000000, v21
	v_fmac_f32_e32 v19, 0xbc000000, v42
	v_add_f32_e32 v1, v22, v1
	v_fmamk_f32 v28, v42, 0xbc000000, v20
	v_fmamk_f32 v29, v42, 0xbc000000, v18
	v_mul_f32_e32 v18, v19, v19
	v_mul_f32_e32 v20, v26, v26
	v_fmamk_f32 v22, v42, 0xbc000000, v17
	v_fmac_f32_e32 v15, 0xbc000000, v42
	v_fmac_f32_e32 v18, v29, v29
	v_fmac_f32_e32 v20, v28, v28
	v_fmamk_f32 v24, v42, 0xbc000000, v16
	v_fmamk_f32 v25, v42, 0xbc000000, v14
	v_mul_f32_e32 v14, v15, v15
	v_mul_f32_e32 v16, v22, v22
	v_add_f32_e32 v18, v18, v20
	v_fmac_f32_e32 v14, v25, v25
	v_fmac_f32_e32 v16, v24, v24
	v_add_f32_e32 v1, v18, v1
	v_add_f32_e32 v14, v14, v16
	v_fmamk_f32 v18, v42, 0xbc000000, v13
	v_fmac_f32_e32 v11, 0xbc000000, v42
	v_add_f32_e32 v1, v14, v1
	v_fmamk_f32 v20, v42, 0xbc000000, v12
	v_fmamk_f32 v21, v42, 0xbc000000, v10
	v_mul_f32_e32 v10, v11, v11
	v_mul_f32_e32 v12, v18, v18
	v_fmamk_f32 v14, v42, 0xbc000000, v9
	v_fmac_f32_e32 v7, 0xbc000000, v42
	v_fmac_f32_e32 v10, v21, v21
	v_fmac_f32_e32 v12, v20, v20
	v_fmamk_f32 v16, v42, 0xbc000000, v8
	v_fmamk_f32 v17, v42, 0xbc000000, v6
	v_mul_f32_e32 v6, v7, v7
	v_mul_f32_e32 v8, v14, v14
	v_add_f32_e32 v10, v10, v12
	v_fmac_f32_e32 v6, v17, v17
	v_fmac_f32_e32 v8, v16, v16
	v_add_f32_e32 v1, v10, v1
	v_add_f32_e32 v6, v6, v8
	v_add_f32_e32 v8, v6, v1
	v_fmamk_f32 v1, v42, 0xbc000000, v5
	v_fmac_f32_e32 v3, 0xbc000000, v42
	v_fmamk_f32 v6, v42, 0xbc000000, v4
	v_fmamk_f32 v10, v42, 0xbc000000, v2
	v_mul_f32_e32 v2, v3, v3
	v_mul_f32_e32 v4, v1, v1
	v_fmac_f32_e32 v2, v10, v10
	v_fmac_f32_e32 v4, v6, v6
	v_add_f32_e32 v2, v2, v4
	v_add_f32_e32 v2, v2, v8
	ds_bpermute_b32 v4, v40, v2
	v_lshlrev_b64 v[12:13], 10, v[94:95]
	v_lshl_add_u64 v[12:13], s[34:35], 0, v[12:13]
	v_lshl_add_u64 v[12:13], v[12:13], 0, s[48:49]
	v_lshl_add_u64 v[12:13], v[12:13], 0, v[92:93]
	s_waitcnt lgkmcnt(0)
	v_add_f32_e32 v2, v2, v4
	ds_bpermute_b32 v4, v41, v2
	s_waitcnt lgkmcnt(0)
; __device__ __forceinline__ unsigned cvt_pk_bf16(float lo, float hi) { unsigned r; asm volatile("v_cvt_pk_bf16_f32 %0, %1, %2" : "=v"(r) : "v"(lo), "v"(hi)); return r; }
; __device__ __forceinline__ float bflo(unsigned w) { return __uint_as_float(w << 16); }
; __device__ __forceinline__ float bfhi(unsigned w) { return __uint_as_float(w & 0xffff0000u); }
; __device__ __forceinline__ float sigmoidf_(float x) { return __builtin_amdgcn_rcpf(1.f + __expf(-x)); }
; __device__ __forceinline__ void mixB3_mfma_unit(const bf16* Z, const float* ST, bf16* Yb, LAS unsigned char* lds, int gn, int hb, float lgf, float lgb, int tid) {
;     ...
;     const float rstd = __builtin_amdgcn_rsqf(s2 * (1.f / 128.f) + GN_EPS);
;     const bf16* gp = Z + (size_t)tokc * NZ + 5632 + hb * 128 + 4 * q;
;     bf16* yp = Yb + (size_t)tokc * 512 + hb * 128 + 4 * q;
; #pragma unroll
;     for (int et = 0; et < 8; ++et) {
;         const uint2 gw = *(const uint2*)(gp + et * 16);
;         const float g0 = pg8::bflo(gw.x), g1 = pg8::bfhi(gw.x), g2 = pg8::bflo(gw.y), g3 = pg8::bfhi(gw.y);
;         uint2 wv; wv.x = pg8::cvt_pk_bf16(o[et][0] * rstd * g0 * pg8::sigmoidf_(g0), o[et][1] * rstd * g1 * pg8::sigmoidf_(g1));
;         wv.y = pg8::cvt_pk_bf16(o[et][2] * rstd * g2 * pg8::sigmoidf_(g2), o[et][3] * rstd * g3 * pg8::sigmoidf_(g3));
;         *(uint2*)(yp + et * 16) = wv;
;     }
	v_add_f32_e32 v2, v2, v4
	v_lshl_add_u64 v[4:5], v[96:97], 0, s[48:49]
	v_lshl_add_u64 v[8:9], v[4:5], 0, v[92:93]
	v_lshl_add_u64 v[4:5], v[8:9], 0, s[2:3]
	v_add_co_u32_e32 v8, vcc, s15, v8
	v_fmamk_f32 v2, v2, 0x3c000000, v233
	s_nop 0
	v_addc_co_u32_e32 v9, vcc, 0, v9, vcc
	global_load_dwordx2 v[42:43], v[8:9], off offset:3072
	v_rsq_f32_e32 v2, v2
	s_waitcnt vmcnt(0)
	v_and_b32_e32 v40, 0xffff0000, v42
	v_mul_f32_e32 v31, v31, v2
	v_lshlrev_b32_e32 v41, 16, v42
	v_mul_f32_e32 v39, v39, v2
	v_mul_f32_e32 v31, v31, v40
	v_mul_f32_e32 v40, 0xbfb8aa3b, v40
	v_mul_f32_e32 v39, v39, v41
	v_mul_f32_e32 v41, 0xbfb8aa3b, v41
	v_exp_f32_e32 v40, v40
	v_exp_f32_e32 v41, v41
	v_lshlrev_b32_e32 v9, 16, v43
	v_and_b32_e32 v8, 0xffff0000, v43
	v_add_f32_e32 v40, 1.0, v40
	v_add_f32_e32 v41, 1.0, v41
	v_rcp_f32_e32 v40, v40
	v_rcp_f32_e32 v41, v41
	v_mul_f32_e32 v36, v36, v2
	v_mul_f32_e32 v27, v27, v2
	v_mul_f32_e32 v31, v40, v31
	v_mul_f32_e32 v39, v41, v39
	v_cvt_pk_bf16_f32 v40, v39, v31
	v_mul_f32_e32 v31, v38, v2
	v_mul_f32_e32 v31, v31, v9
	v_mul_f32_e32 v9, 0xbfb8aa3b, v9
	v_exp_f32_e32 v9, v9
	v_mul_f32_e32 v33, v33, v2
	v_mul_f32_e32 v23, v23, v2
	v_mul_f32_e32 v29, v29, v2
	v_add_f32_e32 v9, 1.0, v9
	v_rcp_f32_e32 v9, v9
	v_mul_f32_e32 v19, v19, v2
	v_mul_f32_e32 v25, v25, v2
	v_mul_f32_e32 v15, v15, v2
	v_mul_f32_e32 v9, v9, v31
	v_mul_f32_e32 v31, v37, v2
	v_mul_f32_e32 v31, v31, v8
	v_mul_f32_e32 v8, 0xbfb8aa3b, v8
	v_exp_f32_e32 v8, v8
	v_mul_f32_e32 v21, v21, v2
	v_mul_f32_e32 v11, v11, v2
	v_mul_f32_e32 v17, v17, v2
	v_add_f32_e32 v8, 1.0, v8
	v_rcp_f32_e32 v8, v8
	v_mul_f32_e32 v7, v7, v2
	v_mul_f32_e32 v3, v3, v2
	v_mul_f32_e32 v1, v1, v2
	v_mul_f32_e32 v8, v8, v31
	v_cvt_pk_bf16_f32 v41, v9, v8
	global_load_dwordx2 v[8:9], v[4:5], off offset:32
	s_waitcnt vmcnt(0)
	v_lshlrev_b32_e32 v31, 16, v8
	v_and_b32_e32 v8, 0xffff0000, v8
	v_mul_f32_e32 v36, v36, v31
	v_mul_f32_e32 v31, 0xbfb8aa3b, v31
	v_mul_f32_e32 v27, v27, v8
	v_mul_f32_e32 v8, 0xbfb8aa3b, v8
	v_exp_f32_e32 v31, v31
	v_exp_f32_e32 v8, v8
	v_lshlrev_b32_e32 v37, 16, v9
	v_lshrrev_b32_e32 v218, 4, v231
	v_lshl_or_b32 v218, v231, 4, v218
	v_and_b32_e32 v218, 0x33, v218
	v_and_or_b32 v218, v231, 12, v218
	v_lshlrev_b32_e32 v218, 2, v218
	ds_bpermute_b32 v220, v218, v12
	ds_bpermute_b32 v221, v218, v13
	ds_bpermute_b32 v40, v218, v40
	ds_bpermute_b32 v41, v218, v41
	s_waitcnt lgkmcnt(0)
	global_store_dwordx2 v[220:221], v[40:41], off
	v_add_f32_e32 v31, 1.0, v31
	v_add_f32_e32 v8, 1.0, v8
	v_rcp_f32_e32 v31, v31
	v_rcp_f32_e32 v8, v8
	v_and_b32_e32 v9, 0xffff0000, v9
	v_mul_f32_e32 v31, v31, v36
	v_mul_f32_e32 v8, v8, v27
	v_cvt_pk_bf16_f32 v8, v31, v8
	v_mul_f32_e32 v31, 0xbfb8aa3b, v37
	v_exp_f32_e32 v31, v31
	v_mul_f32_e32 v27, v35, v2
	v_mul_f32_e32 v27, v27, v37
	v_add_f32_e32 v31, 1.0, v31
	v_rcp_f32_e32 v31, v31
	s_nop 0
	v_mul_f32_e32 v27, v31, v27
	v_mul_f32_e32 v31, v34, v2
	v_mul_f32_e32 v31, v31, v9
	v_mul_f32_e32 v9, 0xbfb8aa3b, v9
	v_exp_f32_e32 v9, v9
	s_nop 0
	v_add_f32_e32 v9, 1.0, v9
	v_rcp_f32_e32 v9, v9
	s_nop 0
	v_mul_f32_e32 v9, v9, v31
	v_cvt_pk_bf16_f32 v9, v27, v9
	ds_bpermute_b32 v8, v218, v8
	ds_bpermute_b32 v9, v218, v9
	s_waitcnt lgkmcnt(0)
	global_store_dwordx2 v[220:221], v[8:9], off offset:32
	global_load_dwordx2 v[8:9], v[4:5], off offset:64
	s_waitcnt vmcnt(0)
	v_lshlrev_b32_e32 v27, 16, v8
	v_and_b32_e32 v8, 0xffff0000, v8
	v_mul_f32_e32 v33, v33, v27
	v_mul_f32_e32 v27, 0xbfb8aa3b, v27
	v_mul_f32_e32 v23, v23, v8
	v_mul_f32_e32 v8, 0xbfb8aa3b, v8
	v_exp_f32_e32 v27, v27
	v_exp_f32_e32 v8, v8
	v_lshlrev_b32_e32 v31, 16, v9
	v_and_b32_e32 v9, 0xffff0000, v9
	v_add_f32_e32 v27, 1.0, v27
	v_add_f32_e32 v8, 1.0, v8
	v_rcp_f32_e32 v27, v27
	v_rcp_f32_e32 v8, v8
	v_mul_f32_e32 v27, v27, v33
	v_mul_f32_e32 v8, v8, v23
	v_cvt_pk_bf16_f32 v8, v27, v8
	v_mul_f32_e32 v27, 0xbfb8aa3b, v31
	v_exp_f32_e32 v27, v27
	v_mul_f32_e32 v23, v32, v2
	v_mul_f32_e32 v23, v23, v31
	v_add_f32_e32 v27, 1.0, v27
	v_rcp_f32_e32 v27, v27
	s_nop 0
	v_mul_f32_e32 v23, v27, v23
	v_mul_f32_e32 v27, v30, v2
	v_mul_f32_e32 v27, v27, v9
	v_mul_f32_e32 v9, 0xbfb8aa3b, v9
	v_exp_f32_e32 v9, v9
	s_nop 0
	v_add_f32_e32 v9, 1.0, v9
	v_rcp_f32_e32 v9, v9
	s_nop 0
	v_mul_f32_e32 v9, v9, v27
	v_cvt_pk_bf16_f32 v9, v23, v9
	ds_bpermute_b32 v8, v218, v8
	ds_bpermute_b32 v9, v218, v9
	s_waitcnt lgkmcnt(0)
	global_store_dwordx2 v[220:221], v[8:9], off offset:64
	global_load_dwordx2 v[8:9], v[4:5], off offset:96
	s_waitcnt vmcnt(0)
	v_lshlrev_b32_e32 v23, 16, v8
	v_and_b32_e32 v8, 0xffff0000, v8
	v_mul_f32_e32 v29, v29, v23
	v_mul_f32_e32 v23, 0xbfb8aa3b, v23
	v_mul_f32_e32 v19, v19, v8
	v_mul_f32_e32 v8, 0xbfb8aa3b, v8
	v_exp_f32_e32 v23, v23
	v_exp_f32_e32 v8, v8
	v_lshlrev_b32_e32 v27, 16, v9
	v_and_b32_e32 v9, 0xffff0000, v9
	v_add_f32_e32 v23, 1.0, v23
	v_add_f32_e32 v8, 1.0, v8
	v_rcp_f32_e32 v23, v23
	v_rcp_f32_e32 v8, v8
	v_mul_f32_e32 v23, v29, v23
	v_mul_f32_e32 v8, v19, v8
	v_cvt_pk_bf16_f32 v8, v23, v8
	v_mul_f32_e32 v23, 0xbfb8aa3b, v27
	v_exp_f32_e32 v23, v23
	v_mul_f32_e32 v19, v28, v2
	v_mul_f32_e32 v19, v19, v27
	v_add_f32_e32 v23, 1.0, v23
	v_rcp_f32_e32 v23, v23
	s_nop 0
	v_mul_f32_e32 v19, v19, v23
	v_mul_f32_e32 v23, v26, v2
	v_mul_f32_e32 v23, v23, v9
	v_mul_f32_e32 v9, 0xbfb8aa3b, v9
	v_exp_f32_e32 v9, v9
	s_nop 0
	v_add_f32_e32 v9, 1.0, v9
	v_rcp_f32_e32 v9, v9
	s_nop 0
	v_mul_f32_e32 v9, v23, v9
	v_cvt_pk_bf16_f32 v9, v19, v9
	ds_bpermute_b32 v8, v218, v8
	ds_bpermute_b32 v9, v218, v9
	s_waitcnt lgkmcnt(0)
; __device__ __forceinline__ unsigned cvt_pk_bf16(float lo, float hi) { unsigned r; asm volatile("v_cvt_pk_bf16_f32 %0, %1, %2" : "=v"(r) : "v"(lo), "v"(hi)); return r; }
; __device__ __forceinline__ float bflo(unsigned w) { return __uint_as_float(w << 16); }
; __device__ __forceinline__ float bfhi(unsigned w) { return __uint_as_float(w & 0xffff0000u); }
; __device__ __forceinline__ float sigmoidf_(float x) { return __builtin_amdgcn_rcpf(1.f + __expf(-x)); }
; __device__ __forceinline__ void mixB3_mfma_unit(const bf16* Z, const float* ST, bf16* Yb, LAS unsigned char* lds, int gn, int hb, float lgf, float lgb, int tid) {
;     ...
; #pragma unroll
;     for (int et = 0; et < 8; ++et) {
;         const uint2 gw = *(const uint2*)(gp + et * 16);
;         const float g0 = pg8::bflo(gw.x), g1 = pg8::bfhi(gw.x), g2 = pg8::bflo(gw.y), g3 = pg8::bfhi(gw.y);
;         uint2 wv; wv.x = pg8::cvt_pk_bf16(o[et][0] * rstd * g0 * pg8::sigmoidf_(g0), o[et][1] * rstd * g1 * pg8::sigmoidf_(g1));
;         wv.y = pg8::cvt_pk_bf16(o[et][2] * rstd * g2 * pg8::sigmoidf_(g2), o[et][3] * rstd * g3 * pg8::sigmoidf_(g3));
;         *(uint2*)(yp + et * 16) = wv;
;     }
; __global__ void __launch_bounds__(NTHR, 2) fwd_megakernel(Params p) {
;     ...
;                         for (int it = bx; it < 128 * 4; it += G) { const int gn = it >> 2, hb = it & 3; int t2 = tid; asm volatile("" : "+v"(t2));
	global_store_dwordx2 v[220:221], v[8:9], off offset:96
	global_load_dwordx2 v[8:9], v[4:5], off offset:128
	s_waitcnt vmcnt(0)
	v_lshlrev_b32_e32 v19, 16, v8
	v_and_b32_e32 v8, 0xffff0000, v8
	v_mul_f32_e32 v25, v25, v19
	v_mul_f32_e32 v19, 0xbfb8aa3b, v19
	v_mul_f32_e32 v15, v15, v8
	v_mul_f32_e32 v8, 0xbfb8aa3b, v8
	v_exp_f32_e32 v19, v19
	v_exp_f32_e32 v8, v8
	v_lshlrev_b32_e32 v23, 16, v9
	v_and_b32_e32 v9, 0xffff0000, v9
	v_add_f32_e32 v19, 1.0, v19
	v_add_f32_e32 v8, 1.0, v8
	v_rcp_f32_e32 v19, v19
	v_rcp_f32_e32 v8, v8
	v_mul_f32_e32 v19, v25, v19
	v_mul_f32_e32 v8, v15, v8
	v_cvt_pk_bf16_f32 v8, v19, v8
	v_mul_f32_e32 v19, 0xbfb8aa3b, v23
	v_exp_f32_e32 v19, v19
	v_mul_f32_e32 v15, v24, v2
	v_mul_f32_e32 v15, v15, v23
	v_add_f32_e32 v19, 1.0, v19
	v_rcp_f32_e32 v19, v19
	s_nop 0
	v_mul_f32_e32 v15, v15, v19
	v_mul_f32_e32 v19, v22, v2
	v_mul_f32_e32 v19, v19, v9
	v_mul_f32_e32 v9, 0xbfb8aa3b, v9
	v_exp_f32_e32 v9, v9
	s_nop 0
	v_add_f32_e32 v9, 1.0, v9
	v_rcp_f32_e32 v9, v9
	s_nop 0
	v_mul_f32_e32 v9, v19, v9
	v_cvt_pk_bf16_f32 v9, v15, v9
	ds_bpermute_b32 v8, v218, v8
	ds_bpermute_b32 v9, v218, v9
	s_waitcnt lgkmcnt(0)
	global_store_dwordx2 v[220:221], v[8:9], off offset:128
	global_load_dwordx2 v[8:9], v[4:5], off offset:160
	s_waitcnt vmcnt(0)
	v_lshlrev_b32_e32 v15, 16, v8
	v_and_b32_e32 v8, 0xffff0000, v8
	v_mul_f32_e32 v21, v21, v15
	v_mul_f32_e32 v15, 0xbfb8aa3b, v15
	v_mul_f32_e32 v11, v11, v8
	v_mul_f32_e32 v8, 0xbfb8aa3b, v8
	v_exp_f32_e32 v15, v15
	v_exp_f32_e32 v8, v8
	v_lshlrev_b32_e32 v19, 16, v9
	v_and_b32_e32 v9, 0xffff0000, v9
	v_add_f32_e32 v15, 1.0, v15
	v_add_f32_e32 v8, 1.0, v8
	v_rcp_f32_e32 v15, v15
	v_rcp_f32_e32 v8, v8
	v_mul_f32_e32 v15, v21, v15
	v_mul_f32_e32 v8, v11, v8
	v_cvt_pk_bf16_f32 v8, v15, v8
	v_mul_f32_e32 v15, 0xbfb8aa3b, v19
	v_exp_f32_e32 v15, v15
	v_mul_f32_e32 v11, v20, v2
	v_mul_f32_e32 v11, v11, v19
	v_add_f32_e32 v15, 1.0, v15
	v_rcp_f32_e32 v15, v15
	s_nop 0
	v_mul_f32_e32 v11, v11, v15
	v_mul_f32_e32 v15, v18, v2
	v_mul_f32_e32 v15, v15, v9
	v_mul_f32_e32 v9, 0xbfb8aa3b, v9
	v_exp_f32_e32 v9, v9
	s_nop 0
	v_add_f32_e32 v9, 1.0, v9
	v_rcp_f32_e32 v9, v9
	s_nop 0
	v_mul_f32_e32 v9, v15, v9
	v_cvt_pk_bf16_f32 v9, v11, v9
	ds_bpermute_b32 v8, v218, v8
	ds_bpermute_b32 v9, v218, v9
	s_waitcnt lgkmcnt(0)
	global_store_dwordx2 v[220:221], v[8:9], off offset:160
	global_load_dwordx2 v[8:9], v[4:5], off offset:192
	s_waitcnt vmcnt(0)
	v_lshlrev_b32_e32 v11, 16, v8
	v_and_b32_e32 v8, 0xffff0000, v8
	v_mul_f32_e32 v17, v17, v11
	v_mul_f32_e32 v11, 0xbfb8aa3b, v11
	v_exp_f32_e32 v11, v11
	v_mul_f32_e32 v7, v7, v8
	v_mul_f32_e32 v8, 0xbfb8aa3b, v8
	v_exp_f32_e32 v8, v8
	v_add_f32_e32 v11, 1.0, v11
	v_rcp_f32_e32 v11, v11
	v_lshlrev_b32_e32 v15, 16, v9
	v_add_f32_e32 v8, 1.0, v8
	v_rcp_f32_e32 v8, v8
	v_mul_f32_e32 v11, v17, v11
	v_and_b32_e32 v9, 0xffff0000, v9
	v_mul_f32_e32 v7, v7, v8
	v_cvt_pk_bf16_f32 v8, v11, v7
	v_mul_f32_e32 v11, 0xbfb8aa3b, v15
	v_exp_f32_e32 v11, v11
	v_mul_f32_e32 v7, v16, v2
	v_mul_f32_e32 v7, v7, v15
	v_add_f32_e32 v11, 1.0, v11
	v_rcp_f32_e32 v11, v11
	s_nop 0
	v_mul_f32_e32 v7, v7, v11
	v_mul_f32_e32 v11, v14, v2
	v_mul_f32_e32 v11, v11, v9
	v_mul_f32_e32 v9, 0xbfb8aa3b, v9
	v_exp_f32_e32 v9, v9
	s_nop 0
	v_add_f32_e32 v9, 1.0, v9
	v_rcp_f32_e32 v9, v9
	s_nop 0
	v_mul_f32_e32 v9, v11, v9
	v_cvt_pk_bf16_f32 v9, v7, v9
	global_load_dwordx2 v[4:5], v[4:5], off offset:224
	s_waitcnt vmcnt(0)
	v_lshlrev_b32_e32 v7, 16, v4
	v_and_b32_e32 v4, 0xffff0000, v4
	ds_bpermute_b32 v8, v218, v8
	ds_bpermute_b32 v9, v218, v9
	s_waitcnt lgkmcnt(0)
	global_store_dwordx2 v[220:221], v[8:9], off offset:192
	v_mul_f32_e32 v9, v10, v2
	v_mul_f32_e32 v3, v3, v4
	v_mul_f32_e32 v4, 0xbfb8aa3b, v4
	v_mul_f32_e32 v9, v9, v7
	v_mul_f32_e32 v7, 0xbfb8aa3b, v7
	v_exp_f32_e32 v4, v4
	v_exp_f32_e32 v7, v7
	v_lshlrev_b32_e32 v8, 16, v5
	v_and_b32_e32 v5, 0xffff0000, v5
	v_add_f32_e32 v4, 1.0, v4
	v_add_f32_e32 v7, 1.0, v7
	v_rcp_f32_e32 v4, v4
	v_rcp_f32_e32 v7, v7
	v_mul_f32_e32 v1, v1, v5
	v_mul_f32_e32 v3, v3, v4
	v_mul_f32_e32 v7, v9, v7
	v_cvt_pk_bf16_f32 v4, v7, v3
	v_mul_f32_e32 v3, v6, v2
	v_mul_f32_e32 v6, 0xbfb8aa3b, v8
	v_mul_f32_e32 v2, 0xbfb8aa3b, v5
	v_exp_f32_e32 v6, v6
	v_exp_f32_e32 v2, v2
	v_mul_f32_e32 v3, v3, v8
	v_add_f32_e32 v6, 1.0, v6
	v_add_f32_e32 v2, 1.0, v2
	v_rcp_f32_e32 v6, v6
	v_rcp_f32_e32 v2, v2
	v_mul_f32_e32 v3, v3, v6
	v_mul_f32_e32 v1, v1, v2
	v_cvt_pk_bf16_f32 v5, v3, v1
	ds_bpermute_b32 v4, v218, v4
	ds_bpermute_b32 v5, v218, v5
	s_waitcnt lgkmcnt(0)
	global_store_dwordx2 v[220:221], v[4:5], off offset:224
	s_cbranch_scc0 .LBB0_154

; #define LAS __attribute__((address_space(3)))
; __device__ __forceinline__ void mixA_compute(bf16* Z, float* LSE, LAS unsigned char* lds, int u, int S, int tid) {
;     const int g = u >> 9, h = u & 7, tt = (u >> 3) & 63;
;     const int dil = 1 << (2 * g), Lg = S / dil, tps = S >> 8, tpr = Lg >> 8;
;     const int sq = tt / tps, x = tt - sq * tps, r = x / tpr, i0 = (x - r * tpr) << 8;
;     const int seq0 = sq * S;
;     const int lane = tid & 63, w = tid >> 6, n = lane & 15, q = lane >> 4;
; #pragma unroll
;     for (int qt = 0; qt < 2; ++qt) {
;     const int wt = 2 * w + qt;
;     const int iq = i0 + 16 * wt + n, tokc = seq0 + iq * dil + r;
;     bf16* qp = Z + (size_t)tokc * NZ + g * 512 + h * 64;
;     const bf16x8_t qf0 = *(const bf16x8_t*)(qp + 8 * q), qf1 = *(const bf16x8_t*)(qp + 32 + 8 * q);
;     f32x4 s[10];
; #pragma unroll
;     for (int t = 0; t < 9; ++t) {
;         LAS unsigned char* kp = lds + (16 * wt + 16 * t + n) * KPITCH + q * 16;
;         const bf16x8_t kf0 = *(LAS bf16x8_t*)kp, kf1 = *(LAS bf16x8_t*)(kp + 64);
;         f32x4 a = {0.f, 0.f, 0.f, 0.f};
;         a = __builtin_amdgcn_mfma_f32_16x16x32_bf16(kf0, qf0, a, 0, 0, 0);
;         s[t] = __builtin_amdgcn_mfma_f32_16x16x32_bf16(kf1, qf1, a, 0, 0, 0);
;     }
;     s[9] = (f32x4){0.f, 0.f, 0.f, 0.f};
;     const float slope = exp2f(-(float)(h + 1)) * (float)dil;
;     float m = -1e30f;
; #pragma unroll
;     for (int t = 0; t < 9; ++t)
; #pragma unroll
;         for (int j = 0; j < 4; ++j) {
;             const int rel = 16 * t + 4 * q + j - 64 - n, idxk = i0 - 64 + 16 * wt + 16 * t + 4 * q + j;
;             const bool valid = (rel >= -64) && (rel <= 64) && (idxk >= 0) && (idxk < Lg);
;             const float sc = s[t][j] * 0.125f - slope * (float)(rel < 0 ? -rel : rel);
;             s[t][j] = valid ? sc : -1e30f; m = fmaxf(m, s[t][j]);
.LBB0_256:
	s_add_i32 s17, s15, 0xfffffe00
	s_ashr_i32 s16, s17, 9
	s_lshl_b32 s22, s16, 1
	v_readlane_b32 s38, v255, 9
	s_lshr_b32 s3, s38, s22
	s_lshr_b32 s4, s3, 8
	v_cvt_f32_i32_e32 v1, s4
	s_and_b32 s25, s15, 7
	s_bfe_u32 s15, s15, 0x60003
	s_sub_i32 s24, s15, s89
	v_rcp_iflag_f32_e32 v2, v1
	s_min_u32 s24, s15, s24
	v_cvt_f32_ubyte0_e32 v3, s24
	s_lshl_b32 s31, 1, s22
	v_mul_f32_e32 v2, v3, v2
	v_trunc_f32_e32 v2, v2
	v_cvt_i32_f32_e32 v56, v2
	v_fma_f32 v2, -v2, v1, v3
	v_cmp_ge_f32_e64 s[34:35], |v2|, v1
	s_cmp_lg_u64 s[34:35], 0
	v_readfirstlane_b32 s33, v56
	s_addc_u32 s33, s33, 0
	s_sext_i32_i8 s33, s33
	s_mul_i32 s4, s4, s33
	s_sub_i32 s4, s24, s4
	s_lshl_b32 s4, s4, 8
	s_cmp_ge_u32 s15, s89
	s_cselect_b32 s15, s38, 0
	s_and_b32 s34, s17, 0xfffffe00
	s_ashr_i32 s35, s34, 31
	s_add_i32 s15, s15, s33
	s_lshl_b64 s[34:35], s[34:35], 1
	s_add_u32 s17, s12, s34
	v_and_b32_e32 v163, 15, v85
	s_addc_u32 s24, s13, s35
	s_lshl_b32 s33, s25, 7
	v_ashrrev_i32_e32 v1, 1, v85
	v_or_b32_e32 v164, s4, v163
	s_add_u32 s68, s17, s33
	v_and_b32_e32 v166, 0xffffffe0, v1
	s_addc_u32 s69, s24, 0
	v_add_lshl_u32 v3, v164, v166, s22
	v_bfe_u32 v87, v85, 4, 2
	v_add_u32_e32 v86, s15, v3
	v_mov_b64_e32 v[56:57], s[68:69]
	v_lshlrev_b32_e32 v2, 4, v87
	v_mad_i64_i32 v[88:89], s[34:35], v86, s66, v[56:57]
	v_mov_b32_e32 v3, v0
	v_lshl_add_u64 v[68:69], v[88:89], 0, v[2:3]
	v_add_u32_e32 v84, 0, v2
	v_or_b32_e32 v2, v166, v163
	v_mad_u64_u32 v[2:3], s[34:35], v2, s67, v[84:85]
	ds_read_b128 v[60:63], v2
	ds_read_b128 v[64:67], v2 offset:64
	v_and_b32_e32 v165, -16, v1
	v_or3_b32 v1, v165, v163, 16
	v_mad_u64_u32 v[72:73], s[34:35], v1, s67, v[84:85]
	ds_read_b128 v[68:71], v72
	ds_read_b128 v[72:75], v72 offset:64
	ds_read_b128 v[76:79], v2 offset:4608
	ds_read_b128 v[80:83], v2 offset:4672
	ds_read_b128 v[96:99], v2 offset:6912
	ds_read_b128 v[100:103], v2 offset:6976
	ds_read_b128 v[104:107], v2 offset:9216
	ds_read_b128 v[108:111], v2 offset:9280
	ds_read_b128 v[112:115], v2 offset:11520
	ds_read_b128 v[116:119], v2 offset:11584
	ds_read_b128 v[120:123], v2 offset:13824
	ds_read_b128 v[124:127], v2 offset:13888
	ds_read_b128 v[128:131], v2 offset:16128
	ds_read_b128 v[132:135], v2 offset:16192
	ds_read_b128 v[136:139], v2 offset:18432
	ds_read_b128 v[140:143], v2 offset:18496
	v_and_b32_e32 v3, 64, v231
	v_xor_b32_e32 v2, 16, v231
	v_add_u32_e32 v168, 64, v3
	s_add_i32 s17, s25, 1
	v_cmp_lt_i32_e32 vcc, v2, v168
	v_cvt_f32_ubyte0_e32 v3, s17
	s_mov_b32 s17, 0x42fc0000
	v_cndmask_b32_e32 v2, v231, v2, vcc
	v_cmp_lt_f32_e32 vcc, s17, v3
	v_lshlrev_b32_e32 v162, 2, v2
	v_cvt_f32_u32_e32 v2, s31
	s_and_b64 s[34:35], vcc, exec
	s_cselect_b32 s31, 0xffffffc0, 0
	v_lshlrev_b32_e32 v1, 2, v87
	s_ashr_i32 s17, s16, 31
	s_sub_i32 s24, s4, 64
	s_lshl_b64 s[16:17], s[16:17], 19
	v_readlane_b32 s34, v254, 22
	v_readlane_b32 s35, v254, 23
	s_add_u32 s16, s34, s16
	s_addc_u32 s17, s35, s17
	s_lshl_b32 s25, s25, 2
	s_add_u32 s64, s16, s25
	s_addc_u32 s65, s17, 0
	s_movk_i32 s25, 0x7f
	s_movk_i32 s33, 0x7e
	s_waitcnt lgkmcnt(14)
	v_mfma_f32_16x16x32_bf16 v[60:63], v[60:63], v[180:183], 0
	v_mfma_f32_16x16x32_bf16 v[68:71], v[68:71], v[180:183], 0
	s_waitcnt lgkmcnt(13)
	v_mfma_f32_16x16x32_bf16 v[76:79], v[76:79], v[180:183], 0
	s_waitcnt lgkmcnt(11)
	v_mfma_f32_16x16x32_bf16 v[96:99], v[96:99], v[180:183], 0
	s_waitcnt lgkmcnt(9)
	v_mfma_f32_16x16x32_bf16 v[104:107], v[104:107], v[180:183], 0
	s_waitcnt lgkmcnt(7)
	v_mfma_f32_16x16x32_bf16 v[112:115], v[112:115], v[180:183], 0
	s_waitcnt lgkmcnt(5)
	v_mfma_f32_16x16x32_bf16 v[120:123], v[120:123], v[180:183], 0
	s_waitcnt lgkmcnt(3)
	v_mfma_f32_16x16x32_bf16 v[128:131], v[128:131], v[180:183], 0
	s_waitcnt lgkmcnt(1)
	v_mfma_f32_16x16x32_bf16 v[56:59], v[136:139], v[180:183], 0
	v_mfma_f32_16x16x32_bf16 v[136:139], v[64:67], v[184:187], v[60:63]
	s_nop 2
	v_cndmask_b32_e32 v60, 0, v245, vcc
	v_sub_f32_e32 v3, v60, v3
	v_exp_f32_e32 v3, v3
	s_waitcnt lgkmcnt(0)
	v_mfma_f32_16x16x32_bf16 v[56:59], v[140:143], v[184:187], v[56:59]
	v_add_u32_e32 v142, s24, v166
	v_cmp_lt_i32_e32 vcc, -1, v142
	v_ldexp_f32 v3, v3, s31
	v_mul_f32_e32 v151, v3, v2
	v_sub_u32_e32 v2, v1, v163
	v_sub_u32_e32 v3, 64, v2
	v_cvt_f32_u32_e32 v201, v3
	s_movk_i32 s31, 0x81
	v_or_b32_e32 v169, v142, v1
	v_cmp_gt_u32_e64 s[52:53], s31, v2
	v_mov_b32_e32 v150, v136
	s_and_b64 s[16:17], s[52:53], vcc
	v_cmp_gt_i32_e64 s[40:41], s3, v169
	v_pk_mul_f32 v[154:155], v[150:151], v[200:201]
	s_and_b64 s[40:41], s[16:17], s[40:41]
	v_sub_f32_e32 v3, v154, v155
	v_cndmask_b32_e64 v154, v241, v3, s[40:41]
	v_add_u32_e32 v3, 1, v2
	v_cmp_gt_u32_e64 s[54:55], s31, v3
	v_sub_u32_e32 v3, 63, v2
	v_cvt_f32_u32_e32 v201, v3
	v_mfma_f32_16x16x32_bf16 v[144:147], v[72:75], v[184:187], v[68:71]
	v_mov_b32_e32 v150, v137
	v_or_b32_e32 v3, 1, v169
	v_pk_mul_f32 v[156:157], v[150:151], v[200:201]
	v_mfma_f32_16x16x32_bf16 v[80:83], v[80:83], v[184:187], v[76:79]
	s_and_b64 s[16:17], s[54:55], vcc
	v_cmp_gt_i32_e64 s[40:41], s3, v3
	v_sub_f32_e32 v3, v156, v157
	v_mfma_f32_16x16x32_bf16 v[76:79], v[100:103], v[184:187], v[96:99]
	s_and_b64 s[40:41], s[16:17], s[40:41]
	v_mov_b32_e32 v150, v138
	v_cndmask_b32_e64 v156, v241, v3, s[40:41]
	v_mfma_f32_16x16x32_bf16 v[72:75], v[108:111], v[184:187], v[104:107]
	v_max3_f32 v3, v154, s84, v156
	v_mfma_f32_16x16x32_bf16 v[68:71], v[116:119], v[184:187], v[112:115]
	v_mfma_f32_16x16x32_bf16 v[64:67], v[124:127], v[184:187], v[120:123]
	v_mfma_f32_16x16x32_bf16 v[60:63], v[132:135], v[184:187], v[128:131]
	v_add_u32_e32 v92, 2, v2
	v_cmp_gt_u32_e64 s[56:57], s31, v92
	v_sub_u32_e32 v92, 62, v2
	v_cvt_f32_u32_e32 v201, v92
; __device__ __forceinline__ void mixA_compute(bf16* Z, float* LSE, LAS unsigned char* lds, int u, int S, int tid) {
;     ...
;     for (int t = 0; t < 9; ++t)
; #pragma unroll
;         for (int j = 0; j < 4; ++j) {
;             const int rel = 16 * t + 4 * q + j - 64 - n, idxk = i0 - 64 + 16 * wt + 16 * t + 4 * q + j;
;             const bool valid = (rel >= -64) && (rel <= 64) && (idxk >= 0) && (idxk < Lg);
;             const float sc = s[t][j] * 0.125f - slope * (float)(rel < 0 ? -rel : rel);
;             s[t][j] = valid ? sc : -1e30f; m = fmaxf(m, s[t][j]);
;         }
	v_or_b32_e32 v92, 2, v169
	s_and_b64 s[16:17], s[56:57], vcc
	v_cmp_gt_i32_e64 s[40:41], s3, v92
	v_pk_mul_f32 v[158:159], v[150:151], v[200:201]
	s_and_b64 s[40:41], s[16:17], s[40:41]
	v_sub_f32_e32 v92, v158, v159
	v_cndmask_b32_e64 v158, v241, v92, s[40:41]
	v_add_u32_e32 v92, 3, v2
	v_sub_u32_e32 v2, 61, v2
	v_cvt_f32_u32_e32 v201, v2
	v_cmp_gt_u32_e64 s[58:59], s31, v92
	v_or_b32_e32 v2, 3, v169
	v_mov_b32_e32 v150, v139
	s_and_b64 s[16:17], s[58:59], vcc
	v_cmp_gt_i32_e64 s[40:41], s3, v2
	v_pk_mul_f32 v[160:161], v[150:151], v[200:201]
	s_and_b64 s[40:41], s[16:17], s[40:41]
	v_sub_f32_e32 v2, v160, v161
	v_cndmask_b32_e64 v160, v241, v2, s[40:41]
	v_max3_f32 v2, v3, v158, v160
	v_or_b32_e32 v3, 16, v1
	v_sub_u32_e32 v3, v3, v163
	v_sub_u32_e32 v92, 64, v3
	v_or_b32_e32 v93, 16, v169
	v_cvt_f32_ubyte0_e32 v201, v92
	v_mov_b32_e32 v150, v144
	v_cmp_gt_i32_e64 s[40:41], s3, v93
	v_pk_mul_f32 v[152:153], v[150:151], v[200:201]
	s_and_b64 s[40:41], vcc, s[40:41]
	v_sub_f32_e32 v92, v152, v153
	v_cndmask_b32_e64 v152, v241, v92, s[40:41]
	v_or_b32_e32 v92, 17, v169
	v_cmp_gt_i32_e64 s[40:41], s3, v92
	v_xor_b32_e32 v92, 63, v3
	v_cvt_f32_ubyte0_e32 v201, v92
	v_mov_b32_e32 v150, v145
	v_pk_mul_f32 v[148:149], v[150:151], v[200:201]
	s_and_b64 s[40:41], vcc, s[40:41]
	v_sub_f32_e32 v92, v148, v149
	v_cndmask_b32_e64 v148, v241, v92, s[40:41]
	v_max3_f32 v92, v2, v152, v148
	v_or_b32_e32 v2, 18, v169
	v_cmp_gt_i32_e64 s[40:41], s3, v2
	v_sub_u32_e32 v2, 62, v3
	v_cvt_f32_ubyte0_e32 v201, v2
	v_mov_b32_e32 v150, v146
	v_pk_mul_f32 v[114:115], v[150:151], v[200:201]
	s_and_b64 s[40:41], vcc, s[40:41]
	v_sub_f32_e32 v2, v114, v115
	v_cndmask_b32_e64 v114, v241, v2, s[40:41]
	v_or_b32_e32 v2, 19, v169
	v_cmp_gt_i32_e64 s[40:41], s3, v2
	v_sub_u32_e32 v2, 61, v3
	v_cvt_f32_ubyte0_e32 v201, v2
	v_mov_b32_e32 v150, v147
	v_pk_mul_f32 v[2:3], v[150:151], v[200:201]
	s_and_b64 vcc, vcc, s[40:41]
	v_sub_f32_e32 v2, v2, v3
	v_cndmask_b32_e32 v2, v241, v2, vcc
	v_max3_f32 v96, v92, v114, v2
	v_or_b32_e32 v92, 32, v1
	v_sub_u32_e32 v98, v92, v163
	v_sub_u32_e32 v92, 64, v98
	s_movk_i32 s16, 0xffdf
	v_add_u32_e32 v93, 32, v169
	v_cvt_f32_ubyte0_e32 v201, v92
	v_mov_b32_e32 v150, v80
	v_cmp_lt_i32_e32 vcc, s16, v142
	v_cmp_gt_i32_e64 s[40:41], s3, v93
	v_pk_mul_f32 v[92:93], v[150:151], v[200:201]
	s_and_b64 s[40:41], vcc, s[40:41]
	v_sub_f32_e32 v80, v92, v93
	v_add_u32_e32 v92, 33, v169
	v_cndmask_b32_e64 v80, v241, v80, s[40:41]
	v_cmp_gt_i32_e64 s[40:41], s3, v92
	v_xor_b32_e32 v92, 63, v98
	v_cvt_f32_ubyte0_e32 v201, v92
	v_mov_b32_e32 v150, v81
	v_pk_mul_f32 v[94:95], v[150:151], v[200:201]
	s_and_b64 s[40:41], vcc, s[40:41]
	v_sub_f32_e32 v81, v94, v95
	v_add_u32_e32 v94, 34, v169
	v_cndmask_b32_e64 v81, v241, v81, s[40:41]
	v_cmp_gt_i32_e64 s[40:41], s3, v94
	v_sub_u32_e32 v94, 62, v98
	v_cvt_f32_ubyte0_e32 v201, v94
	v_mov_b32_e32 v150, v82
	v_max3_f32 v92, v96, v80, v81
	v_pk_mul_f32 v[96:97], v[150:151], v[200:201]
	s_and_b64 s[40:41], vcc, s[40:41]
	v_sub_f32_e32 v82, v96, v97
	v_add_u32_e32 v94, 35, v169
	v_cndmask_b32_e64 v82, v241, v82, s[40:41]
	v_cmp_gt_i32_e64 s[40:41], s3, v94
	v_sub_u32_e32 v94, 61, v98
	v_cvt_f32_ubyte0_e32 v201, v94
	v_or_b32_e32 v94, 48, v1
	v_mov_b32_e32 v150, v83
	v_sub_u32_e32 v94, v94, v163
	v_pk_mul_f32 v[98:99], v[150:151], v[200:201]
	v_sub_u32_e32 v96, 64, v94
	v_sub_f32_e32 v83, v98, v99
	s_and_b64 vcc, vcc, s[40:41]
	s_movk_i32 s16, 0xffcf
	v_add_u32_e32 v98, 48, v169
	v_cvt_f32_ubyte0_e32 v201, v96
	v_mov_b32_e32 v150, v76
	v_xor_b32_e32 v96, 63, v94
	v_cndmask_b32_e32 v83, v241, v83, vcc
	v_cmp_lt_i32_e32 vcc, s16, v142
	v_cmp_gt_i32_e64 s[40:41], s3, v98
	v_pk_mul_f32 v[100:101], v[150:151], v[200:201]
	v_cvt_f32_u32_e32 v201, v96
	v_sub_f32_e32 v76, v100, v101
	s_and_b64 s[40:41], vcc, s[40:41]
	v_add_u32_e32 v96, 49, v169
	v_cndmask_b32_e64 v76, v241, v76, s[40:41]
	v_cmp_gt_i32_e64 s[40:41], s3, v96
	v_subrev_u32_e32 v96, 62, v94
	v_sub_u32_e32 v98, 62, v94
	v_mov_b32_e32 v150, v77
	v_max_i32_e32 v96, v96, v98
	v_pk_mul_f32 v[102:103], v[150:151], v[200:201]
	v_cvt_f32_u32_e32 v201, v96
	v_sub_f32_e32 v77, v102, v103
	s_and_b64 s[40:41], vcc, s[40:41]
	v_add_u32_e32 v96, 50, v169
	v_cndmask_b32_e64 v77, v241, v77, s[40:41]
	v_cmp_gt_i32_e64 s[40:41], s3, v96
	v_mov_b32_e32 v150, v78
	v_subrev_u32_e32 v96, 61, v94
	v_sub_u32_e32 v94, 61, v94
	v_pk_mul_f32 v[104:105], v[150:151], v[200:201]
	v_max_i32_e32 v94, v96, v94
	v_sub_f32_e32 v78, v104, v105
	s_and_b64 s[40:41], vcc, s[40:41]
	v_cvt_f32_u32_e32 v201, v94
	v_add_u32_e32 v94, 51, v169
	v_cndmask_b32_e64 v78, v241, v78, s[40:41]
	v_cmp_gt_i32_e64 s[40:41], s3, v94
	v_or_b32_e32 v94, 64, v1
	v_sub_u32_e32 v94, v94, v163
	v_subrev_u32_e32 v96, 64, v94
	v_sub_u32_e32 v100, 64, v94
	v_mov_b32_e32 v150, v79
	v_max_i32_e32 v96, v96, v100
	v_pk_mul_f32 v[106:107], v[150:151], v[200:201]
	v_cvt_f32_u32_e32 v201, v96
	v_sub_f32_e32 v79, v106, v107
	s_and_b64 vcc, vcc, s[40:41]
	v_add_u32_e32 v98, s4, v166
	v_cndmask_b32_e32 v79, v241, v79, vcc
	v_cmp_lt_i32_e32 vcc, -1, v98
	v_or_b32_e32 v96, v98, v1
	v_subrev_u32_e32 v98, 63, v94
	v_sub_u32_e32 v100, 63, v94
	v_mov_b32_e32 v150, v72
	v_max_i32_e32 v98, v98, v100
	v_cmp_gt_i32_e64 s[40:41], s3, v96
	v_pk_mul_f32 v[108:109], v[150:151], v[200:201]
	v_cvt_f32_u32_e32 v201, v98
	v_sub_f32_e32 v72, v108, v109
	s_and_b64 s[40:41], vcc, s[40:41]
	v_or_b32_e32 v98, 1, v96
	v_cndmask_b32_e64 v72, v241, v72, s[40:41]
	v_cmp_gt_i32_e64 s[40:41], s3, v98
	v_subrev_u32_e32 v98, 62, v94
	v_sub_u32_e32 v100, 62, v94
	v_mov_b32_e32 v150, v73
	v_max_i32_e32 v98, v98, v100
	v_pk_mul_f32 v[110:111], v[150:151], v[200:201]
; __device__ __forceinline__ void mixA_compute(bf16* Z, float* LSE, LAS unsigned char* lds, int u, int S, int tid) {
;     ...
;     for (int t = 0; t < 9; ++t)
; #pragma unroll
;         for (int j = 0; j < 4; ++j) {
;             const int rel = 16 * t + 4 * q + j - 64 - n, idxk = i0 - 64 + 16 * wt + 16 * t + 4 * q + j;
;             const bool valid = (rel >= -64) && (rel <= 64) && (idxk >= 0) && (idxk < Lg);
;             const float sc = s[t][j] * 0.125f - slope * (float)(rel < 0 ? -rel : rel);
;             s[t][j] = valid ? sc : -1e30f; m = fmaxf(m, s[t][j]);
;         }
;     m = fmaxf(m, __shfl_xor(m, 16)); m = fmaxf(m, __shfl_xor(m, 32));
	v_cvt_f32_u32_e32 v201, v98
	v_sub_f32_e32 v73, v110, v111
	s_and_b64 s[40:41], vcc, s[40:41]
	v_or_b32_e32 v98, 2, v96
	v_cndmask_b32_e64 v73, v241, v73, s[40:41]
	v_cmp_gt_i32_e64 s[40:41], s3, v98
	v_subrev_u32_e32 v98, 61, v94
	v_sub_u32_e32 v94, 61, v94
	v_mov_b32_e32 v150, v74
	v_max_i32_e32 v94, v98, v94
	v_pk_mul_f32 v[112:113], v[150:151], v[200:201]
	v_cvt_f32_u32_e32 v201, v94
	v_sub_f32_e32 v74, v112, v113
	s_and_b64 s[40:41], vcc, s[40:41]
	v_or_b32_e32 v94, 3, v96
	v_cndmask_b32_e64 v74, v241, v74, s[40:41]
	v_cmp_gt_i32_e64 s[40:41], s3, v94
	v_or_b32_e32 v94, 0x50, v1
	v_mov_b32_e32 v150, v75
	v_sub_u32_e32 v94, v94, v163
	v_pk_mul_f32 v[116:117], v[150:151], v[200:201]
	v_subrev_u32_e32 v96, 64, v94
	v_sub_f32_e32 v75, v116, v117
	s_and_b64 vcc, vcc, s[40:41]
	s_movk_i32 s16, 0xffaf
	v_add_u32_e32 v98, 0x50, v169
	v_cvt_f32_ubyte0_e32 v201, v96
	v_mov_b32_e32 v150, v68
	v_cndmask_b32_e32 v75, v241, v75, vcc
	v_cmp_lt_i32_e32 vcc, s16, v142
	v_cmp_gt_i32_e64 s[40:41], s3, v98
	v_pk_mul_f32 v[118:119], v[150:151], v[200:201]
	v_subrev_u32_e32 v96, 63, v94
	v_sub_f32_e32 v68, v118, v119
	s_and_b64 s[40:41], vcc, s[40:41]
	v_add_u32_e32 v98, 0x51, v169
	v_cvt_f32_ubyte0_e32 v201, v96
	v_mov_b32_e32 v150, v69
	v_cndmask_b32_e64 v68, v241, v68, s[40:41]
	v_cmp_gt_i32_e64 s[40:41], s3, v98
	v_pk_mul_f32 v[120:121], v[150:151], v[200:201]
	v_subrev_u32_e32 v96, 62, v94
	v_sub_f32_e32 v69, v120, v121
	s_and_b64 s[40:41], vcc, s[40:41]
	v_add_u32_e32 v98, 0x52, v169
	v_cvt_f32_ubyte0_e32 v201, v96
	v_mov_b32_e32 v150, v70
	v_subrev_u32_e32 v94, 61, v94
	v_cndmask_b32_e64 v69, v241, v69, s[40:41]
	v_cmp_gt_i32_e64 s[40:41], s3, v98
	v_pk_mul_f32 v[122:123], v[150:151], v[200:201]
	v_cvt_f32_ubyte0_e32 v201, v94
	v_or_b32_e32 v94, 0x60, v1
	v_sub_f32_e32 v70, v122, v123
	s_and_b64 s[40:41], vcc, s[40:41]
	v_add_u32_e32 v96, 0x53, v169
	v_mov_b32_e32 v150, v71
	v_sub_u32_e32 v94, v94, v163
	v_cndmask_b32_e64 v70, v241, v70, s[40:41]
	v_cmp_gt_i32_e64 s[40:41], s3, v96
	v_pk_mul_f32 v[124:125], v[150:151], v[200:201]
	v_subrev_u32_e32 v96, 64, v94
	v_sub_f32_e32 v71, v124, v125
	s_and_b64 vcc, vcc, s[40:41]
	s_movk_i32 s16, 0xff9f
	v_add_u32_e32 v98, 0x60, v169
	v_cvt_f32_ubyte0_e32 v201, v96
	v_mov_b32_e32 v150, v64
	v_cndmask_b32_e32 v71, v241, v71, vcc
	v_cmp_lt_i32_e32 vcc, s16, v142
	v_cmp_gt_i32_e64 s[40:41], s3, v98
	v_pk_mul_f32 v[126:127], v[150:151], v[200:201]
	v_subrev_u32_e32 v96, 63, v94
	v_sub_f32_e32 v64, v126, v127
	s_and_b64 s[40:41], vcc, s[40:41]
	v_add_u32_e32 v98, 0x61, v169
	v_cvt_f32_ubyte0_e32 v201, v96
	v_mov_b32_e32 v150, v65
	v_cndmask_b32_e64 v64, v241, v64, s[40:41]
	v_cmp_gt_i32_e64 s[40:41], s3, v98
	v_pk_mul_f32 v[128:129], v[150:151], v[200:201]
	v_subrev_u32_e32 v96, 62, v94
	v_sub_f32_e32 v65, v128, v129
	s_and_b64 s[40:41], vcc, s[40:41]
	v_add_u32_e32 v98, 0x62, v169
	v_cvt_f32_ubyte0_e32 v201, v96
	v_mov_b32_e32 v150, v66
	v_subrev_u32_e32 v94, 61, v94
	v_cndmask_b32_e64 v65, v241, v65, s[40:41]
	v_cmp_gt_i32_e64 s[40:41], s3, v98
	v_pk_mul_f32 v[130:131], v[150:151], v[200:201]
	v_cvt_f32_ubyte0_e32 v201, v94
	v_or_b32_e32 v94, 0x70, v1
	v_sub_f32_e32 v66, v130, v131
	s_and_b64 s[40:41], vcc, s[40:41]
	v_add_u32_e32 v96, 0x63, v169
	v_mov_b32_e32 v150, v67
	v_sub_u32_e32 v94, v94, v163
	v_cndmask_b32_e64 v66, v241, v66, s[40:41]
	v_cmp_gt_i32_e64 s[40:41], s3, v96
	v_pk_mul_f32 v[132:133], v[150:151], v[200:201]
	v_subrev_u32_e32 v96, 64, v94
	v_sub_f32_e32 v67, v132, v133
	s_and_b64 vcc, vcc, s[40:41]
	s_movk_i32 s16, 0xff8f
	v_add_u32_e32 v98, 0x70, v169
	v_cvt_f32_ubyte0_e32 v201, v96
	v_mov_b32_e32 v150, v60
	v_cndmask_b32_e32 v67, v241, v67, vcc
	v_cmp_lt_i32_e32 vcc, s16, v142
	v_cmp_gt_i32_e64 s[40:41], s3, v98
	v_pk_mul_f32 v[134:135], v[150:151], v[200:201]
	v_subrev_u32_e32 v96, 63, v94
	v_sub_f32_e32 v60, v134, v135
	s_and_b64 s[40:41], vcc, s[40:41]
	v_add_u32_e32 v98, 0x71, v169
	v_cvt_f32_ubyte0_e32 v201, v96
	v_mov_b32_e32 v150, v61
	v_max3_f32 v92, v92, v82, v83
	v_cndmask_b32_e64 v60, v241, v60, s[40:41]
	v_cmp_gt_i32_e64 s[40:41], s3, v98
	v_pk_mul_f32 v[136:137], v[150:151], v[200:201]
	v_max3_f32 v92, v92, v76, v77
	v_sub_f32_e32 v61, v136, v137
	s_and_b64 s[40:41], vcc, s[40:41]
	v_subrev_u32_e32 v96, 62, v94
	v_max3_f32 v92, v92, v78, v79
	v_cndmask_b32_e64 v61, v241, v61, s[40:41]
	v_cmp_ne_u32_e64 s[40:41], s25, v94
	v_add_u32_e32 v98, 0x72, v169
	v_cvt_f32_ubyte0_e32 v201, v96
	v_mov_b32_e32 v150, v62
	v_max3_f32 v92, v92, v72, v73
	s_and_b64 s[16:17], s[40:41], vcc
	v_cmp_gt_i32_e64 s[42:43], s3, v98
	v_pk_mul_f32 v[138:139], v[150:151], v[200:201]
	v_max3_f32 v92, v92, v74, v75
	v_sub_f32_e32 v62, v138, v139
	s_and_b64 s[42:43], s[16:17], s[42:43]
	v_max3_f32 v92, v92, v68, v69
	v_cndmask_b32_e64 v98, v241, v62, s[42:43]
	v_subrev_u32_e32 v62, 61, v94
	v_max3_f32 v92, v92, v70, v71
	v_cmp_gt_u32_e64 s[42:43], s33, v94
	v_add_u32_e32 v94, 0x73, v169
	v_cvt_f32_ubyte0_e32 v201, v62
	v_mov_b32_e32 v150, v63
	v_max3_f32 v92, v92, v64, v65
	s_and_b64 s[16:17], s[42:43], vcc
	v_cmp_gt_i32_e32 vcc, s3, v94
	v_pk_mul_f32 v[140:141], v[150:151], v[200:201]
	v_max3_f32 v92, v92, v66, v67
	v_sub_f32_e32 v62, v140, v141
	s_and_b64 vcc, s[16:17], vcc
	v_or_b32_e32 v63, 0x80, v1
	v_max3_f32 v92, v92, v60, v61
	v_cndmask_b32_e32 v100, v241, v62, vcc
	v_sub_u32_e32 v63, v63, v163
	v_max3_f32 v62, v92, v98, v100
	v_subrev_u32_e32 v92, 64, v63
	v_cvt_f32_u32_e32 v201, v92
	s_movk_i32 s16, 0xff7f
	v_cmp_lt_i32_e32 vcc, s16, v142
	v_add_u32_e32 v94, 0x80, v169
	v_cmp_gt_u32_e64 s[44:45], s31, v63
	v_mov_b32_e32 v150, v56
	s_and_b64 s[16:17], s[44:45], vcc
	v_cmp_gt_i32_e64 s[46:47], s3, v94
; #define LAS __attribute__((address_space(3)))
; __device__ __forceinline__ s16x4_t trread(LAS unsigned char* p) { return __builtin_amdgcn_ds_read_tr16_b64_v4i16((LAS s16x4_t*)p); }
; __device__ __forceinline__ void mixA_compute(bf16* Z, float* LSE, LAS unsigned char* lds, int u, int S, int tid) {
;     ...
;     for (int t = 0; t < 9; ++t)
; #pragma unroll
;         for (int j = 0; j < 4; ++j) {
;             const int rel = 16 * t + 4 * q + j - 64 - n, idxk = i0 - 64 + 16 * wt + 16 * t + 4 * q + j;
;             const bool valid = (rel >= -64) && (rel <= 64) && (idxk >= 0) && (idxk < Lg);
;             const float sc = s[t][j] * 0.125f - slope * (float)(rel < 0 ? -rel : rel);
;             s[t][j] = valid ? sc : -1e30f; m = fmaxf(m, s[t][j]);
;         }
;     m = fmaxf(m, __shfl_xor(m, 16)); m = fmaxf(m, __shfl_xor(m, 32));
;     float l = 0.f;
; #pragma unroll
;     for (int t = 0; t < 9; ++t)
; #pragma unroll
;         for (int j = 0; j < 4; ++j) { const float pe = __expf(s[t][j] - m); s[t][j] = pe; l += pe; }
;     l += __shfl_xor(l, 16); l += __shfl_xor(l, 32);
;     f32x4 o[4];
; #pragma unroll
;     for (int dt = 0; dt < 4; ++dt) o[dt] = (f32x4){0.f, 0.f, 0.f, 0.f};
;     LAS unsigned char* vb = lds + A_VOFF + (16 * wt + 4 * q + ((lane >> 2) & 3)) * KPITCH + 8 * (lane & 3);
; #pragma unroll
;     for (int G = 0; G < 5; ++G) {
;         const bf16x8_t pb = packp(s[2 * G], s[2 * G + 1]);
; #pragma unroll
;         for (int dt = 0; dt < 4; ++dt) {
;             const s16x4_t lo = trread(vb + (32 * G) * KPITCH + dt * 32), hi = trread(vb + (32 * G + 16) * KPITCH + dt * 32);
	v_pk_mul_f32 v[142:143], v[150:151], v[200:201]
	s_and_b64 s[46:47], s[16:17], s[46:47]
	v_sub_f32_e32 v56, v142, v143
	v_cndmask_b32_e64 v102, v241, v56, s[46:47]
	v_subrev_u32_e32 v56, 63, v63
	v_cvt_f32_u32_e32 v201, v56
	s_movk_i32 s16, 0x80
	v_mov_b32_e32 v150, v57
	v_subrev_u32_e32 v57, 62, v63
	v_cmp_gt_u32_e64 s[46:47], s16, v63
	v_add_u32_e32 v56, 0x81, v169
	v_pk_mul_f32 v[144:145], v[150:151], v[200:201]
	v_cvt_f32_u32_e32 v201, v57
	s_and_b64 s[16:17], s[46:47], vcc
	v_cmp_gt_i32_e64 s[48:49], s3, v56
	v_sub_f32_e32 v56, v144, v145
	s_and_b64 s[48:49], s[16:17], s[48:49]
	v_cndmask_b32_e64 v104, v241, v56, s[48:49]
	v_cmp_gt_u32_e64 s[48:49], s25, v63
	v_add_u32_e32 v57, 0x82, v169
	v_mov_b32_e32 v150, v58
	s_and_b64 s[16:17], s[48:49], vcc
	v_cmp_gt_i32_e64 s[50:51], s3, v57
	v_pk_mul_f32 v[146:147], v[150:151], v[200:201]
	s_and_b64 s[50:51], s[16:17], s[50:51]
	v_sub_f32_e32 v57, v146, v147
	v_cndmask_b32_e64 v106, v241, v57, s[50:51]
	v_subrev_u32_e32 v57, 61, v63
	v_cvt_f32_u32_e32 v201, v57
	v_cmp_gt_u32_e64 s[50:51], s33, v63
	v_add_u32_e32 v57, 0x83, v169
	v_mov_b32_e32 v150, v59
	s_and_b64 s[16:17], s[50:51], vcc
	v_cmp_gt_i32_e32 vcc, s3, v57
	v_pk_mul_f32 v[150:151], v[150:151], v[200:201]
	s_and_b64 vcc, s[16:17], vcc
	v_sub_f32_e32 v57, v150, v151
	v_max3_f32 v56, v62, v102, v104
	v_cndmask_b32_e32 v59, v241, v57, vcc
	v_max3_f32 v56, v56, v106, v59
	ds_bpermute_b32 v57, v162, v56
	v_xor_b32_e32 v58, 32, v231
	v_cmp_lt_i32_e32 vcc, v58, v168
	v_and_b32_e32 v62, 24, v167
	v_add_u32_e32 v92, 0, v62
	v_cndmask_b32_e32 v58, v231, v58, vcc
	s_waitcnt lgkmcnt(0)
	v_max_f32_e32 v57, v57, v57
	v_lshlrev_b32_e32 v96, 2, v58
	v_max_f32_e32 v56, v56, v57
	ds_bpermute_b32 v57, v96, v56
	v_lshrrev_b32_e32 v58, 2, v85
	v_and_or_b32 v94, v58, 3, v1
	v_cmp_eq_u32_e32 vcc, 0, v87
	s_waitcnt lgkmcnt(0)
	v_max_f32_e32 v57, v57, v57
	v_max_f32_e32 v58, v56, v57
	v_sub_f32_e32 v57, v160, v58
	v_mul_f32_e32 v57, 0x3fb8aa3b, v57
	v_exp_f32_e32 v62, v57
	v_sub_f32_e32 v57, v152, v58
	v_mul_f32_e32 v57, 0x3fb8aa3b, v57
	v_exp_f32_e32 v110, v57
	v_sub_f32_e32 v57, v148, v58
	v_mul_f32_e32 v57, 0x3fb8aa3b, v57
	v_exp_f32_e32 v112, v57
	v_sub_f32_e32 v57, v114, v58
	v_mul_f32_e32 v57, 0x3fb8aa3b, v57
	v_exp_f32_e32 v114, v57
	v_sub_f32_e32 v57, v80, v58
	v_mul_f32_e32 v57, 0x3fb8aa3b, v57
	v_exp_f32_e32 v80, v57
	v_sub_f32_e32 v57, v81, v58
	v_mul_f32_e32 v57, 0x3fb8aa3b, v57
	v_exp_f32_e32 v81, v57
	v_sub_f32_e32 v57, v82, v58
	v_mul_f32_e32 v57, 0x3fb8aa3b, v57
	v_exp_f32_e32 v82, v57
	v_sub_f32_e32 v57, v83, v58
	v_mul_f32_e32 v57, 0x3fb8aa3b, v57
	v_sub_f32_e32 v56, v154, v58
	v_exp_f32_e32 v83, v57
	v_sub_f32_e32 v57, v76, v58
	v_mul_f32_e32 v56, 0x3fb8aa3b, v56
	v_mul_f32_e32 v57, 0x3fb8aa3b, v57
	v_exp_f32_e32 v63, v56
	v_sub_f32_e32 v56, v156, v58
	v_exp_f32_e32 v116, v57
	v_sub_f32_e32 v57, v77, v58
	v_mul_f32_e32 v56, 0x3fb8aa3b, v56
	v_mul_f32_e32 v57, 0x3fb8aa3b, v57
	v_exp_f32_e32 v85, v56
	v_sub_f32_e32 v56, v158, v58
	v_exp_f32_e32 v118, v57
	v_sub_f32_e32 v57, v78, v58
	v_mul_f32_e32 v56, 0x3fb8aa3b, v56
	v_mul_f32_e32 v57, 0x3fb8aa3b, v57
	v_exp_f32_e32 v108, v56
	v_exp_f32_e32 v120, v57
	v_sub_f32_e32 v57, v79, v58
	v_mul_f32_e32 v57, 0x3fb8aa3b, v57
	v_add_f32_e32 v56, 0, v63
	v_exp_f32_e32 v122, v57
	v_sub_f32_e32 v57, v72, v58
	v_add_f32_e32 v56, v85, v56
	v_sub_f32_e32 v2, v2, v58
	v_mul_f32_e32 v57, 0x3fb8aa3b, v57
	v_add_f32_e32 v56, v108, v56
	v_mul_f32_e32 v2, 0x3fb8aa3b, v2
	v_exp_f32_e32 v124, v57
	v_sub_f32_e32 v57, v73, v58
	v_add_f32_e32 v56, v62, v56
	v_exp_f32_e32 v2, v2
	v_mul_f32_e32 v57, 0x3fb8aa3b, v57
	v_add_f32_e32 v56, v110, v56
	v_exp_f32_e32 v126, v57
	v_sub_f32_e32 v57, v74, v58
	v_add_f32_e32 v56, v112, v56
	v_mul_f32_e32 v57, 0x3fb8aa3b, v57
	v_add_f32_e32 v56, v114, v56
	v_exp_f32_e32 v128, v57
	v_sub_f32_e32 v57, v75, v58
	v_add_f32_e32 v56, v2, v56
	v_mul_f32_e32 v57, 0x3fb8aa3b, v57
	v_add_f32_e32 v56, v80, v56
	v_exp_f32_e32 v130, v57
	v_sub_f32_e32 v57, v68, v58
	v_add_f32_e32 v56, v81, v56
	v_mul_f32_e32 v57, 0x3fb8aa3b, v57
	v_add_f32_e32 v56, v82, v56
	v_exp_f32_e32 v132, v57
	v_sub_f32_e32 v57, v69, v58
	v_add_f32_e32 v56, v83, v56
	v_mul_f32_e32 v57, 0x3fb8aa3b, v57
	v_add_f32_e32 v56, v116, v56
	v_exp_f32_e32 v134, v57
	v_sub_f32_e32 v57, v70, v58
	v_add_f32_e32 v56, v118, v56
	v_mul_f32_e32 v57, 0x3fb8aa3b, v57
	v_add_f32_e32 v56, v120, v56
	v_exp_f32_e32 v136, v57
	v_sub_f32_e32 v57, v71, v58
	v_add_f32_e32 v56, v122, v56
	v_mul_f32_e32 v57, 0x3fb8aa3b, v57
	v_add_f32_e32 v56, v124, v56
	v_exp_f32_e32 v138, v57
	v_sub_f32_e32 v57, v64, v58
	v_add_f32_e32 v56, v126, v56
	v_mul_f32_e32 v57, 0x3fb8aa3b, v57
	v_add_f32_e32 v56, v128, v56
	v_exp_f32_e32 v140, v57
	v_sub_f32_e32 v57, v65, v58
	v_add_f32_e32 v56, v130, v56
	v_mul_f32_e32 v57, 0x3fb8aa3b, v57
	v_add_f32_e32 v56, v132, v56
	v_exp_f32_e32 v142, v57
	v_sub_f32_e32 v57, v66, v58
	v_add_f32_e32 v56, v134, v56
	v_mul_f32_e32 v57, 0x3fb8aa3b, v57
	v_add_f32_e32 v56, v136, v56
	v_exp_f32_e32 v144, v57
	v_add_f32_e32 v56, v138, v56
	v_add_f32_e32 v56, v140, v56
	v_add_f32_e32 v56, v142, v56
	v_add_f32_e32 v146, v144, v56
	v_sub_f32_e32 v56, v67, v58
	v_mul_f32_e32 v56, 0x3fb8aa3b, v56
	v_exp_f32_e32 v148, v56
	v_sub_f32_e32 v56, v60, v58
	v_mul_f32_e32 v56, 0x3fb8aa3b, v56
	v_exp_f32_e32 v150, v56
	v_or_b32_e32 v56, v94, v166
	v_sub_f32_e32 v68, v61, v58
	v_mad_u64_u32 v[56:57], s[16:17], v56, s67, v[92:93]
	v_cvt_pk_bf16_f32 v60, v63, v85
	v_cvt_pk_bf16_f32 v61, v108, v62
	v_cvt_pk_bf16_f32 v62, v110, v112
	v_cvt_pk_bf16_f32 v63, v114, v2
	ds_read_b64_tr_b16 v[66:67], v56 offset:59904
	ds_read_b64_tr_b16 v[64:65], v56 offset:57600
	v_mul_f32_e32 v2, 0x3fb8aa3b, v68
	ds_read_b64_tr_b16 v[70:71], v56 offset:59936
	ds_read_b64_tr_b16 v[68:69], v56 offset:57632
	ds_read_b64_tr_b16 v[72:73], v56 offset:57664
	ds_read_b64_tr_b16 v[76:77], v56 offset:57696
	ds_read_b64_tr_b16 v[74:75], v56 offset:59968
	ds_read_b64_tr_b16 v[78:79], v56 offset:60000
	s_waitcnt lgkmcnt(4)
; __device__ __forceinline__ unsigned cvt_pk_bf16(float lo, float hi) { unsigned r; asm volatile("v_cvt_pk_bf16_f32 %0, %1, %2" : "=v"(r) : "v"(lo), "v"(hi)); return r; }
; __device__ __forceinline__ s16x4_t trread(LAS unsigned char* p) { return __builtin_amdgcn_ds_read_tr16_b64_v4i16((LAS s16x4_t*)p); }
; __device__ __forceinline__ bf16x8_t cat4(s16x4_t a, s16x4_t b) { return (bf16x8_t){a[0], a[1], a[2], a[3], b[0], b[1], b[2], b[3]}; }
; __device__ __forceinline__ void mixA_compute(bf16* Z, float* LSE, LAS unsigned char* lds, int u, int S, int tid) {
;     ...
; #pragma unroll
;     for (int G = 0; G < 5; ++G) {
;         const bf16x8_t pb = packp(s[2 * G], s[2 * G + 1]);
; #pragma unroll
;         for (int dt = 0; dt < 4; ++dt) {
;             const s16x4_t lo = trread(vb + (32 * G) * KPITCH + dt * 32), hi = trread(vb + (32 * G + 16) * KPITCH + dt * 32);
;             o[dt] = __builtin_amdgcn_mfma_f32_16x16x32_bf16(cat4(lo, hi), pb, o[dt], 0, 0, 0);
;         }
;     }
;     const float inv = __builtin_amdgcn_rcpf(l);
; #pragma unroll
;     for (int dt = 0; dt < 4; ++dt) { uint2 wv; wv.x = pg8::cvt_pk_bf16(o[dt][0] * inv, o[dt][1] * inv); wv.y = pg8::cvt_pk_bf16(o[dt][2] * inv, o[dt][3] * inv);
;         *(uint2*)(qp + dt * 16 + 4 * q) = wv; }
;     if (q == 0) LSE[((size_t)g * MC + tokc) * 8 + h] = m + __logf(l);
	v_mfma_f32_16x16x32_bf16 v[68:71], v[68:71], v[60:63], 0
	v_cvt_pk_bf16_f32 v80, v80, v81
	v_cvt_pk_bf16_f32 v81, v82, v83
	v_cvt_pk_bf16_f32 v82, v116, v118
	v_mfma_f32_16x16x32_bf16 v[64:67], v[64:67], v[60:63], 0
	v_cvt_pk_bf16_f32 v83, v120, v122
	ds_read_b64_tr_b16 v[168:169], v56 offset:64512
	ds_read_b64_tr_b16 v[166:167], v56 offset:62208
	v_exp_f32_e32 v2, v2
	s_waitcnt lgkmcnt(3)
	v_mfma_f32_16x16x32_bf16 v[72:75], v[72:75], v[60:63], 0
	v_sub_f32_e32 v85, v98, v58
	v_mul_f32_e32 v85, 0x3fb8aa3b, v85
	v_sub_f32_e32 v98, v100, v58
	s_waitcnt lgkmcnt(2)
	v_mfma_f32_16x16x32_bf16 v[60:63], v[76:79], v[60:63], 0
	ds_read_b64_tr_b16 v[78:79], v56 offset:64544
	ds_read_b64_tr_b16 v[76:77], v56 offset:62240
	ds_read_b64_tr_b16 v[170:171], v56 offset:62272
	ds_read_b64_tr_b16 v[174:175], v56 offset:62304
	ds_read_b64_tr_b16 v[172:173], v56 offset:64576
	ds_read_b64_tr_b16 v[176:177], v56 offset:64608
	v_add_u32_e32 v56, 0xe100, v56
	v_add_f32_e32 v57, v148, v146
	s_waitcnt lgkmcnt(4)
	v_mfma_f32_16x16x32_bf16 v[68:71], v[76:79], v[80:83], v[68:71]
	v_sub_f32_e32 v76, v102, v58
	v_exp_f32_e32 v85, v85
	v_mul_f32_e32 v98, 0x3fb8aa3b, v98
	v_mfma_f32_16x16x32_bf16 v[64:67], v[166:169], v[80:83], v[64:67]
	v_mul_f32_e32 v100, 0x3fb8aa3b, v76
	v_cvt_pk_bf16_f32 v76, v124, v126
	v_cvt_pk_bf16_f32 v77, v128, v130
	s_waitcnt lgkmcnt(1)
	v_mfma_f32_16x16x32_bf16 v[72:75], v[170:173], v[80:83], v[72:75]
	v_cvt_pk_bf16_f32 v78, v132, v134
	v_cvt_pk_bf16_f32 v79, v136, v138
	ds_read_b64_tr_b16 v[168:169], v56 offset:11520
	ds_read_b64_tr_b16 v[166:167], v56 offset:9216
	s_waitcnt lgkmcnt(2)
	v_mfma_f32_16x16x32_bf16 v[60:63], v[174:177], v[80:83], v[60:63]
	ds_read_b64_tr_b16 v[82:83], v56 offset:11552
	ds_read_b64_tr_b16 v[80:81], v56 offset:9248
	ds_read_b64_tr_b16 v[170:171], v56 offset:9280
	ds_read_b64_tr_b16 v[174:175], v56 offset:9312
	ds_read_b64_tr_b16 v[172:173], v56 offset:11584
	ds_read_b64_tr_b16 v[176:177], v56 offset:11616
	v_add_f32_e32 v57, v150, v57
	v_exp_f32_e32 v98, v98
	v_sub_f32_e32 v102, v104, v58
	v_add_f32_e32 v57, v2, v57
	v_exp_f32_e32 v100, v100
	v_mul_f32_e32 v102, 0x3fb8aa3b, v102
	s_waitcnt lgkmcnt(4)
	v_mfma_f32_16x16x32_bf16 v[68:71], v[80:83], v[76:79], v[68:71]
	v_cvt_pk_bf16_f32 v80, v140, v142
	v_cvt_pk_bf16_f32 v81, v144, v148
	v_cvt_pk_bf16_f32 v82, v150, v2
	v_sub_f32_e32 v2, v106, v58
	v_exp_f32_e32 v102, v102
	v_mul_f32_e32 v2, 0x3fb8aa3b, v2
	v_sub_f32_e32 v59, v59, v58
	v_add_f32_e32 v57, v85, v57
	v_exp_f32_e32 v2, v2
	v_mul_f32_e32 v59, 0x3fb8aa3b, v59
	v_mfma_f32_16x16x32_bf16 v[64:67], v[166:169], v[76:79], v[64:67]
	v_add_f32_e32 v57, v98, v57
	v_cvt_pk_bf16_f32 v83, v85, v98
	ds_read_b64_tr_b16 v[168:169], v56 offset:16128
	ds_read_b64_tr_b16 v[166:167], v56 offset:13824
	s_waitcnt lgkmcnt(3)
	v_mfma_f32_16x16x32_bf16 v[72:75], v[170:173], v[76:79], v[72:75]
	v_exp_f32_e32 v59, v59
	v_add_f32_e32 v57, v100, v57
	v_add_f32_e32 v57, v102, v57
	s_waitcnt lgkmcnt(2)
	v_mfma_f32_16x16x32_bf16 v[60:63], v[174:177], v[76:79], v[60:63]
	ds_read_b64_tr_b16 v[78:79], v56 offset:16160
	ds_read_b64_tr_b16 v[76:77], v56 offset:13856
	ds_read_b64_tr_b16 v[170:171], v56 offset:13888
	ds_read_b64_tr_b16 v[174:175], v56 offset:13920
	ds_read_b64_tr_b16 v[172:173], v56 offset:16192
	ds_read_b64_tr_b16 v[176:177], v56 offset:16224
	v_add_f32_e32 v57, v2, v57
	s_waitcnt lgkmcnt(4)
	v_mfma_f32_16x16x32_bf16 v[68:71], v[76:79], v[80:83], v[68:71]
	v_cvt_pk_bf16_f32 v76, v100, v102
	v_cvt_pk_bf16_f32 v77, v2, v59
	v_add_f32_e32 v2, v59, v57
	v_mfma_f32_16x16x32_bf16 v[64:67], v[166:169], v[80:83], v[64:67]
	v_cvt_pk_bf16_f32 v78, v0, v0
	v_cvt_pk_bf16_f32 v79, v0, v0
	ds_read_b64_tr_b16 v[168:169], v56 offset:20736
	ds_read_b64_tr_b16 v[166:167], v56 offset:18432
	s_waitcnt lgkmcnt(3)
	v_mfma_f32_16x16x32_bf16 v[72:75], v[170:173], v[80:83], v[72:75]
	v_mov_b32_e32 v57, v0
	s_waitcnt lgkmcnt(2)
	v_mfma_f32_16x16x32_bf16 v[60:63], v[174:177], v[80:83], v[60:63]
	ds_read_b64_tr_b16 v[80:81], v56 offset:18464
	ds_read_b64_tr_b16 v[170:171], v56 offset:18496
	ds_read_b64_tr_b16 v[174:175], v56 offset:18528
	ds_read_b64_tr_b16 v[82:83], v56 offset:20768
	ds_read_b64_tr_b16 v[172:173], v56 offset:20800
	ds_read_b64_tr_b16 v[176:177], v56 offset:20832
	ds_bpermute_b32 v56, v162, v2
	s_waitcnt lgkmcnt(0)
	v_add_f32_e32 v2, v2, v56
	ds_bpermute_b32 v59, v96, v2
	v_mfma_f32_16x16x32_bf16 v[64:67], v[166:169], v[76:79], v[64:67]
	v_lshlrev_b32_e32 v56, 3, v87
	s_waitcnt lgkmcnt(0)
	v_add_f32_e32 v2, v2, v59
	v_rcp_f32_e32 v59, v2
	v_mfma_f32_16x16x32_bf16 v[68:71], v[80:83], v[76:79], v[68:71]
	v_mfma_f32_16x16x32_bf16 v[72:75], v[170:173], v[76:79], v[72:75]
	v_mfma_f32_16x16x32_bf16 v[60:63], v[174:177], v[76:79], v[60:63]
	v_lshl_add_u64 v[76:77], v[88:89], 0, v[56:57]
	v_mul_f32_e32 v57, v59, v64
	v_mul_f32_e32 v64, v59, v65
	v_cvt_pk_bf16_f32 v64, v57, v64
	v_mul_f32_e32 v57, v59, v66
	v_mul_f32_e32 v65, v59, v67
	v_cvt_pk_bf16_f32 v65, v57, v65
	v_lshrrev_b32_e32 v218, 4, v231
	v_lshl_or_b32 v218, v231, 4, v218
	v_and_b32_e32 v218, 0x33, v218
	v_and_or_b32 v218, v231, 12, v218
	v_lshlrev_b32_e32 v218, 2, v218
	ds_bpermute_b32 v220, v218, v76
	ds_bpermute_b32 v221, v218, v77
	ds_bpermute_b32 v64, v218, v64
	ds_bpermute_b32 v65, v218, v65
	s_waitcnt lgkmcnt(0)
	global_store_dwordx2 v[220:221], v[64:65], off
	v_mul_f32_e32 v57, v59, v68
	v_mul_f32_e32 v64, v59, v69
	v_cvt_pk_bf16_f32 v64, v57, v64
	v_mul_f32_e32 v57, v59, v70
	v_mul_f32_e32 v65, v59, v71
	v_cvt_pk_bf16_f32 v65, v57, v65
	ds_bpermute_b32 v64, v218, v64
	ds_bpermute_b32 v65, v218, v65
	s_waitcnt lgkmcnt(0)
	global_store_dwordx2 v[220:221], v[64:65], off offset:32
	v_mul_f32_e32 v57, v59, v72
	v_mul_f32_e32 v64, v59, v73
	v_cvt_pk_bf16_f32 v64, v57, v64
	v_mul_f32_e32 v57, v59, v74
	v_mul_f32_e32 v65, v59, v75
	v_cvt_pk_bf16_f32 v65, v57, v65
	v_mul_f32_e32 v57, v59, v60
	v_mul_f32_e32 v60, v59, v61
	ds_bpermute_b32 v64, v218, v64
	ds_bpermute_b32 v65, v218, v65
	s_waitcnt lgkmcnt(0)
	global_store_dwordx2 v[220:221], v[64:65], off offset:64
	v_cvt_pk_bf16_f32 v60, v57, v60
	v_mul_f32_e32 v57, v59, v62
	v_mul_f32_e32 v59, v59, v63
	v_cvt_pk_bf16_f32 v61, v57, v59
	ds_bpermute_b32 v60, v218, v60
	ds_bpermute_b32 v61, v218, v61
	s_waitcnt lgkmcnt(0)
	global_store_dwordx2 v[220:221], v[60:61], off offset:96
	s_and_saveexec_b64 s[16:17], vcc
	s_cbranch_execz .LBB0_258
	s_mov_b32 s25, 0x800000
	v_cmp_gt_f32_e64 s[60:61], s25, v2
	s_mov_b32 s25, 0x3f317217
	v_ashrrev_i32_e32 v87, 31, v86
	v_cndmask_b32_e64 v57, 0, 32, s[60:61]
	v_ldexp_f32 v2, v2, v57
	v_log_f32_e32 v2, v2
	v_lshlrev_b64 v[60:61], 5, v[86:87]
	v_lshl_add_u64 v[60:61], s[64:65], 0, v[60:61]
	v_mul_f32_e32 v57, 0x3f317217, v2
	v_fma_f32 v57, v2, s25, -v57
	v_fmac_f32_e32 v57, 0x3377d1cf, v2
	v_fmac_f32_e32 v57, 0x3f317217, v2
	v_cmp_lt_f32_e64 s[62:63], |v2|, s87
	s_nop 1
	v_cndmask_b32_e64 v2, v2, v57, s[62:63]
	v_cndmask_b32_e64 v57, 0, v242, s[60:61]
	v_sub_f32_e32 v2, v2, v57
	v_add_f32_e32 v2, v58, v2
	global_store_dword v[60:61], v2, off
; #define LAS __attribute__((address_space(3)))
; __device__ __forceinline__ void mixA_compute(bf16* Z, float* LSE, LAS unsigned char* lds, int u, int S, int tid) {
;     ...
;     for (int qt = 0; qt < 2; ++qt) {
;     const int wt = 2 * w + qt;
;     const int iq = i0 + 16 * wt + n, tokc = seq0 + iq * dil + r;
;     bf16* qp = Z + (size_t)tokc * NZ + g * 512 + h * 64;
;     const bf16x8_t qf0 = *(const bf16x8_t*)(qp + 8 * q), qf1 = *(const bf16x8_t*)(qp + 32 + 8 * q);
;     f32x4 s[10];
; #pragma unroll
;     for (int t = 0; t < 9; ++t) {
;         LAS unsigned char* kp = lds + (16 * wt + 16 * t + n) * KPITCH + q * 16;
;         const bf16x8_t kf0 = *(LAS bf16x8_t*)kp, kf1 = *(LAS bf16x8_t*)(kp + 64);
;         f32x4 a = {0.f, 0.f, 0.f, 0.f};
;         a = __builtin_amdgcn_mfma_f32_16x16x32_bf16(kf0, qf0, a, 0, 0, 0);
;         s[t] = __builtin_amdgcn_mfma_f32_16x16x32_bf16(kf1, qf1, a, 0, 0, 0);
;     }
;     s[9] = (f32x4){0.f, 0.f, 0.f, 0.f};
;     const float slope = exp2f(-(float)(h + 1)) * (float)dil;
;     float m = -1e30f;
; #pragma unroll
;     for (int t = 0; t < 9; ++t)
; #pragma unroll
;         for (int j = 0; j < 4; ++j) {
;             const int rel = 16 * t + 4 * q + j - 64 - n, idxk = i0 - 64 + 16 * wt + 16 * t + 4 * q + j;
;             const bool valid = (rel >= -64) && (rel <= 64) && (idxk >= 0) && (idxk < Lg);
;             const float sc = s[t][j] * 0.125f - slope * (float)(rel < 0 ? -rel : rel);
;             s[t][j] = valid ? sc : -1e30f; m = fmaxf(m, s[t][j]);
.LBB0_258:
	s_or_b64 exec, exec, s[16:17]
	v_or_b32_e32 v98, 16, v165
	v_add_lshl_u32 v2, v164, v98, s22
	v_add_u32_e32 v2, s15, v2
	v_mov_b64_e32 v[58:59], s[68:69]
	v_mad_i64_i32 v[88:89], s[16:17], v2, s66, v[58:59]
	v_lshlrev_b32_e32 v56, 1, v56
	v_mov_b32_e32 v57, v0
	v_lshl_add_u64 v[60:61], v[88:89], 0, v[56:57]
	v_or_b32_e32 v60, v98, v163
	v_mad_u64_u32 v[64:65], s[16:17], v60, s67, v[84:85]
	ds_read_b128 v[60:63], v64
	ds_read_b128 v[64:67], v64 offset:64
	v_add_u32_e32 v108, s24, v98
	v_cmp_lt_i32_e64 s[60:61], -1, v108
	v_or_b32_e32 v100, v108, v1
	v_add_u32_e32 v112, 16, v108
	s_movk_i32 s15, 0xffef
	v_or_b32_e32 v112, v112, v1
	v_or_b32_e32 v114, 1, v112
	s_waitcnt lgkmcnt(1)
	v_mfma_f32_16x16x32_bf16 v[60:63], v[60:63], v[188:191], 0
	s_waitcnt lgkmcnt(0)
	v_mfma_f32_16x16x32_bf16 v[168:171], v[64:67], v[192:195], v[60:63]
	s_nop 5
	v_add_u32_e32 v60, v98, v163
	v_mad_u64_u32 v[176:177], s[16:17], v60, s67, v[84:85]
	ds_read_b128 v[60:63], v176 offset:2304
	ds_read_b128 v[64:67], v176 offset:2368
	s_and_b64 s[16:17], s[52:53], s[60:61]
	v_cmp_gt_i32_e64 s[52:53], s3, v100
	s_and_b64 s[52:53], s[16:17], s[52:53]
	v_fma_f32 v102, v168, s23, -v155
	v_cndmask_b32_e64 v106, v241, v102, s[52:53]
	v_or_b32_e32 v102, 1, v100
	s_waitcnt lgkmcnt(1)
	v_mfma_f32_16x16x32_bf16 v[60:63], v[60:63], v[188:191], 0
	s_and_b64 s[16:17], s[54:55], s[60:61]
	v_cmp_gt_i32_e64 s[52:53], s3, v102
	s_and_b64 s[52:53], s[16:17], s[52:53]
	v_fma_f32 v102, v169, s23, -v157
	v_cndmask_b32_e64 v104, v241, v102, s[52:53]
	v_or_b32_e32 v102, 2, v100
	s_and_b64 s[16:17], s[56:57], s[60:61]
	v_cmp_gt_i32_e64 s[52:53], s3, v102
	s_waitcnt lgkmcnt(0)
	v_mfma_f32_16x16x32_bf16 v[84:87], v[64:67], v[192:195], v[60:63]
	s_and_b64 s[52:53], s[16:17], s[52:53]
	v_fma_f32 v102, v170, s23, -v159
	v_or_b32_e32 v100, 3, v100
	v_cndmask_b32_e64 v102, v241, v102, s[52:53]
	s_and_b64 s[16:17], s[58:59], s[60:61]
	v_cmp_gt_i32_e64 s[52:53], s3, v100
	s_and_b64 s[52:53], s[16:17], s[52:53]
	v_fma_f32 v100, v171, s23, -v161
	ds_read_b128 v[60:63], v176 offset:4608
	ds_read_b128 v[64:67], v176 offset:4672
	v_cndmask_b32_e64 v100, v241, v100, s[52:53]
	v_cmp_lt_i32_e64 s[52:53], s15, v108
	v_cmp_gt_i32_e64 s[54:55], s3, v112
	s_and_b64 s[54:55], s[52:53], s[54:55]
	v_fma_f32 v84, v84, s23, -v153
	v_cndmask_b32_e64 v84, v241, v84, s[54:55]
	v_cmp_gt_i32_e64 s[54:55], s3, v114
	s_and_b64 s[54:55], s[52:53], s[54:55]
	v_fma_f32 v85, v85, s23, -v149
	v_or_b32_e32 v114, 2, v112
	s_waitcnt lgkmcnt(1)
	v_mfma_f32_16x16x32_bf16 v[60:63], v[60:63], v[188:191], 0
	v_cndmask_b32_e64 v85, v241, v85, s[54:55]
	v_cmp_gt_i32_e64 s[54:55], s3, v114
	s_and_b64 s[54:55], s[52:53], s[54:55]
	v_fma_f32 v86, v86, s23, -v115
	v_or_b32_e32 v112, 3, v112
	v_max3_f32 v110, v106, s84, v104
	v_cndmask_b32_e64 v86, v241, v86, s[54:55]
	v_cmp_gt_i32_e64 s[54:55], s3, v112
	v_max3_f32 v110, v110, v102, v100
	s_and_b64 s[52:53], s[52:53], s[54:55]
	v_fma_f32 v3, v87, s23, -v3
	s_waitcnt lgkmcnt(0)
	v_mfma_f32_16x16x32_bf16 v[80:83], v[64:67], v[192:195], v[60:63]
	s_nop 2
	ds_read_b128 v[60:63], v176 offset:6912
	ds_read_b128 v[64:67], v176 offset:6976
	v_max3_f32 v110, v110, v84, v85
	v_cndmask_b32_e64 v3, v241, v3, s[52:53]
	v_max3_f32 v87, v110, v86, v3
	v_add_u32_e32 v110, 32, v108
	s_movk_i32 s15, 0xffdf
	v_or_b32_e32 v110, v110, v1
	v_cmp_lt_i32_e64 s[52:53], s15, v108
	v_cmp_gt_i32_e64 s[54:55], s3, v110
	s_waitcnt lgkmcnt(1)
	v_mfma_f32_16x16x32_bf16 v[60:63], v[60:63], v[188:191], 0
	s_and_b64 s[54:55], s[52:53], s[54:55]
	v_fma_f32 v80, v80, s23, -v93
	v_or_b32_e32 v93, 1, v110
	v_cndmask_b32_e64 v80, v241, v80, s[54:55]
	v_cmp_gt_i32_e64 s[54:55], s3, v93
	s_and_b64 s[54:55], s[52:53], s[54:55]
	v_fma_f32 v81, v81, s23, -v95
	v_or_b32_e32 v93, 2, v110
	v_cndmask_b32_e64 v81, v241, v81, s[54:55]
	v_cmp_gt_i32_e64 s[54:55], s3, v93
	s_waitcnt lgkmcnt(0)
	v_mfma_f32_16x16x32_bf16 v[76:79], v[64:67], v[192:195], v[60:63]
	s_and_b64 s[54:55], s[52:53], s[54:55]
	v_fma_f32 v82, v82, s23, -v97
	v_or_b32_e32 v93, 3, v110
	ds_read_b128 v[60:63], v176 offset:9216
	ds_read_b128 v[64:67], v176 offset:9280
	v_cndmask_b32_e64 v82, v241, v82, s[54:55]
	v_cmp_gt_i32_e64 s[54:55], s3, v93
	v_add_u32_e32 v93, 48, v108
	s_and_b64 s[52:53], s[52:53], s[54:55]
	v_fma_f32 v83, v83, s23, -v99
	s_movk_i32 s15, 0xffcf
	v_or_b32_e32 v93, v93, v1
	v_cndmask_b32_e64 v83, v241, v83, s[52:53]
	v_cmp_lt_i32_e64 s[52:53], s15, v108
	v_cmp_gt_i32_e64 s[54:55], s3, v93
	s_and_b64 s[54:55], s[52:53], s[54:55]
	v_fma_f32 v76, v76, s23, -v101
	v_or_b32_e32 v95, 1, v93
	s_waitcnt lgkmcnt(1)
	v_mfma_f32_16x16x32_bf16 v[60:63], v[60:63], v[188:191], 0
	v_cndmask_b32_e64 v76, v241, v76, s[54:55]
	v_cmp_gt_i32_e64 s[54:55], s3, v95
	s_and_b64 s[54:55], s[52:53], s[54:55]
	v_fma_f32 v77, v77, s23, -v103
	v_or_b32_e32 v95, 2, v93
	v_cndmask_b32_e64 v77, v241, v77, s[54:55]
	v_cmp_gt_i32_e64 s[54:55], s3, v95
	s_and_b64 s[54:55], s[52:53], s[54:55]
	v_fma_f32 v78, v78, s23, -v105
	v_or_b32_e32 v93, 3, v93
	s_waitcnt lgkmcnt(0)
	v_mfma_f32_16x16x32_bf16 v[72:75], v[64:67], v[192:195], v[60:63]
	s_nop 2
	ds_read_b128 v[60:63], v176 offset:11520
	ds_read_b128 v[64:67], v176 offset:11584
	v_cndmask_b32_e64 v78, v241, v78, s[54:55]
	v_cmp_gt_i32_e64 s[54:55], s3, v93
	s_and_b64 s[52:53], s[52:53], s[54:55]
	v_fma_f32 v79, v79, s23, -v107
	v_add_u32_e32 v93, s4, v98
	v_cndmask_b32_e64 v79, v241, v79, s[52:53]
	v_cmp_lt_i32_e64 s[52:53], -1, v93
	v_or_b32_e32 v93, v93, v1
	v_cmp_gt_i32_e64 s[54:55], s3, v93
	s_waitcnt lgkmcnt(1)
; __device__ __forceinline__ void mixA_compute(bf16* Z, float* LSE, LAS unsigned char* lds, int u, int S, int tid) {
;     ...
; #pragma unroll
;     for (int t = 0; t < 9; ++t)
; #pragma unroll
;         for (int j = 0; j < 4; ++j) {
;             const int rel = 16 * t + 4 * q + j - 64 - n, idxk = i0 - 64 + 16 * wt + 16 * t + 4 * q + j;
;             const bool valid = (rel >= -64) && (rel <= 64) && (idxk >= 0) && (idxk < Lg);
;             const float sc = s[t][j] * 0.125f - slope * (float)(rel < 0 ? -rel : rel);
;             s[t][j] = valid ? sc : -1e30f; m = fmaxf(m, s[t][j]);
;         }
;     m = fmaxf(m, __shfl_xor(m, 16)); m = fmaxf(m, __shfl_xor(m, 32));
	v_mfma_f32_16x16x32_bf16 v[60:63], v[60:63], v[188:191], 0
	s_and_b64 s[54:55], s[52:53], s[54:55]
	v_fma_f32 v72, v72, s23, -v109
	v_or_b32_e32 v95, 1, v93
	v_cndmask_b32_e64 v72, v241, v72, s[54:55]
	v_cmp_gt_i32_e64 s[54:55], s3, v95
	s_and_b64 s[54:55], s[52:53], s[54:55]
	v_fma_f32 v73, v73, s23, -v111
	v_or_b32_e32 v95, 2, v93
	v_cndmask_b32_e64 v73, v241, v73, s[54:55]
	v_cmp_gt_i32_e64 s[54:55], s3, v95
	s_waitcnt lgkmcnt(0)
	v_mfma_f32_16x16x32_bf16 v[68:71], v[64:67], v[192:195], v[60:63]
	s_nop 2
	ds_read_b128 v[60:63], v176 offset:13824
	ds_read_b128 v[64:67], v176 offset:13888
	s_and_b64 s[54:55], s[52:53], s[54:55]
	v_fma_f32 v74, v74, s23, -v113
	v_or_b32_e32 v93, 3, v93
	v_cndmask_b32_e64 v74, v241, v74, s[54:55]
	v_cmp_gt_i32_e64 s[54:55], s3, v93
	v_add_u32_e32 v93, 0x50, v108
	s_and_b64 s[52:53], s[52:53], s[54:55]
	v_fma_f32 v75, v75, s23, -v117
	s_movk_i32 s4, 0xffaf
	v_or_b32_e32 v93, v93, v1
	v_cndmask_b32_e64 v75, v241, v75, s[52:53]
	v_cmp_lt_i32_e64 s[52:53], s4, v108
	v_cmp_gt_i32_e64 s[54:55], s3, v93
	s_waitcnt lgkmcnt(1)
	v_mfma_f32_16x16x32_bf16 v[60:63], v[60:63], v[188:191], 0
	s_and_b64 s[54:55], s[52:53], s[54:55]
	v_fma_f32 v68, v68, s23, -v119
	v_or_b32_e32 v95, 1, v93
	v_cndmask_b32_e64 v68, v241, v68, s[54:55]
	v_cmp_gt_i32_e64 s[54:55], s3, v95
	s_and_b64 s[54:55], s[52:53], s[54:55]
	v_fma_f32 v69, v69, s23, -v121
	v_or_b32_e32 v95, 2, v93
	v_cndmask_b32_e64 v69, v241, v69, s[54:55]
	v_cmp_gt_i32_e64 s[54:55], s3, v95
	s_waitcnt lgkmcnt(0)
	v_mfma_f32_16x16x32_bf16 v[64:67], v[64:67], v[192:195], v[60:63]
	s_and_b64 s[54:55], s[52:53], s[54:55]
	v_fma_f32 v70, v70, s23, -v123
	v_or_b32_e32 v93, 3, v93
	ds_read_b128 v[60:63], v176 offset:16128
	ds_read_b128 v[172:175], v176 offset:16192
	v_cndmask_b32_e64 v70, v241, v70, s[54:55]
	v_cmp_gt_i32_e64 s[54:55], s3, v93
	v_add_u32_e32 v93, 0x60, v108
	s_and_b64 s[52:53], s[52:53], s[54:55]
	v_fma_f32 v71, v71, s23, -v125
	s_movk_i32 s4, 0xff9f
	v_or_b32_e32 v93, v93, v1
	v_cndmask_b32_e64 v71, v241, v71, s[52:53]
	v_cmp_lt_i32_e64 s[52:53], s4, v108
	v_cmp_gt_i32_e64 s[54:55], s3, v93
	v_max3_f32 v87, v87, v80, v81
	s_and_b64 s[54:55], s[52:53], s[54:55]
	v_fma_f32 v64, v64, s23, -v127
	v_or_b32_e32 v95, 1, v93
	s_waitcnt lgkmcnt(1)
	v_mfma_f32_16x16x32_bf16 v[60:63], v[60:63], v[188:191], 0
	v_max3_f32 v87, v87, v82, v83
	v_cndmask_b32_e64 v64, v241, v64, s[54:55]
	v_cmp_gt_i32_e64 s[54:55], s3, v95
	v_max3_f32 v87, v87, v76, v77
	s_and_b64 s[54:55], s[52:53], s[54:55]
	v_fma_f32 v65, v65, s23, -v129
	v_or_b32_e32 v95, 2, v93
	v_max3_f32 v87, v87, v78, v79
	v_cndmask_b32_e64 v65, v241, v65, s[54:55]
	v_cmp_gt_i32_e64 s[54:55], s3, v95
	v_max3_f32 v87, v87, v72, v73
	s_and_b64 s[54:55], s[52:53], s[54:55]
	v_fma_f32 v66, v66, s23, -v131
	s_waitcnt lgkmcnt(0)
	v_mfma_f32_16x16x32_bf16 v[60:63], v[172:175], v[192:195], v[60:63]
	v_max3_f32 v87, v87, v74, v75
	v_cndmask_b32_e64 v95, v241, v66, s[54:55]
	v_or_b32_e32 v66, 3, v93
	v_max3_f32 v87, v87, v68, v69
	v_cmp_gt_i32_e64 s[54:55], s3, v66
	v_fma_f32 v66, v67, s23, -v133
	v_add_u32_e32 v67, 0x70, v108
	ds_read_b128 v[172:175], v176 offset:18432
	ds_read_b128 v[176:179], v176 offset:18496
	v_max3_f32 v87, v87, v70, v71
	s_and_b64 s[52:53], s[52:53], s[54:55]
	s_movk_i32 s4, 0xff8f
	v_or_b32_e32 v67, v67, v1
	v_max3_f32 v87, v87, v64, v65
	v_cndmask_b32_e64 v93, v241, v66, s[52:53]
	v_cmp_lt_i32_e64 s[52:53], s4, v108
	v_cmp_gt_i32_e64 s[54:55], s3, v67
	v_max3_f32 v66, v87, v95, v93
	s_and_b64 s[54:55], s[52:53], s[54:55]
	v_fma_f32 v60, v60, s23, -v135
	v_or_b32_e32 v87, 1, v67
	v_cndmask_b32_e64 v60, v241, v60, s[54:55]
	v_cmp_gt_i32_e64 s[54:55], s3, v87
	v_or_b32_e32 v87, 2, v67
	s_waitcnt lgkmcnt(1)
	v_mfma_f32_16x16x32_bf16 v[56:59], v[172:175], v[188:191], 0
	s_and_b64 s[16:17], s[40:41], s[52:53]
	v_cmp_gt_i32_e64 s[40:41], s3, v87
	s_and_b64 s[40:41], s[16:17], s[40:41]
	v_fma_f32 v62, v62, s23, -v139
	v_cndmask_b32_e64 v87, v241, v62, s[40:41]
	v_or_b32_e32 v62, 3, v67
	s_and_b64 s[16:17], s[42:43], s[52:53]
	v_cmp_gt_i32_e64 s[40:41], s3, v62
	s_waitcnt lgkmcnt(0)
	v_mfma_f32_16x16x32_bf16 v[56:59], v[176:179], v[192:195], v[56:59]
	s_and_b64 s[40:41], s[16:17], s[40:41]
	v_fma_f32 v62, v63, s23, -v141
	s_movk_i32 s4, 0xff7f
	v_cndmask_b32_e64 v97, v241, v62, s[40:41]
	v_cmp_lt_i32_e64 s[40:41], s4, v108
	s_movk_i32 s4, 0x80
	v_add3_u32 v63, v108, v1, s4
	s_and_b64 s[16:17], s[44:45], s[40:41]
	v_cmp_gt_i32_e64 s[42:43], s3, v63
	s_and_b64 s[42:43], s[16:17], s[42:43]
	v_fma_f32 v56, v56, s23, -v143
	s_and_b64 s[54:55], s[52:53], s[54:55]
	v_fma_f32 v61, v61, s23, -v137
	v_cndmask_b32_e64 v99, v241, v56, s[42:43]
	v_or_b32_e32 v56, 1, v63
	v_cndmask_b32_e64 v61, v241, v61, s[54:55]
	s_and_b64 s[16:17], s[46:47], s[40:41]
	v_cmp_gt_i32_e64 s[42:43], s3, v56
	v_max3_f32 v66, v66, v60, v61
	s_and_b64 s[42:43], s[16:17], s[42:43]
	v_fma_f32 v56, v57, s23, -v145
	v_max3_f32 v62, v66, v87, v97
	v_cndmask_b32_e64 v57, v241, v56, s[42:43]
	v_max3_f32 v56, v62, v99, v57
	v_or_b32_e32 v62, 2, v63
	s_and_b64 s[16:17], s[48:49], s[40:41]
	v_cmp_gt_i32_e64 s[42:43], s3, v62
	s_and_b64 s[42:43], s[16:17], s[42:43]
	v_fma_f32 v58, v58, s23, -v147
	v_cndmask_b32_e64 v101, v241, v58, s[42:43]
	v_or_b32_e32 v58, 3, v63
	s_and_b64 s[16:17], s[50:51], s[40:41]
	v_cmp_gt_i32_e64 s[40:41], s3, v58
	s_and_b64 s[40:41], s[16:17], s[40:41]
	v_fma_f32 v58, v59, s23, -v151
	v_cndmask_b32_e64 v103, v241, v58, s[40:41]
	v_max3_f32 v56, v56, v101, v103
	ds_bpermute_b32 v58, v162, v56
	s_waitcnt lgkmcnt(0)
	v_max_f32_e32 v58, v58, v58
	v_max_f32_e32 v56, v56, v58
	ds_bpermute_b32 v58, v96, v56
	s_waitcnt lgkmcnt(0)
; #define LAS __attribute__((address_space(3)))
; __device__ __forceinline__ s16x4_t trread(LAS unsigned char* p) { return __builtin_amdgcn_ds_read_tr16_b64_v4i16((LAS s16x4_t*)p); }
; __device__ __forceinline__ bf16x8_t cat4(s16x4_t a, s16x4_t b) { return (bf16x8_t){a[0], a[1], a[2], a[3], b[0], b[1], b[2], b[3]}; }
; __device__ __forceinline__ void mixA_compute(bf16* Z, float* LSE, LAS unsigned char* lds, int u, int S, int tid) {
;     ...
;     m = fmaxf(m, __shfl_xor(m, 16)); m = fmaxf(m, __shfl_xor(m, 32));
;     float l = 0.f;
; #pragma unroll
;     for (int t = 0; t < 9; ++t)
; #pragma unroll
;         for (int j = 0; j < 4; ++j) { const float pe = __expf(s[t][j] - m); s[t][j] = pe; l += pe; }
;     l += __shfl_xor(l, 16); l += __shfl_xor(l, 32);
;     f32x4 o[4];
; #pragma unroll
;     for (int dt = 0; dt < 4; ++dt) o[dt] = (f32x4){0.f, 0.f, 0.f, 0.f};
;     LAS unsigned char* vb = lds + A_VOFF + (16 * wt + 4 * q + ((lane >> 2) & 3)) * KPITCH + 8 * (lane & 3);
; #pragma unroll
;     for (int G = 0; G < 5; ++G) {
;         const bf16x8_t pb = packp(s[2 * G], s[2 * G + 1]);
; #pragma unroll
;         for (int dt = 0; dt < 4; ++dt) {
;             const s16x4_t lo = trread(vb + (32 * G) * KPITCH + dt * 32), hi = trread(vb + (32 * G + 16) * KPITCH + dt * 32);
;             o[dt] = __builtin_amdgcn_mfma_f32_16x16x32_bf16(cat4(lo, hi), pb, o[dt], 0, 0, 0);
;         }
	v_max_f32_e32 v58, v58, v58
	v_max_f32_e32 v56, v56, v58
	v_sub_f32_e32 v59, v104, v56
	v_mul_f32_e32 v59, 0x3fb8aa3b, v59
	v_exp_f32_e32 v104, v59
	v_sub_f32_e32 v59, v102, v56
	v_mul_f32_e32 v59, 0x3fb8aa3b, v59
	v_sub_f32_e32 v58, v106, v56
	v_exp_f32_e32 v102, v59
	v_sub_f32_e32 v59, v100, v56
	v_mul_f32_e32 v58, 0x3fb8aa3b, v58
	v_mul_f32_e32 v59, 0x3fb8aa3b, v59
	v_exp_f32_e32 v105, v58
	v_exp_f32_e32 v100, v59
	v_sub_f32_e32 v59, v84, v56
	v_mul_f32_e32 v59, 0x3fb8aa3b, v59
	v_exp_f32_e32 v84, v59
	v_sub_f32_e32 v59, v85, v56
	v_mul_f32_e32 v59, 0x3fb8aa3b, v59
	v_add_f32_e32 v58, 0, v105
	v_exp_f32_e32 v85, v59
	v_sub_f32_e32 v59, v86, v56
	v_add_f32_e32 v58, v104, v58
	v_mul_f32_e32 v59, 0x3fb8aa3b, v59
	v_sub_f32_e32 v3, v3, v56
	v_add_f32_e32 v58, v102, v58
	v_exp_f32_e32 v106, v59
	v_mul_f32_e32 v3, 0x3fb8aa3b, v3
	v_add_f32_e32 v58, v100, v58
	v_exp_f32_e32 v107, v3
	v_add_f32_e32 v58, v84, v58
	v_add_f32_e32 v58, v85, v58
	v_add_f32_e32 v58, v106, v58
	v_add_f32_e32 v3, v107, v58
	v_sub_f32_e32 v58, v80, v56
	v_mul_f32_e32 v58, 0x3fb8aa3b, v58
	v_exp_f32_e32 v108, v58
	v_sub_f32_e32 v58, v81, v56
	v_mul_f32_e32 v58, 0x3fb8aa3b, v58
	v_exp_f32_e32 v109, v58
	v_sub_f32_e32 v58, v82, v56
	v_mul_f32_e32 v58, 0x3fb8aa3b, v58
	v_exp_f32_e32 v110, v58
	v_sub_f32_e32 v58, v83, v56
	v_mul_f32_e32 v58, 0x3fb8aa3b, v58
	v_exp_f32_e32 v111, v58
	v_sub_f32_e32 v58, v76, v56
	v_mul_f32_e32 v58, 0x3fb8aa3b, v58
	v_exp_f32_e32 v112, v58
	v_sub_f32_e32 v58, v77, v56
	v_mul_f32_e32 v58, 0x3fb8aa3b, v58
	v_exp_f32_e32 v113, v58
	v_sub_f32_e32 v58, v78, v56
	v_mul_f32_e32 v58, 0x3fb8aa3b, v58
	v_exp_f32_e32 v114, v58
	v_sub_f32_e32 v58, v79, v56
	v_mul_f32_e32 v58, 0x3fb8aa3b, v58
	v_exp_f32_e32 v115, v58
	v_sub_f32_e32 v58, v72, v56
	v_mul_f32_e32 v58, 0x3fb8aa3b, v58
	v_exp_f32_e32 v66, v58
	v_sub_f32_e32 v58, v73, v56
	v_mul_f32_e32 v58, 0x3fb8aa3b, v58
	v_exp_f32_e32 v67, v58
	v_sub_f32_e32 v58, v74, v56
	v_mul_f32_e32 v58, 0x3fb8aa3b, v58
	v_exp_f32_e32 v116, v58
	v_sub_f32_e32 v58, v75, v56
	v_mul_f32_e32 v58, 0x3fb8aa3b, v58
	v_exp_f32_e32 v117, v58
	v_sub_f32_e32 v58, v68, v56
	v_mul_f32_e32 v58, 0x3fb8aa3b, v58
	v_exp_f32_e32 v118, v58
	v_sub_f32_e32 v58, v69, v56
	v_mul_f32_e32 v58, 0x3fb8aa3b, v58
	v_exp_f32_e32 v69, v58
	v_sub_f32_e32 v58, v70, v56
	v_mul_f32_e32 v58, 0x3fb8aa3b, v58
	v_add_f32_e32 v3, v108, v3
	v_exp_f32_e32 v119, v58
	v_sub_f32_e32 v58, v71, v56
	v_add_f32_e32 v3, v109, v3
	v_mul_f32_e32 v58, 0x3fb8aa3b, v58
	v_add_f32_e32 v3, v110, v3
	v_exp_f32_e32 v120, v58
	v_sub_f32_e32 v58, v64, v56
	v_add_f32_e32 v3, v111, v3
	v_mul_f32_e32 v58, 0x3fb8aa3b, v58
	v_add_f32_e32 v3, v112, v3
	v_exp_f32_e32 v62, v58
	v_sub_f32_e32 v58, v65, v56
	v_add_f32_e32 v3, v113, v3
	v_mul_f32_e32 v58, 0x3fb8aa3b, v58
	v_add_f32_e32 v3, v114, v3
	v_exp_f32_e32 v63, v58
	v_sub_f32_e32 v58, v95, v56
	v_add_f32_e32 v3, v115, v3
	v_mul_f32_e32 v58, 0x3fb8aa3b, v58
	v_add_f32_e32 v3, v66, v3
	v_exp_f32_e32 v64, v58
	v_sub_f32_e32 v58, v93, v56
	v_add_f32_e32 v3, v67, v3
	v_mul_f32_e32 v58, 0x3fb8aa3b, v58
	v_add_f32_e32 v3, v116, v3
	v_exp_f32_e32 v65, v58
	v_sub_f32_e32 v58, v60, v56
	v_add_f32_e32 v3, v117, v3
	v_mul_f32_e32 v58, 0x3fb8aa3b, v58
	v_add_f32_e32 v3, v118, v3
	v_exp_f32_e32 v68, v58
	v_sub_f32_e32 v58, v61, v56
	v_add_f32_e32 v3, v69, v3
	v_mul_f32_e32 v58, 0x3fb8aa3b, v58
	v_add_f32_e32 v3, v119, v3
	v_exp_f32_e32 v121, v58
	v_sub_f32_e32 v58, v87, v56
	v_add_f32_e32 v3, v120, v3
	v_mul_f32_e32 v58, 0x3fb8aa3b, v58
	v_add_f32_e32 v3, v62, v3
	v_exp_f32_e32 v122, v58
	v_sub_f32_e32 v58, v97, v56
	v_add_f32_e32 v3, v63, v3
	v_mul_f32_e32 v58, 0x3fb8aa3b, v58
	v_sub_f32_e32 v57, v57, v56
	v_add_f32_e32 v3, v64, v3
	v_exp_f32_e32 v123, v58
	v_sub_f32_e32 v58, v99, v56
	v_mul_f32_e32 v57, 0x3fb8aa3b, v57
	v_add_f32_e32 v3, v65, v3
	v_mul_f32_e32 v58, 0x3fb8aa3b, v58
	v_exp_f32_e32 v59, v57
	v_sub_f32_e32 v57, v101, v56
	v_add_f32_e32 v3, v68, v3
	v_exp_f32_e32 v58, v58
	v_mul_f32_e32 v57, 0x3fb8aa3b, v57
	v_add_f32_e32 v3, v121, v3
	v_exp_f32_e32 v60, v57
	v_sub_f32_e32 v57, v103, v56
	v_add_f32_e32 v3, v122, v3
	v_mul_f32_e32 v57, 0x3fb8aa3b, v57
	v_add_f32_e32 v3, v123, v3
	v_exp_f32_e32 v61, v57
	v_or_b32_e32 v70, v94, v98
	v_add_f32_e32 v3, v58, v3
	v_mad_u64_u32 v[86:87], s[16:17], v70, s67, v[92:93]
	v_add_f32_e32 v3, v59, v3
	v_cvt_pk_bf16_f32 v70, v105, v104
	v_cvt_pk_bf16_f32 v71, v102, v100
	v_cvt_pk_bf16_f32 v72, v84, v85
	v_cvt_pk_bf16_f32 v73, v106, v107
	ds_read_b64_tr_b16 v[76:77], v86 offset:59904
	ds_read_b64_tr_b16 v[74:75], v86 offset:57600
	ds_read_b64_tr_b16 v[78:79], v86 offset:57632
	ds_read_b64_tr_b16 v[80:81], v86 offset:59936
	v_add_f32_e32 v3, v60, v3
	v_add_f32_e32 v3, v61, v3
	ds_bpermute_b32 v57, v162, v3
	ds_read_b64_tr_b16 v[82:83], v86 offset:57664
	ds_read_b64_tr_b16 v[84:85], v86 offset:59968
	ds_read_b64_tr_b16 v[92:93], v86 offset:57696
	ds_read_b64_tr_b16 v[94:95], v86 offset:60000
	s_waitcnt lgkmcnt(7)
	v_mfma_f32_16x16x32_bf16 v[74:77], v[74:77], v[70:73], 0
	v_add_u32_e32 v87, 0xe100, v86
	s_waitcnt lgkmcnt(4)
	v_add_f32_e32 v3, v3, v57
	ds_bpermute_b32 v57, v96, v3
	v_mfma_f32_16x16x32_bf16 v[78:81], v[78:81], v[70:73], 0
	s_waitcnt lgkmcnt(0)
	v_add_f32_e32 v3, v3, v57
	v_mfma_f32_16x16x32_bf16 v[82:85], v[82:85], v[70:73], 0
	v_rcp_f32_e32 v57, v3
	v_mfma_f32_16x16x32_bf16 v[70:73], v[92:95], v[70:73], 0
	v_cvt_pk_bf16_f32 v92, v108, v109
	v_cvt_pk_bf16_f32 v93, v110, v111
	v_cvt_pk_bf16_f32 v94, v112, v113
	v_cvt_pk_bf16_f32 v95, v114, v115
	ds_read_b64_tr_b16 v[98:99], v86 offset:64512
	ds_read_b64_tr_b16 v[96:97], v86 offset:62208
	ds_read_b64_tr_b16 v[100:101], v86 offset:62240
	s_waitcnt lgkmcnt(1)
; __device__ __forceinline__ unsigned cvt_pk_bf16(float lo, float hi) { unsigned r; asm volatile("v_cvt_pk_bf16_f32 %0, %1, %2" : "=v"(r) : "v"(lo), "v"(hi)); return r; }
; __device__ __forceinline__ s16x4_t trread(LAS unsigned char* p) { return __builtin_amdgcn_ds_read_tr16_b64_v4i16((LAS s16x4_t*)p); }
; __device__ __forceinline__ bf16x8_t cat4(s16x4_t a, s16x4_t b) { return (bf16x8_t){a[0], a[1], a[2], a[3], b[0], b[1], b[2], b[3]}; }
; __device__ __forceinline__ void mixA_compute(bf16* Z, float* LSE, LAS unsigned char* lds, int u, int S, int tid) {
;     ...
; #pragma unroll
;     for (int G = 0; G < 5; ++G) {
;         const bf16x8_t pb = packp(s[2 * G], s[2 * G + 1]);
; #pragma unroll
;         for (int dt = 0; dt < 4; ++dt) {
;             const s16x4_t lo = trread(vb + (32 * G) * KPITCH + dt * 32), hi = trread(vb + (32 * G + 16) * KPITCH + dt * 32);
;             o[dt] = __builtin_amdgcn_mfma_f32_16x16x32_bf16(cat4(lo, hi), pb, o[dt], 0, 0, 0);
;         }
;     }
;     const float inv = __builtin_amdgcn_rcpf(l);
; #pragma unroll
;     for (int dt = 0; dt < 4; ++dt) { uint2 wv; wv.x = pg8::cvt_pk_bf16(o[dt][0] * inv, o[dt][1] * inv); wv.y = pg8::cvt_pk_bf16(o[dt][2] * inv, o[dt][3] * inv);
;         *(uint2*)(qp + dt * 16 + 4 * q) = wv; }
;     if (q == 0) LSE[((size_t)g * MC + tokc) * 8 + h] = m + __logf(l);
	v_mfma_f32_16x16x32_bf16 v[74:77], v[96:99], v[92:95], v[74:77]
	ds_read_b64_tr_b16 v[102:103], v86 offset:64544
	ds_read_b64_tr_b16 v[96:97], v86 offset:62272
	ds_read_b64_tr_b16 v[98:99], v86 offset:64576
	s_waitcnt lgkmcnt(0)
	v_mfma_f32_16x16x32_bf16 v[82:85], v[96:99], v[92:95], v[82:85]
	ds_read_b64_tr_b16 v[96:97], v86 offset:62304
	ds_read_b64_tr_b16 v[98:99], v86 offset:64608
	v_mfma_f32_16x16x32_bf16 v[78:81], v[100:103], v[92:95], v[78:81]
	s_waitcnt lgkmcnt(0)
	v_mfma_f32_16x16x32_bf16 v[70:73], v[96:99], v[92:95], v[70:73]
	v_cvt_pk_bf16_f32 v92, v66, v67
	v_cvt_pk_bf16_f32 v93, v116, v117
	v_cvt_pk_bf16_f32 v94, v118, v69
	v_cvt_pk_bf16_f32 v95, v119, v120
	ds_read_b64_tr_b16 v[98:99], v87 offset:11520
	ds_read_b64_tr_b16 v[96:97], v87 offset:9216
	ds_read_b64_tr_b16 v[100:101], v87 offset:9248
	s_waitcnt lgkmcnt(1)
	v_mfma_f32_16x16x32_bf16 v[74:77], v[96:99], v[92:95], v[74:77]
	ds_read_b64_tr_b16 v[102:103], v87 offset:11552
	ds_read_b64_tr_b16 v[96:97], v87 offset:9280
	ds_read_b64_tr_b16 v[98:99], v87 offset:11584
	s_waitcnt lgkmcnt(0)
	v_mfma_f32_16x16x32_bf16 v[82:85], v[96:99], v[92:95], v[82:85]
	ds_read_b64_tr_b16 v[96:97], v87 offset:9312
	ds_read_b64_tr_b16 v[98:99], v87 offset:11616
	v_cvt_pk_bf16_f32 v62, v62, v63
	v_cvt_pk_bf16_f32 v63, v64, v65
	v_mfma_f32_16x16x32_bf16 v[78:81], v[100:103], v[92:95], v[78:81]
	v_cvt_pk_bf16_f32 v64, v68, v121
	v_cvt_pk_bf16_f32 v65, v122, v123
	s_waitcnt lgkmcnt(0)
	v_mfma_f32_16x16x32_bf16 v[70:73], v[96:99], v[92:95], v[70:73]
	ds_read_b64_tr_b16 v[68:69], v87 offset:16128
	ds_read_b64_tr_b16 v[66:67], v87 offset:13824
	ds_read_b64_tr_b16 v[92:93], v87 offset:13856
	ds_read_b64_tr_b16 v[94:95], v87 offset:16160
	s_waitcnt lgkmcnt(2)
	v_mfma_f32_16x16x32_bf16 v[66:69], v[66:69], v[62:65], v[74:77]
	s_waitcnt lgkmcnt(0)
	v_mfma_f32_16x16x32_bf16 v[74:77], v[92:95], v[62:65], v[78:81]
	s_nop 2
	ds_read_b64_tr_b16 v[78:79], v87 offset:13888
	ds_read_b64_tr_b16 v[80:81], v87 offset:16192
	s_waitcnt lgkmcnt(0)
	v_mfma_f32_16x16x32_bf16 v[78:81], v[78:81], v[62:65], v[82:85]
	s_nop 2
	ds_read_b64_tr_b16 v[82:83], v87 offset:13920
	ds_read_b64_tr_b16 v[84:85], v87 offset:16224
	v_cvt_pk_bf16_f32 v58, v58, v59
	v_cvt_pk_bf16_f32 v59, v60, v61
	s_waitcnt lgkmcnt(0)
	v_mfma_f32_16x16x32_bf16 v[62:65], v[82:85], v[62:65], v[70:73]
	v_cvt_pk_bf16_f32 v60, v0, v0
	v_cvt_pk_bf16_f32 v61, v0, v0
	s_nop 2
	ds_read_b64_tr_b16 v[72:73], v87 offset:20736
	ds_read_b64_tr_b16 v[70:71], v87 offset:18432
	ds_read_b64_tr_b16 v[82:83], v87 offset:18464
	ds_read_b64_tr_b16 v[84:85], v87 offset:20768
	s_waitcnt lgkmcnt(2)
	v_mfma_f32_16x16x32_bf16 v[66:69], v[70:73], v[58:61], v[66:69]
	s_waitcnt lgkmcnt(0)
	v_mfma_f32_16x16x32_bf16 v[70:73], v[82:85], v[58:61], v[74:77]
	s_nop 2
	ds_read_b64_tr_b16 v[74:75], v87 offset:18496
	ds_read_b64_tr_b16 v[76:77], v87 offset:20800
	s_waitcnt lgkmcnt(0)
	v_mfma_f32_16x16x32_bf16 v[74:77], v[74:77], v[58:61], v[78:81]
	s_nop 2
	ds_read_b64_tr_b16 v[78:79], v87 offset:18528
	ds_read_b64_tr_b16 v[80:81], v87 offset:20832
	s_waitcnt lgkmcnt(0)
	v_mfma_f32_16x16x32_bf16 v[58:61], v[78:81], v[58:61], v[62:65]
	s_nop 2
	v_lshlrev_b32_e32 v62, 1, v1
	v_mov_b32_e32 v63, v0
	v_mul_f32_e32 v1, v57, v66
	v_mul_f32_e32 v64, v57, v67
	v_lshl_add_u64 v[62:63], v[88:89], 0, v[62:63]
	v_cvt_pk_bf16_f32 v64, v1, v64
	v_mul_f32_e32 v1, v57, v68
	v_mul_f32_e32 v65, v57, v69
	v_cvt_pk_bf16_f32 v65, v1, v65
	v_lshrrev_b32_e32 v218, 4, v231
	v_lshl_or_b32 v218, v231, 4, v218
	v_and_b32_e32 v218, 0x33, v218
	v_and_or_b32 v218, v231, 12, v218
	v_lshlrev_b32_e32 v218, 2, v218
	ds_bpermute_b32 v220, v218, v62
	ds_bpermute_b32 v221, v218, v63
	ds_bpermute_b32 v64, v218, v64
	ds_bpermute_b32 v65, v218, v65
	s_waitcnt lgkmcnt(0)
	global_store_dwordx2 v[220:221], v[64:65], off
	v_mul_f32_e32 v1, v57, v70
	v_mul_f32_e32 v64, v57, v71
	v_cvt_pk_bf16_f32 v64, v1, v64
	v_mul_f32_e32 v1, v57, v72
	v_mul_f32_e32 v65, v57, v73
	v_cvt_pk_bf16_f32 v65, v1, v65
	ds_bpermute_b32 v64, v218, v64
	ds_bpermute_b32 v65, v218, v65
	s_waitcnt lgkmcnt(0)
	global_store_dwordx2 v[220:221], v[64:65], off offset:32
	v_mul_f32_e32 v1, v57, v74
	v_mul_f32_e32 v64, v57, v75
	v_cvt_pk_bf16_f32 v64, v1, v64
	v_mul_f32_e32 v1, v57, v76
	v_mul_f32_e32 v65, v57, v77
	v_cvt_pk_bf16_f32 v65, v1, v65
	v_mul_f32_e32 v1, v57, v58
	v_mul_f32_e32 v58, v57, v59
	ds_bpermute_b32 v64, v218, v64
	ds_bpermute_b32 v65, v218, v65
	s_waitcnt lgkmcnt(0)
	global_store_dwordx2 v[220:221], v[64:65], off offset:64
	v_cvt_pk_bf16_f32 v58, v1, v58
	v_mul_f32_e32 v1, v57, v60
	v_mul_f32_e32 v57, v57, v61
	v_cvt_pk_bf16_f32 v59, v1, v57
	ds_bpermute_b32 v58, v218, v58
	ds_bpermute_b32 v59, v218, v59
	s_waitcnt lgkmcnt(0)
	global_store_dwordx2 v[220:221], v[58:59], off offset:96
	s_and_saveexec_b64 s[16:17], vcc
	s_mov_b32 s31, 0x3f2aaaab
	s_mov_b32 s33, 0x3f317218
	s_cbranch_execz .LBB0_260
	s_mov_b32 s3, 0x800000
	v_cmp_gt_f32_e32 vcc, s3, v3
	s_mov_b32 s3, 0x3f317217
	s_nop 0
	v_cndmask_b32_e64 v1, 0, 32, vcc
	v_ldexp_f32 v1, v3, v1
	v_log_f32_e32 v1, v1
	v_ashrrev_i32_e32 v3, 31, v2
	v_lshlrev_b64 v[2:3], 5, v[2:3]
	v_lshl_add_u64 v[2:3], s[64:65], 0, v[2:3]
	v_mul_f32_e32 v57, 0x3f317217, v1
	v_fma_f32 v57, v1, s3, -v57
	v_fmac_f32_e32 v57, 0x3377d1cf, v1
	v_fmac_f32_e32 v57, 0x3f317217, v1
	v_cmp_lt_f32_e64 s[40:41], |v1|, s87
	s_nop 1
	v_cndmask_b32_e64 v1, v1, v57, s[40:41]
	v_cndmask_b32_e32 v57, 0, v242, vcc
	v_sub_f32_e32 v1, v1, v57
	v_add_f32_e32 v1, v56, v1
	global_store_dword v[2:3], v1, off

; __device__ __forceinline__ void mixC_mfma_unit(const bf16* Z, bf16* Yc, const float* rpb, LAS unsigned char* lds, int u, int S, int tid) {
;     ...
; #pragma unroll
;     for (int qt = 0; qt < 2; ++qt) {
;     const int qr = 4 * np + 2 * qt + (w >> 2), cb = w & 3, qc = cb * 16 + n;
;     int rs = qr - 4; rs = rs < 0 ? 0 : (rs > rows - 8 ? rows - 8 : rs);
;     int cbs = cb * 16 - 8; cbs = cbs < 0 ? 0 : (cbs > 32 ? 32 : cbs);
;     int cs = qc - 8; cs = cs < 0 ? 0 : (cs > 48 ? 48 : cs);
;     const int tokc = seq0 + qr * 64 + qc;
;     const bf16* qp = Z + (size_t)tokc * NZ + 6144 + h * 64;
;     const bf16x8_t qf0 = *(const bf16x8_t*)(qp + 8 * q), qf1 = *(const bf16x8_t*)(qp + 32 + 8 * q);
;     f32x4 s[16];
; #pragma unroll
;     for (int hf = 0; hf < 2; ++hf) {
;         bf16x8_t kf[8][2];
; #pragma unroll
;         for (int tt = 0; tt < 8; ++tt) { const int t = 8 * hf + tt;
;             const bf16* kp = zk + (size_t)((rs + (t >> 1)) * 64 + cbs + (t & 1) * 16 + n) * NZ + 8 * q;
;             kf[tt][0] = *(const bf16x8_t*)kp; kf[tt][1] = *(const bf16x8_t*)(kp + 32); }
; #pragma unroll
;         for (int tt = 0; tt < 8; ++tt) {
;             f32x4 a = {0.f, 0.f, 0.f, 0.f};
;             a = __builtin_amdgcn_mfma_f32_16x16x32_bf16(kf[tt][0], qf0, a, 0, 0, 0);
;             s[8 * hf + tt] = __builtin_amdgcn_mfma_f32_16x16x32_bf16(kf[tt][1], qf1, a, 0, 0, 0);
;         }
.LBB0_269:
	s_or_b64 exec, exec, s[20:21]
	v_ashrrev_i32_e32 v3, 8, v1
	v_lshrrev_b32_e32 v77, 2, v1
	v_and_b32_e32 v2, 15, v1
	v_add_u32_e32 v88, s22, v3
	v_and_b32_e32 v3, 48, v77
	v_or_b32_e32 v94, v3, v2
	v_med3_u32 v3, v3, 8, 40
	v_add_u32_e32 v85, -8, v3
	v_bfe_u32 v48, v1, 4, 2
	v_or_b32_e32 v89, s4, v94
	v_add_u32_e32 v83, v85, v2
	v_add_u32_e32 v2, -4, v88
	v_readlane_b32 s21, v255, 10
	v_lshlrev_b32_e32 v72, 4, v48
	v_mov_b32_e32 v73, v0
	v_min_i32_e32 v2, s21, v2
	v_cmp_lt_i32_e32 vcc, 3, v88
	v_lshl_add_u32 v76, v88, 6, v89
	v_mov_b64_e32 v[74:75], s[12:13]
	v_lshl_add_u64 v[70:71], s[16:17], 0, v[72:73]
	s_lshl_b32 s70, s3, 1
	v_cndmask_b32_e32 v95, 0, v2, vcc
	v_mad_i64_i32 v[2:3], s[16:17], v76, s66, v[74:75]
	v_lshl_add_u64 v[2:3], v[2:3], 0, s[70:71]
	v_lshl_add_u64 v[30:31], v[2:3], 0, v[72:73]
	s_movk_i32 s20, 0x3000
	v_lshlrev_b32_e32 v101, 6, v95
	v_add_co_u32_e32 v2, vcc, s20, v30
	v_add_u32_e32 v6, v101, v83
	s_nop 0
	v_addc_co_u32_e32 v3, vcc, 0, v31, vcc
	v_mad_i64_i32 v[26:27], s[16:17], v6, s66, v[70:71]
	s_waitcnt lgkmcnt(0)
	s_barrier
	global_load_dwordx4 v[2:5], v[2:3], off
	v_add_u32_e32 v84, 16, v83
	global_load_dwordx4 v[6:9], v[26:27], off
	v_add_u32_e32 v10, v101, v84
	v_mad_i64_i32 v[32:33], s[16:17], v10, s66, v[70:71]
	global_load_dwordx4 v[10:13], v[32:33], off
	v_add_u32_e32 v18, 64, v101
	v_add_u32_e32 v44, 0x80, v101
	v_add_u32_e32 v14, v18, v83
	v_add_u32_e32 v18, v18, v84
	v_add_u32_e32 v22, v44, v83
	v_mad_i64_i32 v[34:35], s[16:17], v14, s66, v[70:71]
	v_mad_i64_i32 v[38:39], s[16:17], v18, s66, v[70:71]
	v_mad_i64_i32 v[42:43], s[16:17], v22, s66, v[70:71]
	global_load_dwordx4 v[14:17], v[34:35], off
	global_load_dwordx4 v[18:21], v[38:39], off
	global_load_dwordx4 v[22:25], v[42:43], off
	s_nop 0
	global_load_dwordx4 v[26:29], v[26:27], off offset:64
	s_mov_b64 s[24:25], 0x3000
	v_lshl_add_u64 v[36:37], v[30:31], 0, s[24:25]
	global_load_dwordx4 v[30:33], v[32:33], off offset:64
	s_nop 0
	global_load_dwordx4 v[78:81], v[36:37], off offset:64
	s_nop 0
	global_load_dwordx4 v[34:37], v[34:35], off offset:64
	s_nop 0
	global_load_dwordx4 v[38:41], v[38:39], off offset:64
	v_add_u32_e32 v46, v44, v84
	v_mad_i64_i32 v[46:47], s[16:17], v46, s66, v[70:71]
	global_load_dwordx4 v[42:45], v[42:43], off offset:64
	v_add_u32_e32 v49, 0xc0, v101
	global_load_dwordx4 v[66:69], v[46:47], off
	v_add_u32_e32 v50, v49, v83
	global_load_dwordx4 v[102:105], v[46:47], off offset:64
	v_mad_i64_i32 v[46:47], s[16:17], v50, s66, v[70:71]
	v_add_u32_e32 v49, v49, v84
	global_load_dwordx4 v[106:109], v[46:47], off
	global_load_dwordx4 v[110:113], v[46:47], off offset:64
	v_mad_i64_i32 v[46:47], s[16:17], v49, s66, v[70:71]
	s_add_u32 s16, s90, s70
	s_addc_u32 s17, s91, 0
	s_waitcnt vmcnt(10)
	v_mfma_f32_16x16x32_bf16 v[22:25], v[22:25], v[2:5], 0
	v_mfma_f32_16x16x32_bf16 v[6:9], v[6:9], v[2:5], 0
	v_mfma_f32_16x16x32_bf16 v[10:13], v[10:13], v[2:5], 0
	s_waitcnt vmcnt(7)
	v_mfma_f32_16x16x32_bf16 v[62:65], v[26:29], v[78:81], v[6:9]
	v_lshlrev_b32_e32 v28, 3, v1
	v_lshlrev_b32_e32 v1, 2, v48
	v_mov_b32_e32 v27, v0
	s_nop 1
	global_load_dwordx4 v[6:9], v[46:47], off
	v_mfma_f32_16x16x32_bf16 v[58:61], v[30:33], v[78:81], v[10:13]
	v_lshlrev_b32_e32 v26, 3, v48
	v_add_u32_e32 v100, v85, v1
	v_and_or_b32 v1, v77, 3, v1
	global_load_dwordx4 v[10:13], v[46:47], off offset:64
	v_mfma_f32_16x16x32_bf16 v[14:17], v[14:17], v[2:5], 0
	v_add_u32_e32 v1, v85, v1
	v_ashrrev_i32_e32 v77, 31, v76
	v_mfma_f32_16x16x32_bf16 v[18:21], v[18:21], v[2:5], 0
	s_waitcnt vmcnt(8)
	v_mfma_f32_16x16x32_bf16 v[54:57], v[34:37], v[78:81], v[14:17]
	s_nop 2
	v_med3_u32 v14, v94, 8, 56
	v_add_u32_e32 v98, -8, v14
	v_add_u32_e32 v99, 8, v14
	v_and_b32_e32 v14, 64, v231
	s_waitcnt vmcnt(7)
	v_mfma_f32_16x16x32_bf16 v[50:53], v[38:41], v[78:81], v[18:21]
	s_nop 2
	v_add_u32_e32 v19, 64, v14
	s_waitcnt vmcnt(5)
	v_mfma_f32_16x16x32_bf16 v[14:17], v[66:69], v[2:5], 0
	v_xor_b32_e32 v18, 16, v231
	v_cmp_lt_i32_e32 vcc, v18, v19
	v_lshl_add_u64 v[66:67], s[16:17], 0, v[26:27]
	s_waitcnt vmcnt(4)
	v_mfma_f32_16x16x32_bf16 v[38:41], v[102:105], v[78:81], v[14:17]
	v_cndmask_b32_e32 v18, v231, v18, vcc
	v_lshlrev_b32_e32 v69, 2, v18
	s_nop 0
	v_xor_b32_e32 v14, 32, v231
	v_cmp_lt_i32_e32 vcc, v14, v19
	s_waitcnt vmcnt(1)
	v_mfma_f32_16x16x32_bf16 v[6:9], v[6:9], v[2:5], 0
	v_cndmask_b32_e32 v18, v231, v14, vcc
	v_lshlrev_b32_e32 v82, 2, v18
	v_mfma_f32_16x16x32_bf16 v[14:17], v[106:109], v[2:5], 0
	v_mfma_f32_16x16x32_bf16 v[34:37], v[110:113], v[78:81], v[14:17]
	v_mfma_f32_16x16x32_bf16 v[46:49], v[42:45], v[78:81], v[22:25]
	s_nop 5
	v_and_b32_e32 v14, 24, v28
	v_add_u32_e32 v68, 0, v14
	s_waitcnt vmcnt(0)
	v_mfma_f32_16x16x32_bf16 v[30:33], v[10:13], v[78:81], v[6:9]
	v_add_u32_e32 v10, 0x100, v101
	v_add_u32_e32 v14, 0x140, v101
	v_add_u32_e32 v26, 0x180, v101
	v_add_u32_e32 v44, 0x1c0, v101
	v_add_u32_e32 v6, v10, v83
	v_add_u32_e32 v10, v10, v84
	v_add_u32_e32 v15, v14, v83
	v_add_u32_e32 v18, v14, v84
	v_add_u32_e32 v22, v26, v83
	v_add_u32_e32 v26, v26, v84
	v_add_u32_e32 v45, v44, v83
	v_add_u32_e32 v44, v44, v84
	v_mad_i64_i32 v[42:43], s[16:17], v6, s66, v[70:71]
	v_mad_i64_i32 v[86:87], s[16:17], v10, s66, v[70:71]
	v_mad_i64_i32 v[92:93], s[16:17], v15, s66, v[70:71]
	v_mad_i64_i32 v[96:97], s[16:17], v18, s66, v[70:71]
	v_mad_i64_i32 v[118:119], s[16:17], v22, s66, v[70:71]
	v_mad_i64_i32 v[120:121], s[16:17], v26, s66, v[70:71]
	v_mad_i64_i32 v[122:123], s[16:17], v45, s66, v[70:71]
	v_mad_i64_i32 v[124:125], s[16:17], v44, s66, v[70:71]
	global_load_dwordx4 v[6:9], v[42:43], off
	global_load_dwordx4 v[10:13], v[86:87], off
	global_load_dwordx4 v[14:17], v[92:93], off
	global_load_dwordx4 v[18:21], v[96:97], off
	global_load_dwordx4 v[102:105], v[118:119], off
	global_load_dwordx4 v[106:109], v[120:121], off
	global_load_dwordx4 v[110:113], v[122:123], off
	global_load_dwordx4 v[114:117], v[124:125], off
	global_load_dwordx4 v[180:183], v[42:43], off offset:64
	global_load_dwordx4 v[184:187], v[86:87], off offset:64
	global_load_dwordx4 v[188:191], v[92:93], off offset:64
	global_load_dwordx4 v[192:195], v[96:97], off offset:64
	global_load_dwordx4 v[202:205], v[118:119], off offset:64
	global_load_dwordx4 v[206:209], v[120:121], off offset:64
	global_load_dwordx4 v[214:217], v[124:125], off offset:64
	global_load_dwordx4 v[210:213], v[122:123], off offset:64
	s_waitcnt vmcnt(15)
; #define LAS __attribute__((address_space(3)))
; __device__ __forceinline__ void mixC_mfma_unit(const bf16* Z, bf16* Yc, const float* rpb, LAS unsigned char* lds, int u, int S, int tid) {
;     ...
;     for (int hf = 0; hf < 2; ++hf) {
;         bf16x8_t kf[8][2];
; #pragma unroll
;         for (int tt = 0; tt < 8; ++tt) { const int t = 8 * hf + tt;
;             const bf16* kp = zk + (size_t)((rs + (t >> 1)) * 64 + cbs + (t & 1) * 16 + n) * NZ + 8 * q;
;             kf[tt][0] = *(const bf16x8_t*)kp; kf[tt][1] = *(const bf16x8_t*)(kp + 32); }
; #pragma unroll
;         for (int tt = 0; tt < 8; ++tt) {
;             f32x4 a = {0.f, 0.f, 0.f, 0.f};
;             a = __builtin_amdgcn_mfma_f32_16x16x32_bf16(kf[tt][0], qf0, a, 0, 0, 0);
;             s[8 * hf + tt] = __builtin_amdgcn_mfma_f32_16x16x32_bf16(kf[tt][1], qf1, a, 0, 0, 0);
;         }
;         __builtin_amdgcn_sched_barrier(0);
;     }
;     const LAS float* rbp = (const LAS float*)(lds + C_ROWS * KPITCH);
;     float m = -1e30f;
; #pragma unroll
;     for (int t = 0; t < 16; ++t)
; #pragma unroll
;         for (int j = 0; j < 4; ++j) {
;             const int kr = rs + (t >> 1), kc = cbs + (t & 1) * 16 + 4 * q + j;
;             const bool valid = (kc >= cs) && (kc < cs + 16);
;             int dc = kc - qc + 15; dc = dc < 0 ? 0 : (dc > 30 ? 30 : dc);
;             const float sc = s[t][j] * 0.125f + rbp[(kr - qr + 7) * 31 + dc];
;             s[t][j] = valid ? sc : -1e30f; m = fmaxf(m, s[t][j]);
;         }
	v_mfma_f32_16x16x32_bf16 v[6:9], v[6:9], v[2:5], 0
	s_waitcnt vmcnt(14)
	v_mfma_f32_16x16x32_bf16 v[10:13], v[10:13], v[2:5], 0
	s_waitcnt vmcnt(13)
	v_mfma_f32_16x16x32_bf16 v[14:17], v[14:17], v[2:5], 0
	s_waitcnt vmcnt(12)
	v_mfma_f32_16x16x32_bf16 v[18:21], v[18:21], v[2:5], 0
	s_waitcnt vmcnt(11)
	v_mfma_f32_16x16x32_bf16 v[102:105], v[102:105], v[2:5], 0
	s_waitcnt vmcnt(10)
	v_mfma_f32_16x16x32_bf16 v[106:109], v[106:109], v[2:5], 0
	s_waitcnt vmcnt(9)
	v_mfma_f32_16x16x32_bf16 v[110:113], v[110:113], v[2:5], 0
	s_waitcnt vmcnt(8)
	v_mfma_f32_16x16x32_bf16 v[114:117], v[114:117], v[2:5], 0
	s_waitcnt vmcnt(7)
	v_mfma_f32_16x16x32_bf16 v[42:45], v[180:183], v[78:81], v[6:9]
	s_waitcnt vmcnt(6)
	v_mfma_f32_16x16x32_bf16 v[26:29], v[184:187], v[78:81], v[10:13]
	s_waitcnt vmcnt(5)
	v_mfma_f32_16x16x32_bf16 v[22:25], v[188:191], v[78:81], v[14:17]
	s_waitcnt vmcnt(4)
	v_mfma_f32_16x16x32_bf16 v[18:21], v[192:195], v[78:81], v[18:21]
	s_waitcnt vmcnt(3)
	v_mfma_f32_16x16x32_bf16 v[14:17], v[202:205], v[78:81], v[102:105]
	s_waitcnt vmcnt(2)
	v_mfma_f32_16x16x32_bf16 v[6:9], v[206:209], v[78:81], v[106:109]
	s_waitcnt vmcnt(1)
	v_mfma_f32_16x16x32_bf16 v[10:13], v[214:217], v[78:81], v[114:117]
	s_waitcnt vmcnt(0)
	v_mfma_f32_16x16x32_bf16 v[2:5], v[210:213], v[78:81], v[110:113]
	v_sub_u32_e32 v78, v95, v88
	s_movk_i32 s4, 0x7c
	v_mul_lo_u32 v78, v78, s4
	s_add_i32 s3, 0, 0x18c00
	v_add_u32_e32 v101, s3, v78
	v_sub_u32_e32 v78, v100, v94
	v_med3_i32 v78, v78, -15, 15
	v_lshlrev_b32_e32 v85, 2, v78
	v_add_u32_e32 v110, v101, v85
	v_add_u32_e32 v78, 0x200, v110
	ds_read2_b32 v[78:79], v78 offset0:104 offset1:135
	v_cmp_ge_u32_e32 vcc, v100, v98
	v_cmp_lt_u32_e64 s[40:41], v100, v99
	s_and_b64 vcc, vcc, s[40:41]
	s_mov_b32 s15, 0xf149f2ca
	s_waitcnt lgkmcnt(0)
	v_fmamk_f32 v62, v62, 0x3e000000, v78
	v_cndmask_b32_e32 v96, v241, v62, vcc
	v_or_b32_e32 v62, 1, v100
	v_cmp_ge_u32_e64 s[40:41], v62, v98
	v_cmp_lt_u32_e64 s[42:43], v62, v99
	v_sub_u32_e32 v62, v62, v94
	v_med3_i32 v62, v62, -15, 15
	v_lshlrev_b32_e32 v78, 2, v62
	v_add_u32_e32 v111, v101, v78
	v_add_u32_e32 v62, 0x200, v111
	ds_read2_b32 v[80:81], v62 offset0:104 offset1:135
	s_and_b64 s[40:41], s[40:41], s[42:43]
	v_fmac_f32_e32 v79, 0x3e000000, v54
	s_waitcnt lgkmcnt(0)
	v_fmamk_f32 v62, v63, 0x3e000000, v80
	v_cndmask_b32_e64 v97, v241, v62, s[40:41]
	v_or_b32_e32 v62, 2, v100
	v_cmp_ge_u32_e64 s[42:43], v62, v98
	v_cmp_lt_u32_e64 s[44:45], v62, v99
	v_sub_u32_e32 v62, v62, v94
	v_med3_i32 v62, v62, -15, 15
	v_lshlrev_b32_e32 v80, 2, v62
	v_add_u32_e32 v112, v101, v80
	v_add_u32_e32 v62, 0x200, v112
	ds_read2_b32 v[62:63], v62 offset0:104 offset1:135
	s_and_b64 s[42:43], s[42:43], s[44:45]
	v_max3_f32 v87, v96, s15, v97
	v_fmac_f32_e32 v81, 0x3e000000, v55
	s_waitcnt lgkmcnt(0)
	v_fmamk_f32 v62, v64, 0x3e000000, v62
	v_or_b32_e32 v64, 3, v100
	v_cmp_ge_u32_e64 s[44:45], v64, v98
	v_cmp_lt_u32_e64 s[46:47], v64, v99
	v_sub_u32_e32 v64, v64, v94
	v_med3_i32 v64, v64, -15, 15
	v_lshlrev_b32_e32 v86, 2, v64
	v_add_u32_e32 v113, v101, v86
	v_add_u32_e32 v64, 0x200, v113
	ds_read2_b32 v[102:103], v64 offset0:104 offset1:135
	s_and_b64 s[44:45], s[44:45], s[46:47]
	v_cndmask_b32_e64 v62, v241, v62, s[42:43]
	v_fmac_f32_e32 v63, 0x3e000000, v56
	v_cndmask_b32_e64 v54, v241, v63, s[42:43]
	s_waitcnt lgkmcnt(0)
	v_fmamk_f32 v64, v65, 0x3e000000, v102
	v_cndmask_b32_e64 v64, v241, v64, s[44:45]
	v_max3_f32 v65, v87, v62, v64
	v_add_u32_e32 v87, 16, v100
	v_cmp_ge_u32_e64 s[46:47], v87, v98
	v_cmp_lt_u32_e64 s[48:49], v87, v99
	v_sub_u32_e32 v87, v87, v94
	v_med3_i32 v87, v87, -15, 15
	v_lshlrev_b32_e32 v87, 2, v87
	v_add_u32_e32 v102, v101, v87
	v_add_u32_e32 v92, 0x200, v102
	ds_read2_b32 v[104:105], v92 offset0:104 offset1:135
	v_add_u32_e32 v92, 17, v100
	s_and_b64 s[46:47], s[46:47], s[48:49]
	v_cmp_ge_u32_e64 s[48:49], v92, v98
	v_cmp_lt_u32_e64 s[50:51], v92, v99
	v_sub_u32_e32 v92, v92, v94
	v_med3_i32 v92, v92, -15, 15
	v_lshlrev_b32_e32 v92, 2, v92
	v_add_u32_e32 v114, v101, v92
	v_add_u32_e32 v93, 0x200, v114
	ds_read2_b32 v[106:107], v93 offset0:104 offset1:135
	s_waitcnt lgkmcnt(1)
	v_fmamk_f32 v58, v58, 0x3e000000, v104
	s_and_b64 s[48:49], s[48:49], s[50:51]
	v_cndmask_b32_e64 v58, v241, v58, s[46:47]
	v_fmac_f32_e32 v103, 0x3e000000, v57
	s_waitcnt lgkmcnt(0)
	v_fmamk_f32 v59, v59, 0x3e000000, v106
	v_cndmask_b32_e64 v59, v241, v59, s[48:49]
	v_max3_f32 v104, v65, v58, v59
	v_add_u32_e32 v65, 18, v100
	v_cmp_ge_u32_e64 s[50:51], v65, v98
	v_cmp_lt_u32_e64 s[52:53], v65, v99
	v_sub_u32_e32 v65, v65, v94
	v_med3_i32 v65, v65, -15, 15
	v_lshlrev_b32_e32 v93, 2, v65
	v_add_u32_e32 v116, v101, v93
	v_add_u32_e32 v65, 0x200, v116
	ds_read2_b32 v[108:109], v65 offset0:104 offset1:135
	s_and_b64 s[50:51], s[50:51], s[52:53]
	v_cndmask_b32_e64 v55, v241, v103, s[44:45]
	v_fmac_f32_e32 v105, 0x3e000000, v50
	v_fmac_f32_e32 v107, 0x3e000000, v51
	s_waitcnt lgkmcnt(0)
	v_fmamk_f32 v60, v60, 0x3e000000, v108
	v_cndmask_b32_e64 v65, v241, v60, s[50:51]
	v_add_u32_e32 v60, 19, v100
	v_cmp_ge_u32_e64 s[52:53], v60, v98
	v_cmp_lt_u32_e64 s[54:55], v60, v99
	v_sub_u32_e32 v60, v60, v94
	v_med3_i32 v60, v60, -15, 15
	v_lshlrev_b32_e32 v94, 2, v60
	v_add_u32_e32 v60, v101, v94
	v_add_u32_e32 v98, 0x200, v60
	ds_read2_b32 v[100:101], v98 offset0:104 offset1:135
	s_and_b64 s[52:53], s[52:53], s[54:55]
	v_cndmask_b32_e32 v99, v241, v79, vcc
	v_cndmask_b32_e64 v98, v241, v81, s[40:41]
	v_cndmask_b32_e64 v57, v241, v107, s[48:49]
	s_waitcnt lgkmcnt(0)
; __device__ __forceinline__ void mixC_mfma_unit(const bf16* Z, bf16* Yc, const float* rpb, LAS unsigned char* lds, int u, int S, int tid) {
;     ...
;     for (int t = 0; t < 16; ++t)
; #pragma unroll
;         for (int j = 0; j < 4; ++j) {
;             const int kr = rs + (t >> 1), kc = cbs + (t & 1) * 16 + 4 * q + j;
;             const bool valid = (kc >= cs) && (kc < cs + 16);
;             int dc = kc - qc + 15; dc = dc < 0 ? 0 : (dc > 30 ? 30 : dc);
;             const float sc = s[t][j] * 0.125f + rbp[(kr - qr + 7) * 31 + dc];
;             s[t][j] = valid ? sc : -1e30f; m = fmaxf(m, s[t][j]);
;         }
	v_fmamk_f32 v61, v61, 0x3e000000, v100
	v_cndmask_b32_e64 v100, v241, v61, s[52:53]
	v_max3_f32 v61, v104, v65, v100
	v_max3_f32 v61, v61, v99, v98
	v_max3_f32 v56, v61, v54, v55
	v_cndmask_b32_e64 v61, v241, v105, s[46:47]
	v_fmac_f32_e32 v109, 0x3e000000, v52
	v_fmac_f32_e32 v101, 0x3e000000, v53
	v_max3_f32 v56, v56, v61, v57
	v_cndmask_b32_e64 v51, v241, v109, s[50:51]
	v_cndmask_b32_e64 v50, v241, v101, s[52:53]
	v_max3_f32 v53, v56, v51, v50
	v_add_u32_e32 v56, 0x400, v110
	v_add_u32_e32 v63, 0x400, v111
	ds_read2_b32 v[104:105], v56 offset0:38 offset1:69
	ds_read2_b32 v[106:107], v63 offset0:38 offset1:69
	v_add_u32_e32 v81, 0x400, v113
	ds_read2_b32 v[110:111], v81 offset0:38 offset1:69
	v_add_u32_e32 v79, 0x400, v112
	s_waitcnt lgkmcnt(2)
	v_fmamk_f32 v46, v46, 0x3e000000, v104
	s_waitcnt lgkmcnt(1)
	v_fmamk_f32 v47, v47, 0x3e000000, v106
	v_cndmask_b32_e32 v46, v241, v46, vcc
	v_cndmask_b32_e64 v52, v241, v47, s[40:41]
	s_waitcnt lgkmcnt(0)
	v_fmamk_f32 v49, v49, 0x3e000000, v110
	v_max3_f32 v47, v53, v46, v52
	ds_read2_b32 v[108:109], v79 offset0:38 offset1:69
	v_cndmask_b32_e64 v53, v241, v49, s[44:45]
	v_add_u32_e32 v49, 0x400, v102
	v_add_u32_e32 v122, 0x400, v114
	ds_read2_b32 v[112:113], v49 offset0:38 offset1:69
	ds_read2_b32 v[114:115], v122 offset0:38 offset1:69
	s_waitcnt lgkmcnt(2)
	v_fmamk_f32 v48, v48, 0x3e000000, v108
	v_cndmask_b32_e64 v48, v241, v48, s[42:43]
	v_max3_f32 v47, v47, v48, v53
	s_waitcnt lgkmcnt(1)
	v_fmamk_f32 v38, v38, 0x3e000000, v112
	s_waitcnt lgkmcnt(0)
	v_fmamk_f32 v39, v39, 0x3e000000, v114
	v_cndmask_b32_e64 v38, v241, v38, s[46:47]
	v_cndmask_b32_e64 v103, v241, v39, s[48:49]
	v_max3_f32 v39, v47, v38, v103
	v_add_u32_e32 v47, 0x400, v116
	ds_read2_b32 v[116:117], v47 offset0:38 offset1:69
	v_add_u32_e32 v60, 0x400, v60
	ds_read2_b32 v[118:119], v60 offset0:38 offset1:69
	v_fmac_f32_e32 v109, 0x3e000000, v36
	v_cndmask_b32_e64 v101, v241, v109, s[42:43]
	s_waitcnt lgkmcnt(1)
	v_fmamk_f32 v40, v40, 0x3e000000, v116
	v_cndmask_b32_e64 v102, v241, v40, s[50:51]
	s_waitcnt lgkmcnt(0)
	v_fmamk_f32 v40, v41, 0x3e000000, v118
	v_fmac_f32_e32 v111, 0x3e000000, v37
	ds_read2_b32 v[108:109], v56 offset0:100 offset1:131
	v_cndmask_b32_e64 v106, v241, v40, s[52:53]
	v_cndmask_b32_e64 v40, v241, v111, s[44:45]
	ds_read2_b32 v[110:111], v63 offset0:100 offset1:131
	v_fmac_f32_e32 v105, 0x3e000000, v34
	v_fmac_f32_e32 v107, 0x3e000000, v35
	v_max3_f32 v39, v39, v102, v106
	v_cndmask_b32_e32 v105, v241, v105, vcc
	v_cndmask_b32_e64 v104, v241, v107, s[40:41]
	v_max3_f32 v34, v39, v105, v104
	v_fmac_f32_e32 v113, 0x3e000000, v30
	v_fmac_f32_e32 v115, 0x3e000000, v31
	v_max3_f32 v34, v34, v101, v40
	v_cndmask_b32_e64 v37, v241, v113, s[46:47]
	v_cndmask_b32_e64 v35, v241, v115, s[48:49]
	v_fmac_f32_e32 v119, 0x3e000000, v33
	s_waitcnt lgkmcnt(1)
	v_fmamk_f32 v33, v42, 0x3e000000, v108
	v_max3_f32 v31, v34, v37, v35
	v_cndmask_b32_e32 v34, v241, v33, vcc
	s_waitcnt lgkmcnt(0)
	v_fmamk_f32 v33, v43, 0x3e000000, v110
	ds_read2_b32 v[42:43], v79 offset0:100 offset1:131
	v_fmac_f32_e32 v117, 0x3e000000, v32
	ds_read2_b32 v[112:113], v81 offset0:100 offset1:131
	v_cndmask_b32_e64 v32, v241, v117, s[50:51]
	v_cndmask_b32_e64 v30, v241, v119, s[52:53]
	ds_read2_b32 v[114:115], v49 offset0:100 offset1:131
	ds_read2_b32 v[116:117], v122 offset0:100 offset1:131
	ds_read2_b32 v[118:119], v47 offset0:100 offset1:131
	ds_read2_b32 v[120:121], v60 offset0:100 offset1:131
	v_cndmask_b32_e64 v36, v241, v33, s[40:41]
	s_waitcnt lgkmcnt(5)
	v_fmamk_f32 v33, v44, 0x3e000000, v42
	v_max3_f32 v31, v31, v32, v30
	v_cndmask_b32_e64 v42, v241, v33, s[42:43]
	s_waitcnt lgkmcnt(4)
	v_fmamk_f32 v33, v45, 0x3e000000, v112
	v_max3_f32 v31, v31, v34, v36
	v_cndmask_b32_e64 v44, v241, v33, s[44:45]
	s_waitcnt lgkmcnt(3)
	v_fmamk_f32 v26, v26, 0x3e000000, v114
	s_waitcnt lgkmcnt(2)
	v_fmamk_f32 v27, v27, 0x3e000000, v116
	s_waitcnt lgkmcnt(1)
	v_fmamk_f32 v28, v28, 0x3e000000, v118
	v_max3_f32 v31, v31, v42, v44
	v_cndmask_b32_e64 v26, v241, v26, s[46:47]
	v_cndmask_b32_e64 v107, v241, v27, s[48:49]
	v_cndmask_b32_e64 v108, v241, v28, s[50:51]
	s_waitcnt lgkmcnt(0)
	v_fmamk_f32 v28, v29, 0x3e000000, v120
	v_max3_f32 v27, v31, v26, v107
	v_cndmask_b32_e64 v110, v241, v28, s[52:53]
	v_fmac_f32_e32 v109, 0x3e000000, v22
	v_fmac_f32_e32 v111, 0x3e000000, v23
	v_max3_f32 v27, v27, v108, v110
	v_cndmask_b32_e32 v109, v241, v109, vcc
	v_cndmask_b32_e64 v29, v241, v111, s[40:41]
	v_fmac_f32_e32 v43, 0x3e000000, v24
	v_fmac_f32_e32 v113, 0x3e000000, v25
	v_fmac_f32_e32 v115, 0x3e000000, v18
	v_max3_f32 v22, v27, v109, v29
	v_cndmask_b32_e64 v24, v241, v43, s[42:43]
	v_cndmask_b32_e64 v28, v241, v113, s[44:45]
	v_cndmask_b32_e64 v23, v241, v115, s[46:47]
	v_fmac_f32_e32 v117, 0x3e000000, v19
	v_fmac_f32_e32 v119, 0x3e000000, v20
	ds_read2_b32 v[112:113], v56 offset0:162 offset1:193
	ds_read2_b32 v[114:115], v63 offset0:162 offset1:193
	v_max3_f32 v25, v22, v24, v28
	v_cndmask_b32_e64 v22, v241, v117, s[48:49]
	v_cndmask_b32_e64 v19, v241, v119, s[50:51]
	v_fmac_f32_e32 v121, 0x3e000000, v21
	ds_read2_b32 v[116:117], v79 offset0:162 offset1:193
	ds_read2_b32 v[118:119], v81 offset0:162 offset1:193
	v_cndmask_b32_e64 v18, v241, v121, s[52:53]
	ds_read2_b32 v[120:121], v49 offset0:162 offset1:193
	ds_read2_b32 v[122:123], v122 offset0:162 offset1:193
	ds_read2_b32 v[124:125], v47 offset0:162 offset1:193
	ds_read2_b32 v[126:127], v60 offset0:162 offset1:193
	v_max3_f32 v25, v25, v23, v22
	s_waitcnt lgkmcnt(7)
	v_fmamk_f32 v14, v14, 0x3e000000, v112
	s_waitcnt lgkmcnt(6)
; __device__ __forceinline__ void mixC_mfma_unit(const bf16* Z, bf16* Yc, const float* rpb, LAS unsigned char* lds, int u, int S, int tid) {
;     ...
;     for (int t = 0; t < 16; ++t)
; #pragma unroll
;         for (int j = 0; j < 4; ++j) {
;             const int kr = rs + (t >> 1), kc = cbs + (t & 1) * 16 + 4 * q + j;
;             const bool valid = (kc >= cs) && (kc < cs + 16);
;             int dc = kc - qc + 15; dc = dc < 0 ? 0 : (dc > 30 ? 30 : dc);
;             const float sc = s[t][j] * 0.125f + rbp[(kr - qr + 7) * 31 + dc];
;             s[t][j] = valid ? sc : -1e30f; m = fmaxf(m, s[t][j]);
;         }
;     m = fmaxf(m, __shfl_xor(m, 16)); m = fmaxf(m, __shfl_xor(m, 32));
;     float l = 0.f;
; #pragma unroll
;     for (int t = 0; t < 16; ++t)
; #pragma unroll
;         for (int j = 0; j < 4; ++j) { const float pe = __expf(s[t][j] - m); s[t][j] = pe; l += pe; }
	v_fmamk_f32 v15, v15, 0x3e000000, v114
	v_max3_f32 v20, v25, v19, v18
	v_cndmask_b32_e32 v14, v241, v14, vcc
	v_cndmask_b32_e64 v15, v241, v15, s[40:41]
	s_waitcnt lgkmcnt(5)
	v_fmamk_f32 v16, v16, 0x3e000000, v116
	s_waitcnt lgkmcnt(4)
	v_fmamk_f32 v17, v17, 0x3e000000, v118
	v_max3_f32 v20, v20, v14, v15
	v_cndmask_b32_e64 v16, v241, v16, s[42:43]
	v_cndmask_b32_e64 v21, v241, v17, s[44:45]
	s_waitcnt lgkmcnt(3)
	v_fmamk_f32 v6, v6, 0x3e000000, v120
	s_waitcnt lgkmcnt(2)
	v_fmamk_f32 v7, v7, 0x3e000000, v122
	v_max3_f32 v17, v20, v16, v21
	v_cndmask_b32_e64 v6, v241, v6, s[46:47]
	v_cndmask_b32_e64 v7, v241, v7, s[48:49]
	s_waitcnt lgkmcnt(1)
	v_fmamk_f32 v8, v8, 0x3e000000, v124
	s_waitcnt lgkmcnt(0)
	v_fmamk_f32 v9, v9, 0x3e000000, v126
	v_max3_f32 v17, v17, v6, v7
	v_cndmask_b32_e64 v8, v241, v8, s[50:51]
	v_cndmask_b32_e64 v112, v241, v9, s[52:53]
	v_fmac_f32_e32 v113, 0x3e000000, v2
	v_fmac_f32_e32 v115, 0x3e000000, v3
	v_max3_f32 v17, v17, v8, v112
	v_cndmask_b32_e32 v113, v241, v113, vcc
	v_cndmask_b32_e64 v9, v241, v115, s[40:41]
	v_fmac_f32_e32 v117, 0x3e000000, v4
	v_fmac_f32_e32 v119, 0x3e000000, v5
	v_max3_f32 v2, v17, v113, v9
	v_cndmask_b32_e64 v111, v241, v117, s[42:43]
	v_cndmask_b32_e64 v5, v241, v119, s[44:45]
	v_fmac_f32_e32 v121, 0x3e000000, v10
	v_fmac_f32_e32 v123, 0x3e000000, v11
	v_max3_f32 v2, v2, v111, v5
	v_cndmask_b32_e64 v10, v241, v121, s[46:47]
	v_cndmask_b32_e64 v3, v241, v123, s[48:49]
	v_fmac_f32_e32 v125, 0x3e000000, v12
	v_fmac_f32_e32 v127, 0x3e000000, v13
	v_max3_f32 v11, v2, v10, v3
	v_cndmask_b32_e64 v4, v241, v125, s[50:51]
	v_cndmask_b32_e64 v2, v241, v127, s[52:53]
	v_max3_f32 v11, v11, v4, v2
	ds_bpermute_b32 v12, v69, v11
	s_waitcnt lgkmcnt(0)
	v_max_f32_e32 v12, v12, v12
	v_max_f32_e32 v11, v11, v12
	ds_bpermute_b32 v12, v82, v11
	s_waitcnt lgkmcnt(0)
	v_max_f32_e32 v12, v12, v12
	v_max_f32_e32 v13, v11, v12
	v_sub_f32_e32 v12, v97, v13
	v_mul_f32_e32 v12, 0x3fb8aa3b, v12
	v_exp_f32_e32 v60, v12
	v_sub_f32_e32 v12, v62, v13
	v_mul_f32_e32 v12, 0x3fb8aa3b, v12
	v_exp_f32_e32 v62, v12
	v_sub_f32_e32 v12, v64, v13
	v_mul_f32_e32 v12, 0x3fb8aa3b, v12
	v_exp_f32_e32 v63, v12
	v_sub_f32_e32 v12, v58, v13
	v_mul_f32_e32 v12, 0x3fb8aa3b, v12
	v_exp_f32_e32 v79, v12
	v_sub_f32_e32 v12, v59, v13
	v_mul_f32_e32 v12, 0x3fb8aa3b, v12
	v_exp_f32_e32 v81, v12
	v_sub_f32_e32 v12, v65, v13
	v_mul_f32_e32 v12, 0x3fb8aa3b, v12
	v_sub_f32_e32 v11, v96, v13
	v_exp_f32_e32 v96, v12
	v_sub_f32_e32 v12, v100, v13
	v_mul_f32_e32 v12, 0x3fb8aa3b, v12
	v_exp_f32_e32 v97, v12
	v_sub_f32_e32 v12, v99, v13
	v_mul_f32_e32 v12, 0x3fb8aa3b, v12
	v_exp_f32_e32 v47, v12
	v_sub_f32_e32 v12, v98, v13
	v_mul_f32_e32 v12, 0x3fb8aa3b, v12
	v_exp_f32_e32 v49, v12
	v_sub_f32_e32 v12, v54, v13
	v_mul_f32_e32 v12, 0x3fb8aa3b, v12
	v_exp_f32_e32 v54, v12
	v_sub_f32_e32 v12, v55, v13
	v_mul_f32_e32 v12, 0x3fb8aa3b, v12
	v_exp_f32_e32 v55, v12
	v_sub_f32_e32 v12, v61, v13
	v_mul_f32_e32 v12, 0x3fb8aa3b, v12
	v_exp_f32_e32 v58, v12
	v_sub_f32_e32 v12, v57, v13
	v_mul_f32_e32 v12, 0x3fb8aa3b, v12
	v_exp_f32_e32 v61, v12
	v_sub_f32_e32 v12, v51, v13
	v_mul_f32_e32 v12, 0x3fb8aa3b, v12
	v_exp_f32_e32 v64, v12
	v_sub_f32_e32 v12, v50, v13
	v_mul_f32_e32 v12, 0x3fb8aa3b, v12
	v_exp_f32_e32 v65, v12
	v_sub_f32_e32 v12, v46, v13
	v_mul_f32_e32 v12, 0x3fb8aa3b, v12
	v_exp_f32_e32 v39, v12
	v_sub_f32_e32 v12, v52, v13
	v_mul_f32_e32 v12, 0x3fb8aa3b, v12
	v_exp_f32_e32 v41, v12
	v_sub_f32_e32 v12, v48, v13
	v_mul_f32_e32 v12, 0x3fb8aa3b, v12
	v_exp_f32_e32 v46, v12
	v_sub_f32_e32 v12, v53, v13
	v_mul_f32_e32 v12, 0x3fb8aa3b, v12
	v_exp_f32_e32 v48, v12
	v_sub_f32_e32 v12, v38, v13
	v_mul_f32_e32 v12, 0x3fb8aa3b, v12
	v_exp_f32_e32 v51, v12
	v_sub_f32_e32 v12, v103, v13
	v_mul_f32_e32 v12, 0x3fb8aa3b, v12
	v_exp_f32_e32 v53, v12
	v_sub_f32_e32 v12, v102, v13
	v_mul_f32_e32 v12, 0x3fb8aa3b, v12
	v_exp_f32_e32 v57, v12
	v_sub_f32_e32 v12, v106, v13
	v_mul_f32_e32 v12, 0x3fb8aa3b, v12
	v_exp_f32_e32 v59, v12
	v_sub_f32_e32 v12, v105, v13
	v_mul_f32_e32 v12, 0x3fb8aa3b, v12
	v_exp_f32_e32 v31, v12
	v_sub_f32_e32 v12, v104, v13
	v_mul_f32_e32 v12, 0x3fb8aa3b, v12
	v_mul_f32_e32 v11, 0x3fb8aa3b, v11
	v_exp_f32_e32 v33, v12
	v_sub_f32_e32 v12, v101, v13
	v_exp_f32_e32 v56, v11
	v_mul_f32_e32 v12, 0x3fb8aa3b, v12
	v_exp_f32_e32 v38, v12
	v_sub_f32_e32 v12, v40, v13
	v_mul_f32_e32 v12, 0x3fb8aa3b, v12
	v_exp_f32_e32 v40, v12
	v_sub_f32_e32 v12, v37, v13
	v_add_f32_e32 v11, 0, v56
	v_mul_f32_e32 v12, 0x3fb8aa3b, v12
	v_add_f32_e32 v11, v60, v11
	v_exp_f32_e32 v43, v12
	v_sub_f32_e32 v12, v35, v13
	v_add_f32_e32 v11, v62, v11
	v_mul_f32_e32 v12, 0x3fb8aa3b, v12
	v_add_f32_e32 v11, v63, v11
	v_exp_f32_e32 v45, v12
	v_sub_f32_e32 v12, v32, v13
	v_add_f32_e32 v11, v79, v11
	v_mul_f32_e32 v12, 0x3fb8aa3b, v12
	v_add_f32_e32 v11, v81, v11
	v_exp_f32_e32 v50, v12
	v_sub_f32_e32 v12, v30, v13
	v_add_f32_e32 v11, v96, v11
	v_mul_f32_e32 v12, 0x3fb8aa3b, v12
	v_add_f32_e32 v11, v97, v11
	v_exp_f32_e32 v52, v12
	v_sub_f32_e32 v12, v34, v13
	v_add_f32_e32 v11, v47, v11
	v_mul_f32_e32 v12, 0x3fb8aa3b, v12
	v_add_f32_e32 v11, v49, v11
	v_exp_f32_e32 v25, v12
	v_sub_f32_e32 v12, v36, v13
	v_add_f32_e32 v11, v54, v11
	v_mul_f32_e32 v12, 0x3fb8aa3b, v12
	v_add_f32_e32 v11, v55, v11
	v_exp_f32_e32 v27, v12
	v_sub_f32_e32 v12, v42, v13
	v_add_f32_e32 v11, v58, v11
	v_mul_f32_e32 v12, 0x3fb8aa3b, v12
	v_add_f32_e32 v11, v61, v11
	v_exp_f32_e32 v30, v12
	v_sub_f32_e32 v12, v44, v13
	v_add_f32_e32 v11, v64, v11
	v_mul_f32_e32 v12, 0x3fb8aa3b, v12
	v_add_f32_e32 v11, v65, v11
	v_exp_f32_e32 v32, v12
	v_sub_f32_e32 v12, v26, v13
	v_add_f32_e32 v11, v39, v11
	v_mul_f32_e32 v12, 0x3fb8aa3b, v12
; #define LAS __attribute__((address_space(3)))
; __device__ __forceinline__ s16x4_t trread(LAS unsigned char* p) { return __builtin_amdgcn_ds_read_tr16_b64_v4i16((LAS s16x4_t*)p); }
; __device__ __forceinline__ bf16x8_t cat4(s16x4_t a, s16x4_t b) { return (bf16x8_t){a[0], a[1], a[2], a[3], b[0], b[1], b[2], b[3]}; }
; __device__ __forceinline__ void mixC_mfma_unit(const bf16* Z, bf16* Yc, const float* rpb, LAS unsigned char* lds, int u, int S, int tid) {
;     ...
;     for (int t = 0; t < 16; ++t)
; #pragma unroll
;         for (int j = 0; j < 4; ++j) { const float pe = __expf(s[t][j] - m); s[t][j] = pe; l += pe; }
;     l += __shfl_xor(l, 16); l += __shfl_xor(l, 32);
;     f32x4 o[4];
; #pragma unroll
;     for (int dt = 0; dt < 4; ++dt) o[dt] = (f32x4){0.f, 0.f, 0.f, 0.f};
;     LAS unsigned char* vb = lds + ((rs - rb) * 64 + cbs + 4 * q + ((lane >> 2) & 3)) * KPITCH + 8 * (lane & 3);
; #pragma unroll
;     for (int G = 0; G < 8; ++G) {
;         const bf16x8_t pb = packp(s[2 * G], s[2 * G + 1]);
; #pragma unroll
;         for (int dt = 0; dt < 4; ++dt) {
;             const s16x4_t lo = trread(vb + (64 * G) * KPITCH + dt * 32), hi = trread(vb + (64 * G + 16) * KPITCH + dt * 32);
;             o[dt] = __builtin_amdgcn_mfma_f32_16x16x32_bf16(cat4(lo, hi), pb, o[dt], 0, 0, 0);
	v_add_f32_e32 v11, v41, v11
	v_exp_f32_e32 v35, v12
	v_sub_f32_e32 v12, v107, v13
	v_add_f32_e32 v11, v46, v11
	v_mul_f32_e32 v12, 0x3fb8aa3b, v12
	v_add_f32_e32 v11, v48, v11
	v_exp_f32_e32 v37, v12
	v_sub_f32_e32 v12, v108, v13
	v_add_f32_e32 v11, v51, v11
	v_mul_f32_e32 v12, 0x3fb8aa3b, v12
	v_add_f32_e32 v11, v53, v11
	v_exp_f32_e32 v42, v12
	v_sub_f32_e32 v12, v110, v13
	v_add_f32_e32 v11, v57, v11
	v_mul_f32_e32 v12, 0x3fb8aa3b, v12
	v_add_f32_e32 v11, v59, v11
	v_exp_f32_e32 v44, v12
	v_sub_f32_e32 v12, v109, v13
	v_add_f32_e32 v11, v31, v11
	v_mul_f32_e32 v12, 0x3fb8aa3b, v12
	v_add_f32_e32 v11, v33, v11
	v_exp_f32_e32 v17, v12
	v_sub_f32_e32 v12, v29, v13
	v_add_f32_e32 v11, v38, v11
	v_mul_f32_e32 v12, 0x3fb8aa3b, v12
	v_add_f32_e32 v11, v40, v11
	v_exp_f32_e32 v20, v12
	v_sub_f32_e32 v12, v24, v13
	v_add_f32_e32 v11, v43, v11
	v_mul_f32_e32 v12, 0x3fb8aa3b, v12
	v_add_f32_e32 v11, v45, v11
	v_exp_f32_e32 v24, v12
	v_sub_f32_e32 v12, v28, v13
	v_add_f32_e32 v11, v50, v11
	v_mul_f32_e32 v12, 0x3fb8aa3b, v12
	v_add_f32_e32 v11, v52, v11
	v_exp_f32_e32 v26, v12
	v_sub_f32_e32 v12, v23, v13
	v_add_f32_e32 v11, v25, v11
	v_mul_f32_e32 v12, 0x3fb8aa3b, v12
	v_add_f32_e32 v11, v27, v11
	v_exp_f32_e32 v28, v12
	v_sub_f32_e32 v12, v22, v13
	v_add_f32_e32 v11, v30, v11
	v_mul_f32_e32 v12, 0x3fb8aa3b, v12
	v_add_f32_e32 v11, v32, v11
	v_exp_f32_e32 v29, v12
	v_sub_f32_e32 v12, v19, v13
	v_add_f32_e32 v11, v35, v11
	v_mul_f32_e32 v12, 0x3fb8aa3b, v12
	v_add_f32_e32 v11, v37, v11
	v_exp_f32_e32 v34, v12
	v_sub_f32_e32 v12, v18, v13
	v_add_f32_e32 v11, v42, v11
	v_mul_f32_e32 v12, 0x3fb8aa3b, v12
	v_add_f32_e32 v11, v44, v11
	v_exp_f32_e32 v36, v12
	v_sub_f32_e32 v12, v14, v13
	v_add_f32_e32 v11, v17, v11
	v_mul_f32_e32 v12, 0x3fb8aa3b, v12
	v_add_f32_e32 v11, v20, v11
	v_exp_f32_e32 v14, v12
	v_sub_f32_e32 v12, v15, v13
	v_add_f32_e32 v11, v24, v11
	v_mul_f32_e32 v12, 0x3fb8aa3b, v12
	v_add_f32_e32 v11, v26, v11
	v_exp_f32_e32 v15, v12
	v_sub_f32_e32 v12, v16, v13
	v_add_f32_e32 v11, v28, v11
	v_mul_f32_e32 v12, 0x3fb8aa3b, v12
	v_add_f32_e32 v11, v29, v11
	v_exp_f32_e32 v16, v12
	v_sub_f32_e32 v12, v21, v13
	v_sub_f32_e32 v7, v7, v13
	v_add_f32_e32 v11, v34, v11
	v_mul_f32_e32 v12, 0x3fb8aa3b, v12
	v_sub_f32_e32 v6, v6, v13
	v_mul_f32_e32 v7, 0x3fb8aa3b, v7
	v_add_f32_e32 v11, v36, v11
	v_exp_f32_e32 v18, v12
	v_mul_f32_e32 v6, 0x3fb8aa3b, v6
	v_exp_f32_e32 v21, v7
	v_sub_f32_e32 v7, v8, v13
	v_add_f32_e32 v11, v14, v11
	v_exp_f32_e32 v19, v6
	v_mul_f32_e32 v7, 0x3fb8aa3b, v7
	v_add_f32_e32 v11, v15, v11
	v_exp_f32_e32 v22, v7
	v_sub_f32_e32 v7, v112, v13
	v_add_f32_e32 v11, v16, v11
	v_mul_f32_e32 v7, 0x3fb8aa3b, v7
	v_add_f32_e32 v11, v18, v11
	v_exp_f32_e32 v23, v7
	v_add_f32_e32 v6, v19, v11
	v_add_f32_e32 v6, v21, v6
	v_add_f32_e32 v6, v22, v6
	v_add_f32_e32 v7, v23, v6
	v_sub_f32_e32 v6, v113, v13
	v_mul_f32_e32 v6, 0x3fb8aa3b, v6
	v_exp_f32_e32 v6, v6
	v_sub_f32_e32 v5, v5, v13
	v_mul_f32_e32 v5, 0x3fb8aa3b, v5
	v_sub_f32_e32 v10, v10, v13
	v_add_f32_e32 v8, v6, v7
	v_sub_f32_e32 v7, v9, v13
	v_mul_f32_e32 v7, 0x3fb8aa3b, v7
	v_exp_f32_e32 v7, v7
	v_mul_f32_e32 v10, 0x3fb8aa3b, v10
	v_sub_f32_e32 v3, v3, v13
	v_exp_f32_e32 v10, v10
	v_add_f32_e32 v9, v7, v8
	v_sub_f32_e32 v8, v111, v13
	v_mul_f32_e32 v8, 0x3fb8aa3b, v8
	v_exp_f32_e32 v8, v8
	v_mul_f32_e32 v3, 0x3fb8aa3b, v3
	v_sub_f32_e32 v4, v4, v13
	v_mul_f32_e32 v4, 0x3fb8aa3b, v4
	v_add_f32_e32 v11, v8, v9
	v_exp_f32_e32 v9, v5
	v_sub_f32_e32 v2, v2, v13
	v_exp_f32_e32 v12, v4
	v_mul_f32_e32 v2, 0x3fb8aa3b, v2
	v_add_f32_e32 v5, v9, v11
	v_exp_f32_e32 v11, v3
	v_exp_f32_e32 v13, v2
	v_add_f32_e32 v5, v10, v5
	v_cvt_pk_bf16_f32 v98, v56, v60
	v_add_f32_e32 v3, v11, v5
	v_add_f32_e32 v3, v12, v3
	v_add_f32_e32 v2, v13, v3
	ds_bpermute_b32 v3, v69, v2
	v_cvt_pk_bf16_f32 v99, v62, v63
	v_cvt_pk_bf16_f32 v100, v79, v81
	v_cvt_pk_bf16_f32 v101, v96, v97
	v_add_u32_e32 v81, 2, v88
	s_waitcnt lgkmcnt(0)
	v_add_f32_e32 v4, v2, v3
	v_subrev_u32_e32 v2, s2, v95
	v_lshl_add_u32 v2, v2, 6, v1
	v_mad_u64_u32 v[2:3], s[16:17], v2, s67, v[68:69]
	ds_read_b64_tr_b16 v[104:105], v2 offset:2304
	ds_read_b64_tr_b16 v[102:103], v2
	ds_read_b64_tr_b16 v[106:107], v2 offset:32
	ds_read_b64_tr_b16 v[108:109], v2 offset:2336
	ds_read_b64_tr_b16 v[110:111], v2 offset:64
	ds_read_b64_tr_b16 v[112:113], v2 offset:2368
	ds_read_b64_tr_b16 v[114:115], v2 offset:96
	ds_read_b64_tr_b16 v[116:117], v2 offset:2400
	s_waitcnt lgkmcnt(6)
	v_mfma_f32_16x16x32_bf16 v[102:105], v[102:105], v[98:101], 0
	v_add_u32_e32 v3, 0x10500, v2
	ds_bpermute_b32 v5, v82, v4
	v_cmp_lt_i32_e64 s[54:55], 3, v81
	s_waitcnt lgkmcnt(5)
	v_mfma_f32_16x16x32_bf16 v[106:109], v[106:109], v[98:101], 0
	s_waitcnt lgkmcnt(3)
	v_mfma_f32_16x16x32_bf16 v[110:113], v[110:113], v[98:101], 0
	s_waitcnt lgkmcnt(1)
	v_mfma_f32_16x16x32_bf16 v[96:99], v[114:117], v[98:101], 0
	v_cvt_pk_bf16_f32 v114, v47, v49
	v_cvt_pk_bf16_f32 v115, v54, v55
	v_cvt_pk_bf16_f32 v116, v58, v61
	v_cvt_pk_bf16_f32 v117, v64, v65
	ds_read_b64_tr_b16 v[62:63], v2 offset:11520
	ds_read_b64_tr_b16 v[60:61], v2 offset:9216
	ds_read_b64_tr_b16 v[100:101], v2 offset:9248
	s_waitcnt lgkmcnt(1)
	v_mfma_f32_16x16x32_bf16 v[60:63], v[60:63], v[114:117], v[102:105]
	s_nop 2
	ds_read_b64_tr_b16 v[102:103], v2 offset:11552
	s_waitcnt lgkmcnt(0)
	v_mfma_f32_16x16x32_bf16 v[100:103], v[100:103], v[114:117], v[106:109]
	ds_read_b64_tr_b16 v[104:105], v2 offset:9280
	s_nop 1
	ds_read_b64_tr_b16 v[106:107], v2 offset:11584
	s_waitcnt lgkmcnt(0)
; __device__ __forceinline__ s16x4_t trread(LAS unsigned char* p) { return __builtin_amdgcn_ds_read_tr16_b64_v4i16((LAS s16x4_t*)p); }
; __device__ __forceinline__ bf16x8_t cat4(s16x4_t a, s16x4_t b) { return (bf16x8_t){a[0], a[1], a[2], a[3], b[0], b[1], b[2], b[3]}; }
; __device__ __forceinline__ void mixC_mfma_unit(const bf16* Z, bf16* Yc, const float* rpb, LAS unsigned char* lds, int u, int S, int tid) {
;     ...
; #pragma unroll
;     for (int G = 0; G < 8; ++G) {
;         const bf16x8_t pb = packp(s[2 * G], s[2 * G + 1]);
; #pragma unroll
;         for (int dt = 0; dt < 4; ++dt) {
;             const s16x4_t lo = trread(vb + (64 * G) * KPITCH + dt * 32), hi = trread(vb + (64 * G + 16) * KPITCH + dt * 32);
;             o[dt] = __builtin_amdgcn_mfma_f32_16x16x32_bf16(cat4(lo, hi), pb, o[dt], 0, 0, 0);
;         }
	v_mfma_f32_16x16x32_bf16 v[104:107], v[104:107], v[114:117], v[110:113]
	ds_read_b64_tr_b16 v[108:109], v2 offset:9312
	s_nop 1
	ds_read_b64_tr_b16 v[110:111], v2 offset:11616
	v_cvt_pk_bf16_f32 v54, v39, v41
	v_cvt_pk_bf16_f32 v55, v46, v48
	v_cvt_pk_bf16_f32 v56, v51, v53
	v_cvt_pk_bf16_f32 v57, v57, v59
	ds_read_b64_tr_b16 v[48:49], v2 offset:20736
	ds_read_b64_tr_b16 v[46:47], v2 offset:18432
	ds_read_b64_tr_b16 v[58:59], v2 offset:18464
	s_waitcnt lgkmcnt(1)
	v_mfma_f32_16x16x32_bf16 v[46:49], v[46:49], v[54:57], v[60:63]
	s_nop 2
	ds_read_b64_tr_b16 v[60:61], v2 offset:20768
	ds_read_b64_tr_b16 v[62:63], v2 offset:18496
	ds_read_b64_tr_b16 v[64:65], v2 offset:20800
	s_waitcnt lgkmcnt(2)
	v_mfma_f32_16x16x32_bf16 v[58:61], v[58:61], v[54:57], v[100:103]
	s_nop 2
	ds_read_b64_tr_b16 v[100:101], v2 offset:18528
	ds_read_b64_tr_b16 v[102:103], v2 offset:20832
	v_mfma_f32_16x16x32_bf16 v[96:99], v[108:111], v[114:117], v[96:99]
	s_waitcnt lgkmcnt(2)
	v_mfma_f32_16x16x32_bf16 v[62:65], v[62:65], v[54:57], v[104:107]
	s_waitcnt lgkmcnt(0)
	v_mfma_f32_16x16x32_bf16 v[54:57], v[100:103], v[54:57], v[96:99]
	v_cvt_pk_bf16_f32 v96, v31, v33
	v_cvt_pk_bf16_f32 v97, v38, v40
	v_cvt_pk_bf16_f32 v98, v43, v45
	v_cvt_pk_bf16_f32 v99, v50, v52
	ds_read_b64_tr_b16 v[40:41], v2 offset:29952
	ds_read_b64_tr_b16 v[38:39], v2 offset:27648
	ds_read_b64_tr_b16 v[50:51], v2 offset:27680
	ds_read_b64_tr_b16 v[52:53], v2 offset:29984
	s_waitcnt lgkmcnt(2)
	v_mfma_f32_16x16x32_bf16 v[38:41], v[38:41], v[96:99], v[46:49]
	s_waitcnt lgkmcnt(0)
	v_mfma_f32_16x16x32_bf16 v[46:49], v[50:53], v[96:99], v[58:61]
	ds_read_b64_tr_b16 v[50:51], v2 offset:27712
	ds_read_b64_tr_b16 v[52:53], v2 offset:30016
	s_nop 0
	ds_read_b64_tr_b16 v[58:59], v2 offset:27744
	ds_read_b64_tr_b16 v[60:61], v2 offset:30048
	s_waitcnt lgkmcnt(0)
	v_mfma_f32_16x16x32_bf16 v[54:57], v[58:61], v[96:99], v[54:57]
	v_cvt_pk_bf16_f32 v58, v25, v27
	v_cvt_pk_bf16_f32 v59, v30, v32
	v_cvt_pk_bf16_f32 v60, v35, v37
	v_cvt_pk_bf16_f32 v61, v42, v44
	ds_read_b64_tr_b16 v[32:33], v2 offset:39168
	ds_read_b64_tr_b16 v[30:31], v2 offset:36864
	ds_read_b64_tr_b16 v[42:43], v2 offset:36896
	ds_read_b64_tr_b16 v[44:45], v2 offset:39200
	s_waitcnt lgkmcnt(2)
	v_mfma_f32_16x16x32_bf16 v[30:33], v[30:33], v[58:61], v[38:41]
	s_waitcnt lgkmcnt(0)
	v_mfma_f32_16x16x32_bf16 v[38:41], v[42:45], v[58:61], v[46:49]
	ds_read_b64_tr_b16 v[42:43], v2 offset:36928
	ds_read_b64_tr_b16 v[44:45], v2 offset:39232
	s_nop 0
	ds_read_b64_tr_b16 v[46:47], v2 offset:36960
	ds_read_b64_tr_b16 v[48:49], v2 offset:39264
	v_mfma_f32_16x16x32_bf16 v[50:53], v[50:53], v[96:99], v[62:65]
	s_waitcnt lgkmcnt(2)
	v_mfma_f32_16x16x32_bf16 v[42:45], v[42:45], v[58:61], v[50:53]
	v_cvt_pk_bf16_f32 v50, v17, v20
	v_cvt_pk_bf16_f32 v51, v24, v26
	v_cvt_pk_bf16_f32 v52, v28, v29
	v_cvt_pk_bf16_f32 v53, v34, v36
	ds_read_b64_tr_b16 v[26:27], v2 offset:48384
	ds_read_b64_tr_b16 v[24:25], v2 offset:46080
	ds_read_b64_tr_b16 v[28:29], v2 offset:46112
	s_waitcnt lgkmcnt(1)
	s_nop 1
	v_mfma_f32_16x16x32_bf16 v[24:27], v[24:27], v[50:53], v[30:33]
	s_nop 2
	ds_read_b64_tr_b16 v[30:31], v2 offset:48416
	ds_read_b64_tr_b16 v[32:33], v2 offset:46144
	ds_read_b64_tr_b16 v[34:35], v2 offset:48448
	s_waitcnt lgkmcnt(2)
	v_mfma_f32_16x16x32_bf16 v[28:31], v[28:31], v[50:53], v[38:41]
	ds_read_b64_tr_b16 v[36:37], v2 offset:46176
	s_nop 1
	ds_read_b64_tr_b16 v[38:39], v2 offset:48480
	v_cvt_pk_bf16_f32 v14, v14, v15
	v_cvt_pk_bf16_f32 v15, v16, v18
	v_cvt_pk_bf16_f32 v16, v19, v21
	v_cvt_pk_bf16_f32 v17, v22, v23
	ds_read_b64_tr_b16 v[20:21], v2 offset:57600
	ds_read_b64_tr_b16 v[18:19], v2 offset:55296
	ds_read_b64_tr_b16 v[22:23], v2 offset:55328
	s_waitcnt lgkmcnt(1)
	v_mfma_f32_16x16x32_bf16 v[18:21], v[18:21], v[14:17], v[24:27]
	s_nop 2
	ds_read_b64_tr_b16 v[24:25], v2 offset:57632
	s_waitcnt lgkmcnt(0)
	v_mfma_f32_16x16x32_bf16 v[22:25], v[22:25], v[14:17], v[28:31]
	ds_read_b64_tr_b16 v[26:27], v2 offset:55360
	s_nop 1
	ds_read_b64_tr_b16 v[28:29], v2 offset:57664
	v_mfma_f32_16x16x32_bf16 v[32:35], v[32:35], v[50:53], v[42:45]
	v_mfma_f32_16x16x32_bf16 v[46:49], v[46:49], v[58:61], v[54:57]
	s_waitcnt lgkmcnt(0)
	v_mfma_f32_16x16x32_bf16 v[26:29], v[26:29], v[14:17], v[32:35]
	ds_read_b64_tr_b16 v[30:31], v2 offset:55392
	s_nop 3
	ds_read_b64_tr_b16 v[32:33], v2 offset:57696
	v_cvt_pk_bf16_f32 v6, v6, v7
	v_cvt_pk_bf16_f32 v7, v8, v9
	v_mfma_f32_16x16x32_bf16 v[36:39], v[36:39], v[50:53], v[46:49]
	v_cvt_pk_bf16_f32 v8, v10, v11
	v_cvt_pk_bf16_f32 v9, v12, v13
	s_waitcnt lgkmcnt(0)
	v_mfma_f32_16x16x32_bf16 v[14:17], v[30:33], v[14:17], v[36:39]
	ds_read_b64_tr_b16 v[12:13], v3
	ds_read_b64_tr_b16 v[10:11], v2 offset:64512
	ds_read_b64_tr_b16 v[30:31], v2 offset:64544
	v_add_u32_e32 v3, 0x10520, v2
	ds_read_b64_tr_b16 v[32:33], v3
	v_add_u32_e32 v3, 0x10540, v2
	s_waitcnt lgkmcnt(2)
	v_mfma_f32_16x16x32_bf16 v[10:13], v[10:13], v[6:9], v[18:21]
	s_waitcnt lgkmcnt(0)
	v_mfma_f32_16x16x32_bf16 v[18:21], v[30:33], v[6:9], v[22:25]
	s_nop 2
	ds_read_b64_tr_b16 v[22:23], v2 offset:64576
	ds_read_b64_tr_b16 v[24:25], v3
	s_waitcnt lgkmcnt(0)
	v_mfma_f32_16x16x32_bf16 v[22:25], v[22:25], v[6:9], v[26:29]
	s_nop 2
	ds_read_b64_tr_b16 v[26:27], v2 offset:64608
	v_add_u32_e32 v2, 0x10560, v2
	ds_read_b64_tr_b16 v[28:29], v2
	v_add_f32_e32 v2, v4, v5
	s_waitcnt lgkmcnt(0)
; __device__ __forceinline__ unsigned cvt_pk_bf16(float lo, float hi) { unsigned r; asm volatile("v_cvt_pk_bf16_f32 %0, %1, %2" : "=v"(r) : "v"(lo), "v"(hi)); return r; }
; __device__ __forceinline__ void mixC_mfma_unit(const bf16* Z, bf16* Yc, const float* rpb, LAS unsigned char* lds, int u, int S, int tid) {
;     ...
;     const int qr = 4 * np + 2 * qt + (w >> 2), cb = w & 3, qc = cb * 16 + n;
;     int rs = qr - 4; rs = rs < 0 ? 0 : (rs > rows - 8 ? rows - 8 : rs);
;     int cbs = cb * 16 - 8; cbs = cbs < 0 ? 0 : (cbs > 32 ? 32 : cbs);
;     int cs = qc - 8; cs = cs < 0 ? 0 : (cs > 48 ? 48 : cs);
;     const int tokc = seq0 + qr * 64 + qc;
;     const bf16* qp = Z + (size_t)tokc * NZ + 6144 + h * 64;
;     const bf16x8_t qf0 = *(const bf16x8_t*)(qp + 8 * q), qf1 = *(const bf16x8_t*)(qp + 32 + 8 * q);
;     f32x4 s[16];
; #pragma unroll
;     for (int hf = 0; hf < 2; ++hf) {
;         bf16x8_t kf[8][2];
; #pragma unroll
;         for (int tt = 0; tt < 8; ++tt) { const int t = 8 * hf + tt;
;             const bf16* kp = zk + (size_t)((rs + (t >> 1)) * 64 + cbs + (t & 1) * 16 + n) * NZ + 8 * q;
;             kf[tt][0] = *(const bf16x8_t*)kp; kf[tt][1] = *(const bf16x8_t*)(kp + 32); }
; #pragma unroll
;         for (int tt = 0; tt < 8; ++tt) {
;             f32x4 a = {0.f, 0.f, 0.f, 0.f};
;             a = __builtin_amdgcn_mfma_f32_16x16x32_bf16(kf[tt][0], qf0, a, 0, 0, 0);
;             s[8 * hf + tt] = __builtin_amdgcn_mfma_f32_16x16x32_bf16(kf[tt][1], qf1, a, 0, 0, 0);
;         }
;     ...
;     const float inv = __builtin_amdgcn_rcpf(l);
;     bf16* yp = Yc + (size_t)tokc * 512 + h * 64;
; #pragma unroll
;     for (int dt = 0; dt < 4; ++dt) { uint2 wv; wv.x = pg8::cvt_pk_bf16(o[dt][0] * inv, o[dt][1] * inv); wv.y = pg8::cvt_pk_bf16(o[dt][2] * inv, o[dt][3] * inv);
;         *(uint2*)(yp + dt * 16 + 4 * q) = wv; }
	v_mfma_f32_16x16x32_bf16 v[6:9], v[26:29], v[6:9], v[14:17]
	s_nop 2
	v_rcp_f32_e32 v14, v2
	v_lshlrev_b64 v[2:3], 10, v[76:77]
	v_lshl_add_u64 v[2:3], v[66:67], 0, v[2:3]
	v_lshl_add_u32 v76, v81, 6, v89
	v_mul_f32_e32 v4, v14, v10
	v_mul_f32_e32 v5, v14, v11
	v_cvt_pk_bf16_f32 v4, v4, v5
	v_mul_f32_e32 v5, v14, v12
	v_mul_f32_e32 v10, v14, v13
	v_cvt_pk_bf16_f32 v5, v5, v10
	v_lshrrev_b32_e32 v218, 4, v231
	v_lshl_or_b32 v218, v231, 4, v218
	v_and_b32_e32 v218, 0x33, v218
	v_and_or_b32 v218, v231, 12, v218
	v_lshlrev_b32_e32 v218, 2, v218
	ds_bpermute_b32 v220, v218, v2
	ds_bpermute_b32 v221, v218, v3
	ds_bpermute_b32 v4, v218, v4
	ds_bpermute_b32 v5, v218, v5
	s_waitcnt lgkmcnt(0)
	global_store_dwordx2 v[220:221], v[4:5], off
	v_mul_f32_e32 v4, v14, v18
	v_mul_f32_e32 v5, v14, v19
	v_cvt_pk_bf16_f32 v4, v4, v5
	v_mul_f32_e32 v5, v14, v20
	v_mul_f32_e32 v10, v14, v21
	v_cvt_pk_bf16_f32 v5, v5, v10
	ds_bpermute_b32 v4, v218, v4
	ds_bpermute_b32 v5, v218, v5
	s_waitcnt lgkmcnt(0)
	global_store_dwordx2 v[220:221], v[4:5], off offset:32
	v_mul_f32_e32 v4, v14, v22
	v_mul_f32_e32 v5, v14, v23
	v_cvt_pk_bf16_f32 v4, v4, v5
	v_mul_f32_e32 v5, v14, v24
	v_mul_f32_e32 v10, v14, v25
	v_cvt_pk_bf16_f32 v5, v5, v10
	ds_bpermute_b32 v4, v218, v4
	ds_bpermute_b32 v5, v218, v5
	s_waitcnt lgkmcnt(0)
	global_store_dwordx2 v[220:221], v[4:5], off offset:64
	v_mul_f32_e32 v4, v14, v6
	v_mul_f32_e32 v5, v14, v7
	v_cvt_pk_bf16_f32 v4, v4, v5
	v_mul_f32_e32 v5, v14, v8
	v_mul_f32_e32 v6, v14, v9
	v_cvt_pk_bf16_f32 v5, v5, v6
	ds_bpermute_b32 v4, v218, v4
	ds_bpermute_b32 v5, v218, v5
	s_waitcnt lgkmcnt(0)
	global_store_dwordx2 v[220:221], v[4:5], off offset:96
	v_add_u32_e32 v2, -2, v88
	v_min_i32_e32 v2, s21, v2
	v_cndmask_b32_e64 v79, 0, v2, s[54:55]
	v_mad_i64_i32 v[2:3], s[16:17], v76, s66, v[74:75]
	v_lshl_add_u64 v[2:3], v[2:3], 0, s[70:71]
	v_lshl_add_u64 v[2:3], v[2:3], 0, v[72:73]
	v_lshl_add_u64 v[6:7], v[2:3], 0, s[24:25]
	v_add_co_u32_e64 v2, s[54:55], s20, v2
	v_lshlrev_b32_e32 v95, 6, v79
	s_nop 0
	v_addc_co_u32_e64 v3, s[54:55], 0, v3, s[54:55]
	global_load_dwordx4 v[2:5], v[2:3], off
	s_nop 0
	global_load_dwordx4 v[10:13], v[6:7], off offset:64
	v_add_u32_e32 v6, v95, v83
	v_mad_i64_i32 v[14:15], s[16:17], v6, s66, v[70:71]
	global_load_dwordx4 v[6:9], v[14:15], off
	s_nop 0
	global_load_dwordx4 v[14:17], v[14:15], off offset:64
	v_add_u32_e32 v18, v95, v84
	v_mad_i64_i32 v[22:23], s[16:17], v18, s66, v[70:71]
	global_load_dwordx4 v[18:21], v[22:23], off
	s_nop 0
	global_load_dwordx4 v[22:25], v[22:23], off offset:64
	v_add_u32_e32 v34, 64, v95
	v_add_u32_e32 v26, v34, v83
	v_mad_i64_i32 v[30:31], s[16:17], v26, s66, v[70:71]
	global_load_dwordx4 v[26:29], v[30:31], off
	s_nop 0
	global_load_dwordx4 v[30:33], v[30:31], off offset:64
	v_add_u32_e32 v34, v34, v84
	v_mad_i64_i32 v[38:39], s[16:17], v34, s66, v[70:71]
	global_load_dwordx4 v[34:37], v[38:39], off
	s_nop 0
	global_load_dwordx4 v[38:41], v[38:39], off offset:64
	v_add_u32_e32 v50, 0x80, v95
	v_add_u32_e32 v42, v50, v83
	v_mad_i64_i32 v[46:47], s[16:17], v42, s66, v[70:71]
	global_load_dwordx4 v[42:45], v[46:47], off
	s_nop 0
	global_load_dwordx4 v[46:49], v[46:47], off offset:64
	v_add_u32_e32 v50, v50, v84
	v_mad_i64_i32 v[50:51], s[16:17], v50, s66, v[70:71]
	global_load_dwordx4 v[72:75], v[50:51], off
	global_load_dwordx4 v[96:99], v[50:51], off offset:64
	v_add_u32_e32 v52, 0xc0, v95
	v_add_u32_e32 v50, v52, v83
	v_mad_i64_i32 v[50:51], s[16:17], v50, s66, v[70:71]
	global_load_dwordx4 v[100:103], v[50:51], off
	global_load_dwordx4 v[104:107], v[50:51], off offset:64
	v_add_u32_e32 v50, v52, v84
	v_mad_i64_i32 v[50:51], s[16:17], v50, s66, v[70:71]
	global_load_dwordx4 v[108:111], v[50:51], off
	global_load_dwordx4 v[112:115], v[50:51], off offset:64
	s_waitcnt vmcnt(15)
	v_mfma_f32_16x16x32_bf16 v[6:9], v[6:9], v[2:5], 0
	v_ashrrev_i32_e32 v77, 31, v76
	s_waitcnt vmcnt(14)
	v_mfma_f32_16x16x32_bf16 v[62:65], v[14:17], v[10:13], v[6:9]
	s_waitcnt vmcnt(13)
	v_mfma_f32_16x16x32_bf16 v[6:9], v[18:21], v[2:5], 0
	s_waitcnt vmcnt(12)
	v_mfma_f32_16x16x32_bf16 v[50:53], v[22:25], v[10:13], v[6:9]
	s_waitcnt vmcnt(11)
	v_mfma_f32_16x16x32_bf16 v[6:9], v[26:29], v[2:5], 0
	s_waitcnt vmcnt(10)
	v_mfma_f32_16x16x32_bf16 v[54:57], v[30:33], v[10:13], v[6:9]
	s_waitcnt vmcnt(9)
	v_mfma_f32_16x16x32_bf16 v[6:9], v[34:37], v[2:5], 0
	s_waitcnt vmcnt(8)
	v_mfma_f32_16x16x32_bf16 v[58:61], v[38:41], v[10:13], v[6:9]
	s_waitcnt vmcnt(7)
	v_mfma_f32_16x16x32_bf16 v[6:9], v[42:45], v[2:5], 0
	s_waitcnt vmcnt(6)
	v_mfma_f32_16x16x32_bf16 v[46:49], v[46:49], v[10:13], v[6:9]
	s_waitcnt vmcnt(5)
	v_mfma_f32_16x16x32_bf16 v[6:9], v[72:75], v[2:5], 0
	s_waitcnt vmcnt(4)
	v_mfma_f32_16x16x32_bf16 v[34:37], v[96:99], v[10:13], v[6:9]
	s_waitcnt vmcnt(3)
	v_mfma_f32_16x16x32_bf16 v[6:9], v[100:103], v[2:5], 0
	s_waitcnt vmcnt(2)
	v_mfma_f32_16x16x32_bf16 v[38:41], v[104:107], v[10:13], v[6:9]
	s_waitcnt vmcnt(1)
	v_mfma_f32_16x16x32_bf16 v[6:9], v[108:111], v[2:5], 0
	s_waitcnt vmcnt(0)
; #define LAS __attribute__((address_space(3)))
; __device__ __forceinline__ void mixC_mfma_unit(const bf16* Z, bf16* Yc, const float* rpb, LAS unsigned char* lds, int u, int S, int tid) {
;     ...
;     for (int hf = 0; hf < 2; ++hf) {
;         bf16x8_t kf[8][2];
; #pragma unroll
;         for (int tt = 0; tt < 8; ++tt) { const int t = 8 * hf + tt;
;             const bf16* kp = zk + (size_t)((rs + (t >> 1)) * 64 + cbs + (t & 1) * 16 + n) * NZ + 8 * q;
;             kf[tt][0] = *(const bf16x8_t*)kp; kf[tt][1] = *(const bf16x8_t*)(kp + 32); }
; #pragma unroll
;         for (int tt = 0; tt < 8; ++tt) {
;             f32x4 a = {0.f, 0.f, 0.f, 0.f};
;             a = __builtin_amdgcn_mfma_f32_16x16x32_bf16(kf[tt][0], qf0, a, 0, 0, 0);
;             s[8 * hf + tt] = __builtin_amdgcn_mfma_f32_16x16x32_bf16(kf[tt][1], qf1, a, 0, 0, 0);
;         }
;         __builtin_amdgcn_sched_barrier(0);
;     }
;     const LAS float* rbp = (const LAS float*)(lds + C_ROWS * KPITCH);
;     float m = -1e30f;
; #pragma unroll
;     for (int t = 0; t < 16; ++t)
; #pragma unroll
;         for (int j = 0; j < 4; ++j) {
;             const int kr = rs + (t >> 1), kc = cbs + (t & 1) * 16 + 4 * q + j;
;             const bool valid = (kc >= cs) && (kc < cs + 16);
;             int dc = kc - qc + 15; dc = dc < 0 ? 0 : (dc > 30 ? 30 : dc);
;             const float sc = s[t][j] * 0.125f + rbp[(kr - qr + 7) * 31 + dc];
;             s[t][j] = valid ? sc : -1e30f; m = fmaxf(m, s[t][j]);
;         }
	v_mfma_f32_16x16x32_bf16 v[30:33], v[112:115], v[10:13], v[6:9]
	v_add_u32_e32 v14, 0x100, v95
	v_add_u32_e32 v18, 0x140, v95
	v_add_u32_e32 v44, 0x180, v95
	v_add_u32_e32 v45, 0x1c0, v95
	v_add_u32_e32 v6, v14, v83
	v_add_u32_e32 v14, v14, v84
	v_add_u32_e32 v19, v18, v83
	v_add_u32_e32 v22, v18, v84
	v_add_u32_e32 v26, v44, v83
	v_add_u32_e32 v44, v44, v84
	v_add_u32_e32 v23, v45, v83
	v_add_u32_e32 v45, v45, v84
	v_mad_i64_i32 v[42:43], s[16:17], v6, s66, v[70:71]
	v_mad_i64_i32 v[88:89], s[16:17], v14, s66, v[70:71]
	v_mad_i64_i32 v[112:113], s[16:17], v19, s66, v[70:71]
	v_mad_i64_i32 v[114:115], s[16:17], v22, s66, v[70:71]
	v_mad_i64_i32 v[116:117], s[16:17], v26, s66, v[70:71]
	v_mad_i64_i32 v[118:119], s[16:17], v44, s66, v[70:71]
	v_mad_i64_i32 v[120:121], s[16:17], v23, s66, v[70:71]
	v_mad_i64_i32 v[70:71], s[16:17], v45, s66, v[70:71]
	global_load_dwordx4 v[6:9], v[42:43], off
	global_load_dwordx4 v[14:17], v[88:89], off
	global_load_dwordx4 v[18:21], v[112:113], off
	global_load_dwordx4 v[72:75], v[114:115], off
	global_load_dwordx4 v[96:99], v[116:117], off
	global_load_dwordx4 v[100:103], v[118:119], off
	global_load_dwordx4 v[104:107], v[120:121], off
	global_load_dwordx4 v[108:111], v[70:71], off
	global_load_dwordx4 v[180:183], v[42:43], off offset:64
	global_load_dwordx4 v[184:187], v[88:89], off offset:64
	global_load_dwordx4 v[188:191], v[112:113], off offset:64
	global_load_dwordx4 v[192:195], v[114:115], off offset:64
	global_load_dwordx4 v[202:205], v[116:117], off offset:64
	global_load_dwordx4 v[206:209], v[118:119], off offset:64
	global_load_dwordx4 v[210:213], v[120:121], off offset:64
	global_load_dwordx4 v[214:217], v[70:71], off offset:64
	s_waitcnt vmcnt(15)
	v_mfma_f32_16x16x32_bf16 v[6:9], v[6:9], v[2:5], 0
	s_waitcnt vmcnt(14)
	v_mfma_f32_16x16x32_bf16 v[14:17], v[14:17], v[2:5], 0
	s_waitcnt vmcnt(13)
	v_mfma_f32_16x16x32_bf16 v[18:21], v[18:21], v[2:5], 0
	s_waitcnt vmcnt(12)
	v_mfma_f32_16x16x32_bf16 v[72:75], v[72:75], v[2:5], 0
	s_waitcnt vmcnt(11)
	v_mfma_f32_16x16x32_bf16 v[96:99], v[96:99], v[2:5], 0
	s_waitcnt vmcnt(10)
	v_mfma_f32_16x16x32_bf16 v[100:103], v[100:103], v[2:5], 0
	s_waitcnt vmcnt(9)
	v_mfma_f32_16x16x32_bf16 v[104:107], v[104:107], v[2:5], 0
	s_waitcnt vmcnt(8)
	v_mfma_f32_16x16x32_bf16 v[108:111], v[108:111], v[2:5], 0
	s_waitcnt vmcnt(7)
	v_mfma_f32_16x16x32_bf16 v[42:45], v[180:183], v[10:13], v[6:9]
	s_waitcnt vmcnt(6)
	v_mfma_f32_16x16x32_bf16 v[26:29], v[184:187], v[10:13], v[14:17]
	s_waitcnt vmcnt(5)
	v_mfma_f32_16x16x32_bf16 v[22:25], v[188:191], v[10:13], v[18:21]
	s_waitcnt vmcnt(4)
	v_mfma_f32_16x16x32_bf16 v[18:21], v[192:195], v[10:13], v[72:75]
	s_waitcnt vmcnt(3)
	v_mfma_f32_16x16x32_bf16 v[14:17], v[202:205], v[10:13], v[96:99]
	s_waitcnt vmcnt(2)
	v_mfma_f32_16x16x32_bf16 v[6:9], v[206:209], v[10:13], v[100:103]
	s_waitcnt vmcnt(1)
	v_mfma_f32_16x16x32_bf16 v[2:5], v[210:213], v[10:13], v[104:107]
	s_waitcnt vmcnt(0)
	v_mfma_f32_16x16x32_bf16 v[10:13], v[214:217], v[10:13], v[108:111]
	v_sub_u32_e32 v70, v79, v81
	v_mul_lo_u32 v70, v70, s4
	v_add_u32_e32 v74, s3, v70
	v_add_u32_e32 v83, v74, v85
	v_add_u32_e32 v70, 0x200, v83
	v_add_u32_e32 v95, v74, v78
	ds_read2_b32 v[72:73], v70 offset0:104 offset1:135
	v_add_u32_e32 v70, 0x200, v95
	ds_read2_b32 v[84:85], v70 offset0:104 offset1:135
	v_add_u32_e32 v98, v74, v87
	v_add_u32_e32 v99, v74, v92
	s_waitcnt lgkmcnt(1)
	v_fmamk_f32 v62, v62, 0x3e000000, v72
	v_cndmask_b32_e32 v62, v241, v62, vcc
	s_waitcnt lgkmcnt(0)
	v_fmamk_f32 v63, v63, 0x3e000000, v84
	v_add_u32_e32 v84, v74, v80
	v_add_u32_e32 v71, 0x200, v84
	ds_read2_b32 v[80:81], v71 offset0:104 offset1:135
	v_cndmask_b32_e64 v63, v241, v63, s[40:41]
	v_max3_f32 v70, v62, s15, v63
	v_add_u32_e32 v100, v74, v94
	v_add_u32_e32 v104, 0x400, v83
	s_waitcnt lgkmcnt(0)
	v_fmamk_f32 v64, v64, 0x3e000000, v80
	v_add_u32_e32 v80, v74, v86
	v_add_u32_e32 v71, 0x200, v80
	ds_read2_b32 v[88:89], v71 offset0:104 offset1:135
	v_cndmask_b32_e64 v64, v241, v64, s[42:43]
	v_add_u32_e32 v105, 0x400, v95
	v_add_u32_e32 v106, 0x400, v80
	v_fmac_f32_e32 v73, 0x3e000000, v54
	s_waitcnt lgkmcnt(0)
	v_fmamk_f32 v65, v65, 0x3e000000, v88
	v_cndmask_b32_e64 v65, v241, v65, s[44:45]
	v_max3_f32 v72, v70, v64, v65
	v_add_u32_e32 v70, 0x200, v98
	ds_read2_b32 v[86:87], v70 offset0:104 offset1:135
	v_fmac_f32_e32 v89, 0x3e000000, v57
	v_fmac_f32_e32 v85, 0x3e000000, v55
	v_cndmask_b32_e64 v55, v241, v89, s[44:45]
	ds_read2_b32 v[88:89], v106 offset0:38 offset1:69
	s_waitcnt lgkmcnt(1)
	v_fmamk_f32 v50, v50, 0x3e000000, v86
	v_cndmask_b32_e64 v70, v241, v50, s[46:47]
	v_add_u32_e32 v50, 0x200, v99
	ds_read2_b32 v[96:97], v50 offset0:104 offset1:135
	v_fmac_f32_e32 v87, 0x3e000000, v58
	v_fmac_f32_e32 v81, 0x3e000000, v56
	v_cndmask_b32_e64 v54, v241, v81, s[42:43]
	s_waitcnt lgkmcnt(1)
	v_fmamk_f32 v49, v49, 0x3e000000, v88
	s_waitcnt lgkmcnt(0)
	v_fmamk_f32 v50, v51, 0x3e000000, v96
	v_add_u32_e32 v96, v74, v93
	v_cndmask_b32_e64 v71, v241, v50, s[48:49]
	v_add_u32_e32 v50, 0x200, v96
	ds_read2_b32 v[50:51], v50 offset0:104 offset1:135
	v_max3_f32 v78, v72, v70, v71
	v_fmac_f32_e32 v97, 0x3e000000, v59
	ds_read2_b32 v[58:59], v104 offset0:38 offset1:69
	v_add_u32_e32 v107, 0x400, v99
	s_waitcnt lgkmcnt(1)
	v_fmamk_f32 v50, v52, 0x3e000000, v50
	v_cndmask_b32_e64 v72, v241, v50, s[50:51]
	v_add_u32_e32 v50, 0x200, v100
	ds_read2_b32 v[92:93], v50 offset0:104 offset1:135
	v_fmac_f32_e32 v51, 0x3e000000, v60
	v_cndmask_b32_e64 v52, v241, v97, s[48:49]
	v_cndmask_b32_e64 v51, v241, v51, s[50:51]
	s_waitcnt lgkmcnt(1)
	v_fmamk_f32 v46, v46, 0x3e000000, v58
	s_waitcnt lgkmcnt(0)
; __device__ __forceinline__ void mixC_mfma_unit(const bf16* Z, bf16* Yc, const float* rpb, LAS unsigned char* lds, int u, int S, int tid) {
;     ...
;     for (int t = 0; t < 16; ++t)
; #pragma unroll
;         for (int j = 0; j < 4; ++j) {
;             const int kr = rs + (t >> 1), kc = cbs + (t & 1) * 16 + 4 * q + j;
;             const bool valid = (kc >= cs) && (kc < cs + 16);
;             int dc = kc - qc + 15; dc = dc < 0 ? 0 : (dc > 30 ? 30 : dc);
;             const float sc = s[t][j] * 0.125f + rbp[(kr - qr + 7) * 31 + dc];
;             s[t][j] = valid ? sc : -1e30f; m = fmaxf(m, s[t][j]);
;         }
	v_fmamk_f32 v50, v53, 0x3e000000, v92
	v_fmac_f32_e32 v93, 0x3e000000, v61
	ds_read2_b32 v[60:61], v105 offset0:38 offset1:69
	v_cndmask_b32_e64 v75, v241, v50, s[52:53]
	v_max3_f32 v50, v78, v72, v75
	v_cndmask_b32_e32 v78, v241, v73, vcc
	v_cndmask_b32_e64 v73, v241, v85, s[40:41]
	v_max3_f32 v50, v50, v78, v73
	v_max3_f32 v50, v50, v54, v55
	v_cndmask_b32_e64 v53, v241, v87, s[46:47]
	v_max3_f32 v56, v50, v53, v52
	v_cndmask_b32_e64 v50, v241, v93, s[52:53]
	s_waitcnt lgkmcnt(0)
	v_fmamk_f32 v47, v47, 0x3e000000, v60
	v_max3_f32 v56, v56, v51, v50
	v_cndmask_b32_e32 v46, v241, v46, vcc
	v_cndmask_b32_e64 v57, v241, v47, s[40:41]
	v_max3_f32 v47, v56, v46, v57
	v_add_u32_e32 v56, 0x400, v84
	v_cndmask_b32_e64 v60, v241, v49, s[44:45]
	v_add_u32_e32 v49, 0x400, v98
	ds_read2_b32 v[86:87], v56 offset0:38 offset1:69
	ds_read2_b32 v[92:93], v49 offset0:38 offset1:69
	ds_read2_b32 v[94:95], v107 offset0:38 offset1:69
	v_add_u32_e32 v108, 0x400, v100
	ds_read2_b32 v[98:99], v108 offset0:38 offset1:69
	s_waitcnt lgkmcnt(3)
	v_fmamk_f32 v48, v48, 0x3e000000, v86
	s_waitcnt lgkmcnt(2)
	v_fmamk_f32 v34, v34, 0x3e000000, v92
	v_cndmask_b32_e64 v48, v241, v48, s[42:43]
	v_cndmask_b32_e64 v74, v241, v34, s[46:47]
	s_waitcnt lgkmcnt(1)
	v_fmamk_f32 v34, v35, 0x3e000000, v94
	v_max3_f32 v47, v47, v48, v60
	v_cndmask_b32_e64 v81, v241, v34, s[48:49]
	v_max3_f32 v34, v47, v74, v81
	v_add_u32_e32 v47, 0x400, v96
	ds_read2_b32 v[96:97], v47 offset0:38 offset1:69
	v_fmac_f32_e32 v59, 0x3e000000, v38
	v_cndmask_b32_e32 v84, v241, v59, vcc
	v_fmac_f32_e32 v93, 0x3e000000, v30
	ds_read2_b32 v[58:59], v104 offset0:100 offset1:131
	s_waitcnt lgkmcnt(1)
	v_fmamk_f32 v35, v36, 0x3e000000, v96
	v_cndmask_b32_e64 v80, v241, v35, s[50:51]
	v_fmamk_f32 v35, v37, 0x3e000000, v98
	v_cndmask_b32_e64 v37, v241, v93, s[46:47]
	ds_read2_b32 v[92:93], v105 offset0:100 offset1:131
	v_cndmask_b32_e64 v85, v241, v35, s[52:53]
	v_fmac_f32_e32 v61, 0x3e000000, v39
	v_max3_f32 v34, v34, v80, v85
	v_cndmask_b32_e64 v83, v241, v61, s[40:41]
	v_fmac_f32_e32 v87, 0x3e000000, v40
	v_fmac_f32_e32 v89, 0x3e000000, v41
	v_max3_f32 v34, v34, v84, v83
	v_cndmask_b32_e64 v38, v241, v87, s[42:43]
	v_cndmask_b32_e64 v40, v241, v89, s[44:45]
	v_fmac_f32_e32 v95, 0x3e000000, v31
	v_max3_f32 v34, v34, v38, v40
	v_cndmask_b32_e64 v35, v241, v95, s[48:49]
	v_fmac_f32_e32 v99, 0x3e000000, v33
	s_waitcnt lgkmcnt(1)
	v_fmamk_f32 v33, v42, 0x3e000000, v58
	v_max3_f32 v31, v34, v37, v35
	v_cndmask_b32_e32 v34, v241, v33, vcc
	s_waitcnt lgkmcnt(0)
	v_fmamk_f32 v33, v43, 0x3e000000, v92
	ds_read2_b32 v[42:43], v56 offset0:100 offset1:131
	v_fmac_f32_e32 v97, 0x3e000000, v32
	ds_read2_b32 v[94:95], v106 offset0:100 offset1:131
	v_cndmask_b32_e64 v32, v241, v97, s[50:51]
	v_cndmask_b32_e64 v30, v241, v99, s[52:53]
	ds_read2_b32 v[96:97], v49 offset0:100 offset1:131
	ds_read2_b32 v[98:99], v107 offset0:100 offset1:131
	ds_read2_b32 v[100:101], v47 offset0:100 offset1:131
	ds_read2_b32 v[102:103], v108 offset0:100 offset1:131
	v_cndmask_b32_e64 v36, v241, v33, s[40:41]
	s_waitcnt lgkmcnt(5)
	v_fmamk_f32 v33, v44, 0x3e000000, v42
	v_max3_f32 v31, v31, v32, v30
	v_cndmask_b32_e64 v42, v241, v33, s[42:43]
	s_waitcnt lgkmcnt(4)
	v_fmamk_f32 v33, v45, 0x3e000000, v94
	v_max3_f32 v31, v31, v34, v36
	v_cndmask_b32_e64 v44, v241, v33, s[44:45]
	s_waitcnt lgkmcnt(3)
	v_fmamk_f32 v26, v26, 0x3e000000, v96
	s_waitcnt lgkmcnt(2)
	v_fmamk_f32 v27, v27, 0x3e000000, v98
	s_waitcnt lgkmcnt(1)
	v_fmamk_f32 v28, v28, 0x3e000000, v100
	v_max3_f32 v31, v31, v42, v44
	v_cndmask_b32_e64 v26, v241, v26, s[46:47]
	v_cndmask_b32_e64 v86, v241, v27, s[48:49]
	v_cndmask_b32_e64 v87, v241, v28, s[50:51]
	s_waitcnt lgkmcnt(0)
	v_fmamk_f32 v28, v29, 0x3e000000, v102
	v_max3_f32 v27, v31, v26, v86
	v_cndmask_b32_e64 v89, v241, v28, s[52:53]
	v_fmac_f32_e32 v59, 0x3e000000, v22
	v_fmac_f32_e32 v93, 0x3e000000, v23
	v_max3_f32 v27, v27, v87, v89
	v_cndmask_b32_e32 v88, v241, v59, vcc
	v_cndmask_b32_e64 v29, v241, v93, s[40:41]
	v_fmac_f32_e32 v43, 0x3e000000, v24
	v_fmac_f32_e32 v95, 0x3e000000, v25
	v_max3_f32 v22, v27, v88, v29
	v_cndmask_b32_e64 v24, v241, v43, s[42:43]
	v_cndmask_b32_e64 v28, v241, v95, s[44:45]
	v_fmac_f32_e32 v97, 0x3e000000, v18
	v_fmac_f32_e32 v99, 0x3e000000, v19
	ds_read2_b32 v[58:59], v104 offset0:162 offset1:193
	ds_read2_b32 v[94:95], v105 offset0:162 offset1:193
	v_max3_f32 v25, v22, v24, v28
	v_cndmask_b32_e64 v23, v241, v97, s[46:47]
	v_cndmask_b32_e64 v22, v241, v99, s[48:49]
	v_fmac_f32_e32 v101, 0x3e000000, v20
	v_fmac_f32_e32 v103, 0x3e000000, v21
	ds_read2_b32 v[96:97], v56 offset0:162 offset1:193
	ds_read2_b32 v[98:99], v106 offset0:162 offset1:193
	v_cndmask_b32_e64 v19, v241, v101, s[50:51]
	v_cndmask_b32_e64 v18, v241, v103, s[52:53]
	ds_read2_b32 v[100:101], v49 offset0:162 offset1:193
	ds_read2_b32 v[102:103], v107 offset0:162 offset1:193
	ds_read2_b32 v[104:105], v47 offset0:162 offset1:193
	ds_read2_b32 v[106:107], v108 offset0:162 offset1:193
	v_max3_f32 v25, v25, v23, v22
	s_waitcnt lgkmcnt(7)
	v_fmamk_f32 v14, v14, 0x3e000000, v58
	s_waitcnt lgkmcnt(6)
	v_fmamk_f32 v15, v15, 0x3e000000, v94
	v_max3_f32 v20, v25, v19, v18
	v_cndmask_b32_e32 v14, v241, v14, vcc
	v_cndmask_b32_e64 v15, v241, v15, s[40:41]
	s_waitcnt lgkmcnt(5)
	v_fmamk_f32 v16, v16, 0x3e000000, v96
	s_waitcnt lgkmcnt(4)
	v_fmamk_f32 v17, v17, 0x3e000000, v98
	v_max3_f32 v20, v20, v14, v15
	v_cndmask_b32_e64 v16, v241, v16, s[42:43]
	v_cndmask_b32_e64 v21, v241, v17, s[44:45]
	s_waitcnt lgkmcnt(3)
	v_fmamk_f32 v6, v6, 0x3e000000, v100
	s_waitcnt lgkmcnt(2)
; __device__ __forceinline__ void mixC_mfma_unit(const bf16* Z, bf16* Yc, const float* rpb, LAS unsigned char* lds, int u, int S, int tid) {
;     ...
;             s[t][j] = valid ? sc : -1e30f; m = fmaxf(m, s[t][j]);
;         }
;     m = fmaxf(m, __shfl_xor(m, 16)); m = fmaxf(m, __shfl_xor(m, 32));
;     float l = 0.f;
; #pragma unroll
;     for (int t = 0; t < 16; ++t)
; #pragma unroll
;         for (int j = 0; j < 4; ++j) { const float pe = __expf(s[t][j] - m); s[t][j] = pe; l += pe; }
; __global__ void __launch_bounds__(NTHR, 2) fwd_megakernel(Params p) {
;     ...
;                         for (; it < NB1 + NA + NC; it += G) { int t2 = tid; asm volatile("" : "+v"(t2)); mixC_mfma_unit(Zb, Y + (size_t)2 * MC * 512, rpb, lds, it - NB1 - NA, S, t2); }
	v_fmamk_f32 v7, v7, 0x3e000000, v102
	v_max3_f32 v17, v20, v16, v21
	v_cndmask_b32_e64 v6, v241, v6, s[46:47]
	v_cndmask_b32_e64 v7, v241, v7, s[48:49]
	s_waitcnt lgkmcnt(1)
	v_fmamk_f32 v8, v8, 0x3e000000, v104
	s_waitcnt lgkmcnt(0)
	v_fmamk_f32 v9, v9, 0x3e000000, v106
	v_max3_f32 v17, v17, v6, v7
	v_cndmask_b32_e64 v8, v241, v8, s[50:51]
	v_cndmask_b32_e64 v93, v241, v9, s[52:53]
	v_fmac_f32_e32 v59, 0x3e000000, v2
	v_fmac_f32_e32 v95, 0x3e000000, v3
	v_max3_f32 v17, v17, v8, v93
	v_cndmask_b32_e32 v94, v241, v59, vcc
	v_cndmask_b32_e64 v9, v241, v95, s[40:41]
	v_fmac_f32_e32 v97, 0x3e000000, v4
	v_fmac_f32_e32 v99, 0x3e000000, v5
	v_max3_f32 v2, v17, v94, v9
	v_cndmask_b32_e64 v92, v241, v97, s[42:43]
	v_cndmask_b32_e64 v5, v241, v99, s[44:45]
	v_fmac_f32_e32 v101, 0x3e000000, v10
	v_fmac_f32_e32 v103, 0x3e000000, v11
	v_max3_f32 v2, v2, v92, v5
	v_cndmask_b32_e64 v10, v241, v101, s[46:47]
	v_cndmask_b32_e64 v3, v241, v103, s[48:49]
	v_fmac_f32_e32 v105, 0x3e000000, v12
	v_fmac_f32_e32 v107, 0x3e000000, v13
	v_max3_f32 v11, v2, v10, v3
	v_cndmask_b32_e64 v4, v241, v105, s[50:51]
	v_cndmask_b32_e64 v2, v241, v107, s[52:53]
	v_max3_f32 v11, v11, v4, v2
	ds_bpermute_b32 v12, v69, v11
	s_add_i32 s14, s14, s98
	s_mov_b32 s84, 0xf149f2ca
	s_cmpk_gt_i32 s14, 0x9ff
	s_waitcnt lgkmcnt(0)
	v_max_f32_e32 v12, v12, v12
	v_max_f32_e32 v11, v11, v12
	ds_bpermute_b32 v12, v82, v11
	s_waitcnt lgkmcnt(0)
	v_max_f32_e32 v12, v12, v12
	v_max_f32_e32 v13, v11, v12
	v_sub_f32_e32 v12, v63, v13
	v_mul_f32_e32 v12, 0x3fb8aa3b, v12
	v_exp_f32_e32 v59, v12
	v_sub_f32_e32 v12, v64, v13
	v_mul_f32_e32 v12, 0x3fb8aa3b, v12
	v_sub_f32_e32 v11, v62, v13
	v_exp_f32_e32 v62, v12
	v_sub_f32_e32 v12, v65, v13
	v_mul_f32_e32 v12, 0x3fb8aa3b, v12
	v_exp_f32_e32 v63, v12
	v_sub_f32_e32 v12, v70, v13
	v_mul_f32_e32 v12, 0x3fb8aa3b, v12
	v_exp_f32_e32 v65, v12
	v_sub_f32_e32 v12, v71, v13
	v_mul_f32_e32 v12, 0x3fb8aa3b, v12
	v_exp_f32_e32 v71, v12
	v_sub_f32_e32 v12, v72, v13
	v_mul_f32_e32 v12, 0x3fb8aa3b, v12
	v_exp_f32_e32 v72, v12
	v_sub_f32_e32 v12, v75, v13
	v_mul_f32_e32 v12, 0x3fb8aa3b, v12
	v_exp_f32_e32 v75, v12
	v_sub_f32_e32 v12, v78, v13
	v_mul_f32_e32 v12, 0x3fb8aa3b, v12
	v_exp_f32_e32 v47, v12
	v_sub_f32_e32 v12, v73, v13
	v_mul_f32_e32 v12, 0x3fb8aa3b, v12
	v_exp_f32_e32 v49, v12
	v_sub_f32_e32 v12, v54, v13
	v_mul_f32_e32 v12, 0x3fb8aa3b, v12
	v_exp_f32_e32 v54, v12
	v_sub_f32_e32 v12, v55, v13
	v_mul_f32_e32 v12, 0x3fb8aa3b, v12
	v_exp_f32_e32 v55, v12
	v_sub_f32_e32 v12, v53, v13
	v_mul_f32_e32 v12, 0x3fb8aa3b, v12
	v_exp_f32_e32 v58, v12
	v_sub_f32_e32 v12, v52, v13
	v_mul_f32_e32 v12, 0x3fb8aa3b, v12
	v_exp_f32_e32 v61, v12
	v_sub_f32_e32 v12, v51, v13
	v_mul_f32_e32 v12, 0x3fb8aa3b, v12
	v_exp_f32_e32 v64, v12
	v_sub_f32_e32 v12, v50, v13
	v_mul_f32_e32 v12, 0x3fb8aa3b, v12
	v_exp_f32_e32 v70, v12
	v_sub_f32_e32 v12, v46, v13
	v_mul_f32_e32 v12, 0x3fb8aa3b, v12
	v_exp_f32_e32 v39, v12
	v_sub_f32_e32 v12, v57, v13
	v_mul_f32_e32 v12, 0x3fb8aa3b, v12
	v_exp_f32_e32 v41, v12
	v_sub_f32_e32 v12, v48, v13
	v_mul_f32_e32 v12, 0x3fb8aa3b, v12
	v_exp_f32_e32 v46, v12
	v_sub_f32_e32 v12, v60, v13
	v_mul_f32_e32 v12, 0x3fb8aa3b, v12
	v_exp_f32_e32 v48, v12
	v_sub_f32_e32 v12, v74, v13
	v_mul_f32_e32 v12, 0x3fb8aa3b, v12
	v_exp_f32_e32 v51, v12
	v_sub_f32_e32 v12, v81, v13
	v_mul_f32_e32 v12, 0x3fb8aa3b, v12
	v_exp_f32_e32 v53, v12
	v_sub_f32_e32 v12, v80, v13
	v_mul_f32_e32 v12, 0x3fb8aa3b, v12
	v_exp_f32_e32 v57, v12
	v_sub_f32_e32 v12, v85, v13
	v_mul_f32_e32 v12, 0x3fb8aa3b, v12
	v_exp_f32_e32 v60, v12
	v_sub_f32_e32 v12, v84, v13
	v_mul_f32_e32 v12, 0x3fb8aa3b, v12
	v_exp_f32_e32 v31, v12
	v_sub_f32_e32 v12, v83, v13
	v_mul_f32_e32 v12, 0x3fb8aa3b, v12
	v_mul_f32_e32 v11, 0x3fb8aa3b, v11
	v_exp_f32_e32 v33, v12
	v_sub_f32_e32 v12, v38, v13
	v_exp_f32_e32 v56, v11
	v_mul_f32_e32 v12, 0x3fb8aa3b, v12
	v_exp_f32_e32 v38, v12
	v_sub_f32_e32 v12, v40, v13
	v_mul_f32_e32 v12, 0x3fb8aa3b, v12
	v_exp_f32_e32 v40, v12
	v_sub_f32_e32 v12, v37, v13
	v_add_f32_e32 v11, 0, v56
	v_mul_f32_e32 v12, 0x3fb8aa3b, v12
	v_add_f32_e32 v11, v59, v11
	v_exp_f32_e32 v43, v12
	v_sub_f32_e32 v12, v35, v13
	v_add_f32_e32 v11, v62, v11
	v_mul_f32_e32 v12, 0x3fb8aa3b, v12
	v_add_f32_e32 v11, v63, v11
	v_exp_f32_e32 v45, v12
	v_sub_f32_e32 v12, v32, v13
	v_add_f32_e32 v11, v65, v11
	v_mul_f32_e32 v12, 0x3fb8aa3b, v12
	v_add_f32_e32 v11, v71, v11
	v_exp_f32_e32 v50, v12
	v_sub_f32_e32 v12, v30, v13
	v_add_f32_e32 v11, v72, v11
	v_mul_f32_e32 v12, 0x3fb8aa3b, v12
	v_add_f32_e32 v11, v75, v11
	v_exp_f32_e32 v52, v12
	v_sub_f32_e32 v12, v34, v13
	v_add_f32_e32 v11, v47, v11
	v_mul_f32_e32 v12, 0x3fb8aa3b, v12
	v_add_f32_e32 v11, v49, v11
	v_exp_f32_e32 v25, v12
	v_sub_f32_e32 v12, v36, v13
	v_add_f32_e32 v11, v54, v11
	v_mul_f32_e32 v12, 0x3fb8aa3b, v12
	v_add_f32_e32 v11, v55, v11
	v_exp_f32_e32 v27, v12
	v_sub_f32_e32 v12, v42, v13
	v_add_f32_e32 v11, v58, v11
	v_mul_f32_e32 v12, 0x3fb8aa3b, v12
	v_add_f32_e32 v11, v61, v11
	v_exp_f32_e32 v30, v12
	v_sub_f32_e32 v12, v44, v13
	v_add_f32_e32 v11, v64, v11
	v_mul_f32_e32 v12, 0x3fb8aa3b, v12
	v_add_f32_e32 v11, v70, v11
	v_exp_f32_e32 v32, v12
	v_sub_f32_e32 v12, v26, v13
	v_add_f32_e32 v11, v39, v11
	v_mul_f32_e32 v12, 0x3fb8aa3b, v12
	v_add_f32_e32 v11, v41, v11
	v_exp_f32_e32 v35, v12
	v_sub_f32_e32 v12, v86, v13
	v_add_f32_e32 v11, v46, v11
	v_mul_f32_e32 v12, 0x3fb8aa3b, v12
	v_add_f32_e32 v11, v48, v11
	v_exp_f32_e32 v37, v12
	v_sub_f32_e32 v12, v87, v13
	v_add_f32_e32 v11, v51, v11
	v_mul_f32_e32 v12, 0x3fb8aa3b, v12
	v_add_f32_e32 v11, v53, v11
	v_exp_f32_e32 v42, v12
	v_sub_f32_e32 v12, v89, v13
	v_add_f32_e32 v11, v57, v11
; #define LAS __attribute__((address_space(3)))
; __device__ __forceinline__ s16x4_t trread(LAS unsigned char* p) { return __builtin_amdgcn_ds_read_tr16_b64_v4i16((LAS s16x4_t*)p); }
; __device__ __forceinline__ bf16x8_t cat4(s16x4_t a, s16x4_t b) { return (bf16x8_t){a[0], a[1], a[2], a[3], b[0], b[1], b[2], b[3]}; }
; __device__ __forceinline__ void mixC_mfma_unit(const bf16* Z, bf16* Yc, const float* rpb, LAS unsigned char* lds, int u, int S, int tid) {
;     ...
;     for (int t = 0; t < 16; ++t)
; #pragma unroll
;         for (int j = 0; j < 4; ++j) { const float pe = __expf(s[t][j] - m); s[t][j] = pe; l += pe; }
;     l += __shfl_xor(l, 16); l += __shfl_xor(l, 32);
;     f32x4 o[4];
; #pragma unroll
;     for (int dt = 0; dt < 4; ++dt) o[dt] = (f32x4){0.f, 0.f, 0.f, 0.f};
;     LAS unsigned char* vb = lds + ((rs - rb) * 64 + cbs + 4 * q + ((lane >> 2) & 3)) * KPITCH + 8 * (lane & 3);
; #pragma unroll
;     for (int G = 0; G < 8; ++G) {
;         const bf16x8_t pb = packp(s[2 * G], s[2 * G + 1]);
; #pragma unroll
;         for (int dt = 0; dt < 4; ++dt) {
;             const s16x4_t lo = trread(vb + (64 * G) * KPITCH + dt * 32), hi = trread(vb + (64 * G + 16) * KPITCH + dt * 32);
;             o[dt] = __builtin_amdgcn_mfma_f32_16x16x32_bf16(cat4(lo, hi), pb, o[dt], 0, 0, 0);
;         }
	v_mul_f32_e32 v12, 0x3fb8aa3b, v12
	v_add_f32_e32 v11, v60, v11
	v_exp_f32_e32 v44, v12
	v_sub_f32_e32 v12, v88, v13
	v_add_f32_e32 v11, v31, v11
	v_mul_f32_e32 v12, 0x3fb8aa3b, v12
	v_add_f32_e32 v11, v33, v11
	v_exp_f32_e32 v17, v12
	v_sub_f32_e32 v12, v29, v13
	v_add_f32_e32 v11, v38, v11
	v_mul_f32_e32 v12, 0x3fb8aa3b, v12
	v_add_f32_e32 v11, v40, v11
	v_exp_f32_e32 v20, v12
	v_sub_f32_e32 v12, v24, v13
	v_add_f32_e32 v11, v43, v11
	v_mul_f32_e32 v12, 0x3fb8aa3b, v12
	v_add_f32_e32 v11, v45, v11
	v_exp_f32_e32 v24, v12
	v_sub_f32_e32 v12, v28, v13
	v_add_f32_e32 v11, v50, v11
	v_mul_f32_e32 v12, 0x3fb8aa3b, v12
	v_add_f32_e32 v11, v52, v11
	v_exp_f32_e32 v26, v12
	v_sub_f32_e32 v12, v23, v13
	v_add_f32_e32 v11, v25, v11
	v_mul_f32_e32 v12, 0x3fb8aa3b, v12
	v_add_f32_e32 v11, v27, v11
	v_exp_f32_e32 v28, v12
	v_sub_f32_e32 v12, v22, v13
	v_add_f32_e32 v11, v30, v11
	v_mul_f32_e32 v12, 0x3fb8aa3b, v12
	v_add_f32_e32 v11, v32, v11
	v_exp_f32_e32 v29, v12
	v_sub_f32_e32 v12, v19, v13
	v_add_f32_e32 v11, v35, v11
	v_mul_f32_e32 v12, 0x3fb8aa3b, v12
	v_add_f32_e32 v11, v37, v11
	v_exp_f32_e32 v34, v12
	v_sub_f32_e32 v12, v18, v13
	v_add_f32_e32 v11, v42, v11
	v_mul_f32_e32 v12, 0x3fb8aa3b, v12
	v_add_f32_e32 v11, v44, v11
	v_exp_f32_e32 v36, v12
	v_sub_f32_e32 v12, v14, v13
	v_add_f32_e32 v11, v17, v11
	v_mul_f32_e32 v12, 0x3fb8aa3b, v12
	v_add_f32_e32 v11, v20, v11
	v_exp_f32_e32 v14, v12
	v_sub_f32_e32 v12, v15, v13
	v_add_f32_e32 v11, v24, v11
	v_mul_f32_e32 v12, 0x3fb8aa3b, v12
	v_add_f32_e32 v11, v26, v11
	v_exp_f32_e32 v15, v12
	v_sub_f32_e32 v12, v16, v13
	v_add_f32_e32 v11, v28, v11
	v_mul_f32_e32 v12, 0x3fb8aa3b, v12
	v_add_f32_e32 v11, v29, v11
	v_exp_f32_e32 v16, v12
	v_sub_f32_e32 v12, v21, v13
	v_sub_f32_e32 v7, v7, v13
	v_add_f32_e32 v11, v34, v11
	v_mul_f32_e32 v12, 0x3fb8aa3b, v12
	v_sub_f32_e32 v6, v6, v13
	v_mul_f32_e32 v7, 0x3fb8aa3b, v7
	v_add_f32_e32 v11, v36, v11
	v_exp_f32_e32 v18, v12
	v_mul_f32_e32 v6, 0x3fb8aa3b, v6
	v_exp_f32_e32 v21, v7
	v_sub_f32_e32 v7, v8, v13
	v_add_f32_e32 v11, v14, v11
	v_exp_f32_e32 v19, v6
	v_mul_f32_e32 v7, 0x3fb8aa3b, v7
	v_add_f32_e32 v11, v15, v11
	v_exp_f32_e32 v22, v7
	v_sub_f32_e32 v7, v93, v13
	v_add_f32_e32 v11, v16, v11
	v_mul_f32_e32 v7, 0x3fb8aa3b, v7
	v_add_f32_e32 v11, v18, v11
	v_exp_f32_e32 v23, v7
	v_add_f32_e32 v6, v19, v11
	v_add_f32_e32 v6, v21, v6
	v_add_f32_e32 v6, v22, v6
	v_add_f32_e32 v7, v23, v6
	v_sub_f32_e32 v6, v94, v13
	v_mul_f32_e32 v6, 0x3fb8aa3b, v6
	v_exp_f32_e32 v6, v6
	v_sub_f32_e32 v5, v5, v13
	v_mul_f32_e32 v5, 0x3fb8aa3b, v5
	v_sub_f32_e32 v10, v10, v13
	v_add_f32_e32 v8, v6, v7
	v_sub_f32_e32 v7, v9, v13
	v_mul_f32_e32 v7, 0x3fb8aa3b, v7
	v_exp_f32_e32 v7, v7
	v_mul_f32_e32 v10, 0x3fb8aa3b, v10
	v_sub_f32_e32 v3, v3, v13
	v_exp_f32_e32 v10, v10
	v_add_f32_e32 v9, v7, v8
	v_sub_f32_e32 v8, v92, v13
	v_mul_f32_e32 v8, 0x3fb8aa3b, v8
	v_exp_f32_e32 v8, v8
	v_mul_f32_e32 v3, 0x3fb8aa3b, v3
	v_sub_f32_e32 v4, v4, v13
	v_mul_f32_e32 v4, 0x3fb8aa3b, v4
	v_add_f32_e32 v11, v8, v9
	v_exp_f32_e32 v9, v5
	v_sub_f32_e32 v2, v2, v13
	v_exp_f32_e32 v12, v4
	v_mul_f32_e32 v2, 0x3fb8aa3b, v2
	v_add_f32_e32 v5, v9, v11
	v_exp_f32_e32 v11, v3
	v_exp_f32_e32 v13, v2
	v_add_f32_e32 v5, v10, v5
	v_cvt_pk_bf16_f32 v78, v56, v59
	v_add_f32_e32 v3, v11, v5
	v_add_f32_e32 v3, v12, v3
	v_add_f32_e32 v2, v13, v3
	ds_bpermute_b32 v3, v69, v2
	s_waitcnt lgkmcnt(0)
	v_add_f32_e32 v4, v2, v3
	v_subrev_u32_e32 v2, s2, v79
	v_lshl_add_u32 v1, v2, 6, v1
	v_mad_u64_u32 v[2:3], s[2:3], v1, s67, v[68:69]
	ds_bpermute_b32 v5, v82, v4
	v_cvt_pk_bf16_f32 v79, v62, v63
	v_cvt_pk_bf16_f32 v80, v65, v71
	v_cvt_pk_bf16_f32 v81, v72, v75
	ds_read_b64_tr_b16 v[74:75], v2 offset:2304
	ds_read_b64_tr_b16 v[72:73], v2
	ds_read_b64_tr_b16 v[82:83], v2 offset:32
	ds_read_b64_tr_b16 v[84:85], v2 offset:2336
	ds_read_b64_tr_b16 v[86:87], v2 offset:64
	ds_read_b64_tr_b16 v[88:89], v2 offset:2368
	ds_read_b64_tr_b16 v[92:93], v2 offset:96
	ds_read_b64_tr_b16 v[94:95], v2 offset:2400
	s_waitcnt lgkmcnt(6)
	v_mfma_f32_16x16x32_bf16 v[72:75], v[72:75], v[78:81], 0
	v_add_u32_e32 v1, 0x10500, v2
	s_waitcnt lgkmcnt(4)
	v_mfma_f32_16x16x32_bf16 v[82:85], v[82:85], v[78:81], 0
	s_waitcnt lgkmcnt(2)
	v_mfma_f32_16x16x32_bf16 v[86:89], v[86:89], v[78:81], 0
	s_waitcnt lgkmcnt(0)
	v_mfma_f32_16x16x32_bf16 v[78:81], v[92:95], v[78:81], 0
	v_cvt_pk_bf16_f32 v92, v47, v49
	v_cvt_pk_bf16_f32 v93, v54, v55
	v_cvt_pk_bf16_f32 v94, v58, v61
	v_cvt_pk_bf16_f32 v95, v64, v70
	ds_read_b64_tr_b16 v[64:65], v2 offset:11520
	ds_read_b64_tr_b16 v[62:63], v2 offset:9216
	ds_read_b64_tr_b16 v[68:69], v2 offset:9248
	ds_read_b64_tr_b16 v[70:71], v2 offset:11552
	s_waitcnt lgkmcnt(2)
	v_mfma_f32_16x16x32_bf16 v[62:65], v[62:65], v[92:95], v[72:75]
	s_nop 2
	ds_read_b64_tr_b16 v[72:73], v2 offset:9280
	ds_read_b64_tr_b16 v[74:75], v2 offset:11584
	s_waitcnt lgkmcnt(2)
	v_mfma_f32_16x16x32_bf16 v[68:71], v[68:71], v[92:95], v[82:85]
	s_nop 2
	ds_read_b64_tr_b16 v[82:83], v2 offset:9312
	ds_read_b64_tr_b16 v[84:85], v2 offset:11616
	v_cvt_pk_bf16_f32 v54, v39, v41
	v_cvt_pk_bf16_f32 v55, v46, v48
	v_cvt_pk_bf16_f32 v56, v51, v53
	v_cvt_pk_bf16_f32 v57, v57, v60
	ds_read_b64_tr_b16 v[48:49], v2 offset:20736
	ds_read_b64_tr_b16 v[46:47], v2 offset:18432
	ds_read_b64_tr_b16 v[58:59], v2 offset:18464
	ds_read_b64_tr_b16 v[60:61], v2 offset:20768
	s_waitcnt lgkmcnt(2)
	v_mfma_f32_16x16x32_bf16 v[46:49], v[46:49], v[54:57], v[62:65]
	s_nop 2
	ds_read_b64_tr_b16 v[62:63], v2 offset:18496
	ds_read_b64_tr_b16 v[64:65], v2 offset:20800
	s_waitcnt lgkmcnt(2)
; __device__ __forceinline__ unsigned cvt_pk_bf16(float lo, float hi) { unsigned r; asm volatile("v_cvt_pk_bf16_f32 %0, %1, %2" : "=v"(r) : "v"(lo), "v"(hi)); return r; }
; __device__ __forceinline__ s16x4_t trread(LAS unsigned char* p) { return __builtin_amdgcn_ds_read_tr16_b64_v4i16((LAS s16x4_t*)p); }
; __device__ __forceinline__ bf16x8_t cat4(s16x4_t a, s16x4_t b) { return (bf16x8_t){a[0], a[1], a[2], a[3], b[0], b[1], b[2], b[3]}; }
; __device__ __forceinline__ void mixC_mfma_unit(const bf16* Z, bf16* Yc, const float* rpb, LAS unsigned char* lds, int u, int S, int tid) {
;     ...
; #pragma unroll
;     for (int G = 0; G < 8; ++G) {
;         const bf16x8_t pb = packp(s[2 * G], s[2 * G + 1]);
; #pragma unroll
;         for (int dt = 0; dt < 4; ++dt) {
;             const s16x4_t lo = trread(vb + (64 * G) * KPITCH + dt * 32), hi = trread(vb + (64 * G + 16) * KPITCH + dt * 32);
;             o[dt] = __builtin_amdgcn_mfma_f32_16x16x32_bf16(cat4(lo, hi), pb, o[dt], 0, 0, 0);
;         }
;     }
;     const float inv = __builtin_amdgcn_rcpf(l);
;     bf16* yp = Yc + (size_t)tokc * 512 + h * 64;
; #pragma unroll
;     for (int dt = 0; dt < 4; ++dt) { uint2 wv; wv.x = pg8::cvt_pk_bf16(o[dt][0] * inv, o[dt][1] * inv); wv.y = pg8::cvt_pk_bf16(o[dt][2] * inv, o[dt][3] * inv);
;         *(uint2*)(yp + dt * 16 + 4 * q) = wv; }
	v_mfma_f32_16x16x32_bf16 v[58:61], v[58:61], v[54:57], v[68:71]
	s_nop 2
	ds_read_b64_tr_b16 v[68:69], v2 offset:18528
	ds_read_b64_tr_b16 v[70:71], v2 offset:20832
	v_mfma_f32_16x16x32_bf16 v[72:75], v[72:75], v[92:95], v[86:89]
	v_mfma_f32_16x16x32_bf16 v[78:81], v[82:85], v[92:95], v[78:81]
	s_waitcnt lgkmcnt(2)
	v_mfma_f32_16x16x32_bf16 v[62:65], v[62:65], v[54:57], v[72:75]
	s_waitcnt lgkmcnt(0)
	v_mfma_f32_16x16x32_bf16 v[54:57], v[68:71], v[54:57], v[78:81]
	v_cvt_pk_bf16_f32 v68, v31, v33
	v_cvt_pk_bf16_f32 v69, v38, v40
	v_cvt_pk_bf16_f32 v70, v43, v45
	v_cvt_pk_bf16_f32 v71, v50, v52
	ds_read_b64_tr_b16 v[40:41], v2 offset:29952
	ds_read_b64_tr_b16 v[38:39], v2 offset:27648
	ds_read_b64_tr_b16 v[50:51], v2 offset:27680
	ds_read_b64_tr_b16 v[52:53], v2 offset:29984
	s_waitcnt lgkmcnt(2)
	v_mfma_f32_16x16x32_bf16 v[38:41], v[38:41], v[68:71], v[46:49]
	s_waitcnt lgkmcnt(0)
	v_mfma_f32_16x16x32_bf16 v[46:49], v[50:53], v[68:71], v[58:61]
	ds_read_b64_tr_b16 v[50:51], v2 offset:27712
	ds_read_b64_tr_b16 v[52:53], v2 offset:30016
	s_nop 0
	ds_read_b64_tr_b16 v[58:59], v2 offset:27744
	ds_read_b64_tr_b16 v[60:61], v2 offset:30048
	s_waitcnt lgkmcnt(0)
	v_mfma_f32_16x16x32_bf16 v[54:57], v[58:61], v[68:71], v[54:57]
	v_cvt_pk_bf16_f32 v58, v25, v27
	v_cvt_pk_bf16_f32 v59, v30, v32
	v_cvt_pk_bf16_f32 v60, v35, v37
	v_cvt_pk_bf16_f32 v61, v42, v44
	ds_read_b64_tr_b16 v[32:33], v2 offset:39168
	ds_read_b64_tr_b16 v[30:31], v2 offset:36864
	ds_read_b64_tr_b16 v[42:43], v2 offset:36896
	ds_read_b64_tr_b16 v[44:45], v2 offset:39200
	s_waitcnt lgkmcnt(2)
	v_mfma_f32_16x16x32_bf16 v[30:33], v[30:33], v[58:61], v[38:41]
	s_waitcnt lgkmcnt(0)
	v_mfma_f32_16x16x32_bf16 v[38:41], v[42:45], v[58:61], v[46:49]
	ds_read_b64_tr_b16 v[42:43], v2 offset:36928
	ds_read_b64_tr_b16 v[44:45], v2 offset:39232
	s_nop 0
	ds_read_b64_tr_b16 v[46:47], v2 offset:36960
	ds_read_b64_tr_b16 v[48:49], v2 offset:39264
	v_mfma_f32_16x16x32_bf16 v[50:53], v[50:53], v[68:71], v[62:65]
	s_waitcnt lgkmcnt(2)
	v_mfma_f32_16x16x32_bf16 v[42:45], v[42:45], v[58:61], v[50:53]
	v_cvt_pk_bf16_f32 v50, v17, v20
	v_cvt_pk_bf16_f32 v51, v24, v26
	v_cvt_pk_bf16_f32 v52, v28, v29
	v_cvt_pk_bf16_f32 v53, v34, v36
	ds_read_b64_tr_b16 v[26:27], v2 offset:48384
	ds_read_b64_tr_b16 v[24:25], v2 offset:46080
	ds_read_b64_tr_b16 v[28:29], v2 offset:46112
	s_waitcnt lgkmcnt(1)
	s_nop 1
	v_mfma_f32_16x16x32_bf16 v[24:27], v[24:27], v[50:53], v[30:33]
	s_nop 2
	ds_read_b64_tr_b16 v[30:31], v2 offset:48416
	ds_read_b64_tr_b16 v[32:33], v2 offset:46144
	ds_read_b64_tr_b16 v[34:35], v2 offset:48448
	s_waitcnt lgkmcnt(2)
	v_mfma_f32_16x16x32_bf16 v[28:31], v[28:31], v[50:53], v[38:41]
	ds_read_b64_tr_b16 v[36:37], v2 offset:46176
	s_nop 1
	ds_read_b64_tr_b16 v[38:39], v2 offset:48480
	v_cvt_pk_bf16_f32 v14, v14, v15
	v_cvt_pk_bf16_f32 v15, v16, v18
	v_cvt_pk_bf16_f32 v16, v19, v21
	v_cvt_pk_bf16_f32 v17, v22, v23
	ds_read_b64_tr_b16 v[20:21], v2 offset:57600
	ds_read_b64_tr_b16 v[18:19], v2 offset:55296
	ds_read_b64_tr_b16 v[22:23], v2 offset:55328
	s_waitcnt lgkmcnt(1)
	v_mfma_f32_16x16x32_bf16 v[18:21], v[18:21], v[14:17], v[24:27]
	s_nop 2
	ds_read_b64_tr_b16 v[24:25], v2 offset:57632
	s_waitcnt lgkmcnt(0)
	v_mfma_f32_16x16x32_bf16 v[22:25], v[22:25], v[14:17], v[28:31]
	ds_read_b64_tr_b16 v[26:27], v2 offset:55360
	s_nop 1
	ds_read_b64_tr_b16 v[28:29], v2 offset:57664
	v_mfma_f32_16x16x32_bf16 v[32:35], v[32:35], v[50:53], v[42:45]
	v_mfma_f32_16x16x32_bf16 v[46:49], v[46:49], v[58:61], v[54:57]
	s_waitcnt lgkmcnt(0)
	v_mfma_f32_16x16x32_bf16 v[26:29], v[26:29], v[14:17], v[32:35]
	ds_read_b64_tr_b16 v[30:31], v2 offset:55392
	s_nop 3
	ds_read_b64_tr_b16 v[32:33], v2 offset:57696
	v_cvt_pk_bf16_f32 v6, v6, v7
	v_cvt_pk_bf16_f32 v7, v8, v9
	v_mfma_f32_16x16x32_bf16 v[36:39], v[36:39], v[50:53], v[46:49]
	v_cvt_pk_bf16_f32 v8, v10, v11
	v_cvt_pk_bf16_f32 v9, v12, v13
	s_waitcnt lgkmcnt(0)
	v_mfma_f32_16x16x32_bf16 v[14:17], v[30:33], v[14:17], v[36:39]
	ds_read_b64_tr_b16 v[12:13], v1
	ds_read_b64_tr_b16 v[10:11], v2 offset:64512
	ds_read_b64_tr_b16 v[30:31], v2 offset:64544
	v_add_u32_e32 v1, 0x10520, v2
	ds_read_b64_tr_b16 v[32:33], v1
	v_add_u32_e32 v1, 0x10540, v2
	s_waitcnt lgkmcnt(2)
	v_mfma_f32_16x16x32_bf16 v[10:13], v[10:13], v[6:9], v[18:21]
	s_waitcnt lgkmcnt(0)
	v_mfma_f32_16x16x32_bf16 v[18:21], v[30:33], v[6:9], v[22:25]
	s_nop 2
	ds_read_b64_tr_b16 v[22:23], v2 offset:64576
	ds_read_b64_tr_b16 v[24:25], v1
	v_add_u32_e32 v1, 0x10560, v2
	s_waitcnt lgkmcnt(0)
	v_mfma_f32_16x16x32_bf16 v[22:25], v[22:25], v[6:9], v[26:29]
	s_nop 2
	ds_read_b64_tr_b16 v[26:27], v2 offset:64608
	ds_read_b64_tr_b16 v[28:29], v1
	v_add_f32_e32 v1, v4, v5
	v_rcp_f32_e32 v1, v1
	v_lshlrev_b64 v[2:3], 10, v[76:77]
	v_lshl_add_u64 v[2:3], v[66:67], 0, v[2:3]
	s_waitcnt lgkmcnt(0)
	v_mfma_f32_16x16x32_bf16 v[6:9], v[26:29], v[6:9], v[14:17]
	v_mul_f32_e32 v4, v1, v10
	v_mul_f32_e32 v5, v1, v11
	v_cvt_pk_bf16_f32 v4, v4, v5
	v_mul_f32_e32 v5, v1, v12
	v_mul_f32_e32 v10, v1, v13
	v_cvt_pk_bf16_f32 v5, v5, v10
	v_lshrrev_b32_e32 v218, 4, v231
	v_lshl_or_b32 v218, v231, 4, v218
	v_and_b32_e32 v218, 0x33, v218
	v_and_or_b32 v218, v231, 12, v218
	v_lshlrev_b32_e32 v218, 2, v218
	ds_bpermute_b32 v220, v218, v2
	ds_bpermute_b32 v221, v218, v3
	ds_bpermute_b32 v4, v218, v4
	ds_bpermute_b32 v5, v218, v5
	s_waitcnt lgkmcnt(0)
	global_store_dwordx2 v[220:221], v[4:5], off
	v_mul_f32_e32 v4, v1, v18
	v_mul_f32_e32 v5, v1, v19
	v_cvt_pk_bf16_f32 v4, v4, v5
	v_mul_f32_e32 v5, v1, v20
	v_mul_f32_e32 v10, v1, v21
	v_cvt_pk_bf16_f32 v5, v5, v10
	ds_bpermute_b32 v4, v218, v4
	ds_bpermute_b32 v5, v218, v5
	s_waitcnt lgkmcnt(0)
	global_store_dwordx2 v[220:221], v[4:5], off offset:32
	v_mul_f32_e32 v4, v1, v22
	v_mul_f32_e32 v5, v1, v23
	v_cvt_pk_bf16_f32 v4, v4, v5
	v_mul_f32_e32 v5, v1, v24
	v_mul_f32_e32 v10, v1, v25
	v_cvt_pk_bf16_f32 v5, v5, v10
	ds_bpermute_b32 v4, v218, v4
	ds_bpermute_b32 v5, v218, v5
	s_waitcnt lgkmcnt(0)
	global_store_dwordx2 v[220:221], v[4:5], off offset:64
	v_mul_f32_e32 v4, v1, v6
	v_mul_f32_e32 v5, v1, v7
	v_cvt_pk_bf16_f32 v4, v4, v5
	v_mul_f32_e32 v5, v1, v8
	v_mul_f32_e32 v1, v1, v9
	v_cvt_pk_bf16_f32 v5, v5, v1
	ds_bpermute_b32 v4, v218, v4
	ds_bpermute_b32 v5, v218, v5
	s_waitcnt lgkmcnt(0)
	global_store_dwordx2 v[220:221], v[4:5], off offset:96
	s_cbranch_scc1 .LBB0_264
